# v39_gemm_micro
# speedup vs baseline: 1.0149x; 1.0149x over previous
; #define WAIT_L(n) asm volatile("s_waitcnt lgkmcnt(" #n ")" ::: "memory")
; #define BAR __builtin_amdgcn_s_barrier()
; #define SCHED __builtin_amdgcn_sched_barrier(0)
; template <int EPI>
; __device__ __forceinline__ void gemm_tile(const Params& p, const bf16* __restrict__ A, const bf16* __restrict__ Bt, const int K,
;                                           const int nt, const int brow, const int bcol, int pm, int pn) {
;     ...
;     LDB(B0, 0, 0); SCHED; LDA(At, 0, 0); STAGE(SA(1, 1), A, brow + HALF, t + 1);
;     WAIT_L(8); BAR; WAIT_L(0); MMA(0, 0, At, B0); BAR; SCHED;
;     LDB(B1, 0, 1); STAGE(SB(0, 0), Bt, bcol, t + 2);
;     BAR; WAIT_L(0); MMA(0, 1, At, B1); BAR;
;     LDA(At, 0, 1); STAGE(SA(0, 0), A, brow, t + 2);
;     BAR; WAIT_L(0); MMA(1, 0, At, B0); BAR; SCHED;
.LBB0_116:
	ds_read_b128 v[156:159], v153
	ds_read_b128 v[160:163], v153 offset:1024
	ds_read_b128 v[164:167], v153 offset:2048
	ds_read_b128 v[168:171], v153 offset:3072
	v_readfirstlane_b32 s11, v154
	v_lshl_add_u64 v[204:205], v[130:131], 0, s[8:9]
	s_mov_b32 m0, s11
	v_readfirstlane_b32 s11, v155
	ds_read_b128 v[172:175], v135
	ds_read_b128 v[176:179], v135 offset:1024
	ds_read_b128 v[180:183], v134
	ds_read_b128 v[184:187], v134 offset:1024
	ds_read_b128 v[188:191], v133
	ds_read_b128 v[192:195], v133 offset:1024
	ds_read_b128 v[196:199], v132
	ds_read_b128 v[200:203], v132 offset:1024
	global_load_lds_dwordx4 v[204:205], off
	v_lshl_add_u64 v[204:205], v[130:131], 0, s[12:13]
	s_mov_b32 m0, s11
	s_nop 0
	global_load_lds_dwordx4 v[204:205], off
	s_waitcnt lgkmcnt(8)
	s_setprio 1
	s_barrier
	s_waitcnt lgkmcnt(0)
	s_waitcnt lgkmcnt(0)
	v_mfma_f32_16x16x32_bf16 v[124:127], v[172:175], v[156:159], v[124:127]
	v_mfma_f32_16x16x32_bf16 v[120:123], v[172:175], v[164:167], v[120:123]
	v_mfma_f32_16x16x32_bf16 v[116:119], v[180:183], v[156:159], v[116:119]
	v_mfma_f32_16x16x32_bf16 v[112:115], v[180:183], v[164:167], v[112:115]
	v_mfma_f32_16x16x32_bf16 v[108:111], v[188:191], v[156:159], v[108:111]
	v_mfma_f32_16x16x32_bf16 v[104:107], v[188:191], v[164:167], v[104:107]
	v_mfma_f32_16x16x32_bf16 v[100:103], v[196:199], v[156:159], v[100:103]
	v_mfma_f32_16x16x32_bf16 v[96:99], v[196:199], v[164:167], v[96:99]
	v_mfma_f32_16x16x32_bf16 v[124:127], v[176:179], v[160:163], v[124:127]
	v_mfma_f32_16x16x32_bf16 v[120:123], v[176:179], v[168:171], v[120:123]
	v_mfma_f32_16x16x32_bf16 v[116:119], v[184:187], v[160:163], v[116:119]
	v_mfma_f32_16x16x32_bf16 v[112:115], v[184:187], v[168:171], v[112:115]
	v_mfma_f32_16x16x32_bf16 v[108:111], v[192:195], v[160:163], v[108:111]
	v_mfma_f32_16x16x32_bf16 v[104:107], v[192:195], v[168:171], v[104:107]
	v_mfma_f32_16x16x32_bf16 v[100:103], v[200:203], v[160:163], v[100:103]
	v_mfma_f32_16x16x32_bf16 v[96:99], v[200:203], v[168:171], v[96:99]
	s_setprio 0
	s_barrier
	v_lshl_add_u64 v[204:205], v[130:131], 0, s[4:5]
	v_readfirstlane_b32 s11, v137
	v_lshl_add_u64 v[224:225], v[204:205], 0, s[14:15]
	s_mov_b32 m0, s11
	v_readfirstlane_b32 s11, v138
	ds_read_b128 v[208:211], v151
	ds_read_b128 v[212:215], v151 offset:1024
	ds_read_b128 v[216:219], v151 offset:2048
	ds_read_b128 v[220:223], v151 offset:3072
	global_load_lds_dwordx4 v[224:225], off
	v_lshl_add_u64 v[224:225], v[204:205], 0, s[16:17]
	s_mov_b32 m0, s11
	s_nop 0
	global_load_lds_dwordx4 v[224:225], off
	s_setprio 1
	s_barrier
	s_waitcnt lgkmcnt(0)
	s_waitcnt lgkmcnt(0)
	v_mfma_f32_16x16x32_bf16 v[92:95], v[172:175], v[208:211], v[92:95]
	v_mfma_f32_16x16x32_bf16 v[88:91], v[172:175], v[216:219], v[88:91]
	v_mfma_f32_16x16x32_bf16 v[84:87], v[180:183], v[208:211], v[84:87]
	v_mfma_f32_16x16x32_bf16 v[80:83], v[180:183], v[216:219], v[80:83]
	v_mfma_f32_16x16x32_bf16 v[76:79], v[188:191], v[208:211], v[76:79]
	v_mfma_f32_16x16x32_bf16 v[72:75], v[188:191], v[216:219], v[72:75]
	v_mfma_f32_16x16x32_bf16 v[68:71], v[196:199], v[208:211], v[68:71]
	v_mfma_f32_16x16x32_bf16 v[64:67], v[196:199], v[216:219], v[64:67]
	v_mfma_f32_16x16x32_bf16 v[92:95], v[176:179], v[212:215], v[92:95]
	v_mfma_f32_16x16x32_bf16 v[88:91], v[176:179], v[220:223], v[88:91]
	v_mfma_f32_16x16x32_bf16 v[84:87], v[184:187], v[212:215], v[84:87]
	v_mfma_f32_16x16x32_bf16 v[80:83], v[184:187], v[220:223], v[80:83]
	v_mfma_f32_16x16x32_bf16 v[76:79], v[192:195], v[212:215], v[76:79]
	v_mfma_f32_16x16x32_bf16 v[72:75], v[192:195], v[220:223], v[72:75]
	v_mfma_f32_16x16x32_bf16 v[68:71], v[200:203], v[212:215], v[68:71]
	v_mfma_f32_16x16x32_bf16 v[64:67], v[200:203], v[220:223], v[64:67]
	s_setprio 0
	v_readfirstlane_b32 s11, v136
	s_mov_b32 m0, s11
	v_readfirstlane_b32 s11, v140
	s_barrier
	ds_read_b128 v[172:175], v135 offset:16384
	ds_read_b128 v[176:179], v135 offset:17408
	ds_read_b128 v[180:183], v134 offset:16384
	ds_read_b128 v[184:187], v134 offset:17408
	ds_read_b128 v[188:191], v133 offset:16384
	ds_read_b128 v[192:195], v133 offset:17408
	ds_read_b128 v[196:199], v132 offset:16384
	ds_read_b128 v[200:203], v132 offset:17408
	global_load_lds_dwordx4 v[130:131], off
	v_lshl_add_u64 v[224:225], v[130:131], 0, s[18:19]
	s_mov_b32 m0, s11
	s_nop 0
	global_load_lds_dwordx4 v[224:225], off
	s_setprio 1
	s_barrier
	s_waitcnt lgkmcnt(0)
	s_waitcnt lgkmcnt(0)
	v_mfma_f32_16x16x32_bf16 v[60:63], v[172:175], v[156:159], v[60:63]
	v_mfma_f32_16x16x32_bf16 v[56:59], v[172:175], v[164:167], v[56:59]
	v_mfma_f32_16x16x32_bf16 v[52:55], v[180:183], v[156:159], v[52:55]
	v_mfma_f32_16x16x32_bf16 v[48:51], v[180:183], v[164:167], v[48:51]
	v_mfma_f32_16x16x32_bf16 v[44:47], v[188:191], v[156:159], v[44:47]
	v_mfma_f32_16x16x32_bf16 v[40:43], v[188:191], v[164:167], v[40:43]
	v_mfma_f32_16x16x32_bf16 v[36:39], v[196:199], v[156:159], v[36:39]
	v_mfma_f32_16x16x32_bf16 v[32:35], v[196:199], v[164:167], v[32:35]
	v_mfma_f32_16x16x32_bf16 v[60:63], v[176:179], v[160:163], v[60:63]
	v_mfma_f32_16x16x32_bf16 v[56:59], v[176:179], v[168:171], v[56:59]
	v_mfma_f32_16x16x32_bf16 v[52:55], v[184:187], v[160:163], v[52:55]
	v_mfma_f32_16x16x32_bf16 v[48:51], v[184:187], v[168:171], v[48:51]
	v_mfma_f32_16x16x32_bf16 v[44:47], v[192:195], v[160:163], v[44:47]
	v_mfma_f32_16x16x32_bf16 v[40:43], v[192:195], v[168:171], v[40:43]
	v_mfma_f32_16x16x32_bf16 v[36:39], v[200:203], v[160:163], v[36:39]
	v_mfma_f32_16x16x32_bf16 v[32:35], v[200:203], v[168:171], v[32:35]
	s_setprio 0
	s_barrier
; #define WAIT_V(n) asm volatile("s_waitcnt vmcnt(" #n ")" ::: "memory")
; #define WAIT_L(n) asm volatile("s_waitcnt lgkmcnt(" #n ")" ::: "memory")
; #define BAR __builtin_amdgcn_s_barrier()
; #define SCHED __builtin_amdgcn_sched_barrier(0)
; template <int EPI>
; __device__ __forceinline__ void gemm_tile(const Params& p, const bf16* __restrict__ A, const bf16* __restrict__ Bt, const int K,
;                                           const int nt, const int brow, const int bcol, int pm, int pn) {
;     ...
;     STAGE(SB(0, 1), Bt, bcol + HALF, t + 2);
;     WAIT_V(6); BAR; MMA(1, 1, At, B1); BAR;
;     LDB(B0, 1, 0); SCHED; LDA(At, 1, 0); STAGE(SA(0, 1), A, brow + HALF, t + 2);
;     WAIT_L(8); BAR; WAIT_L(0); MMA(0, 0, At, B0); BAR; SCHED;
;     LDB(B1, 1, 1); STAGE(SB(1, 0), Bt, bcol, t + 3);
;     BAR; WAIT_L(0); MMA(0, 1, At, B1); BAR;
;     LDA(At, 1, 1); STAGE(SA(1, 0), A, brow, t + 3);
	v_readfirstlane_b32 s11, v141
	v_lshl_add_u64 v[156:157], v[204:205], 0, s[20:21]
	s_mov_b32 m0, s11
	v_readfirstlane_b32 s11, v142
	global_load_lds_dwordx4 v[156:157], off
	v_lshl_add_u64 v[156:157], v[204:205], 0, s[22:23]
	s_mov_b32 m0, s11
	s_nop 0
	global_load_lds_dwordx4 v[156:157], off
	s_waitcnt vmcnt(6)
	s_setprio 1
	s_barrier
	v_mfma_f32_16x16x32_bf16 v[28:31], v[172:175], v[208:211], v[28:31]
	v_mfma_f32_16x16x32_bf16 v[24:27], v[172:175], v[216:219], v[24:27]
	v_mfma_f32_16x16x32_bf16 v[20:23], v[180:183], v[208:211], v[20:23]
	v_mfma_f32_16x16x32_bf16 v[16:19], v[180:183], v[216:219], v[16:19]
	v_mfma_f32_16x16x32_bf16 v[12:15], v[188:191], v[208:211], v[12:15]
	v_mfma_f32_16x16x32_bf16 v[8:11], v[188:191], v[216:219], v[8:11]
	v_mfma_f32_16x16x32_bf16 v[4:7], v[196:199], v[208:211], v[4:7]
	v_mfma_f32_16x16x32_bf16 v[0:3], v[196:199], v[216:219], v[0:3]
	v_mfma_f32_16x16x32_bf16 v[28:31], v[176:179], v[212:215], v[28:31]
	v_mfma_f32_16x16x32_bf16 v[24:27], v[176:179], v[220:223], v[24:27]
	v_mfma_f32_16x16x32_bf16 v[20:23], v[184:187], v[212:215], v[20:23]
	v_mfma_f32_16x16x32_bf16 v[16:19], v[184:187], v[220:223], v[16:19]
	v_mfma_f32_16x16x32_bf16 v[12:15], v[192:195], v[212:215], v[12:15]
	v_mfma_f32_16x16x32_bf16 v[8:11], v[192:195], v[220:223], v[8:11]
	v_mfma_f32_16x16x32_bf16 v[4:7], v[200:203], v[212:215], v[4:7]
	v_mfma_f32_16x16x32_bf16 v[0:3], v[200:203], v[220:223], v[0:3]
	s_setprio 0
	s_barrier
	ds_read_b128 v[156:159], v144
	ds_read_b128 v[160:163], v144 offset:1024
	ds_read_b128 v[164:167], v144 offset:2048
	ds_read_b128 v[168:171], v144 offset:3072
	v_readfirstlane_b32 s11, v143
	v_lshl_add_u64 v[208:209], v[130:131], 0, s[24:25]
	s_mov_b32 m0, s11
	v_readfirstlane_b32 s11, v145
	ds_read_b128 v[172:175], v135 offset:32768
	ds_read_b128 v[176:179], v135 offset:33792
	ds_read_b128 v[180:183], v134 offset:32768
	ds_read_b128 v[184:187], v134 offset:33792
	ds_read_b128 v[188:191], v133 offset:32768
	ds_read_b128 v[192:195], v133 offset:33792
	ds_read_b128 v[196:199], v132 offset:32768
	ds_read_b128 v[200:203], v132 offset:33792
	global_load_lds_dwordx4 v[208:209], off
	v_lshl_add_u64 v[208:209], v[130:131], 0, s[26:27]
	s_mov_b32 m0, s11
	s_nop 0
	global_load_lds_dwordx4 v[208:209], off
	s_waitcnt lgkmcnt(8)
	s_setprio 1
	s_barrier
	s_waitcnt lgkmcnt(0)
	s_waitcnt lgkmcnt(0)
	v_mfma_f32_16x16x32_bf16 v[124:127], v[172:175], v[156:159], v[124:127]
	v_mfma_f32_16x16x32_bf16 v[120:123], v[172:175], v[164:167], v[120:123]
	v_mfma_f32_16x16x32_bf16 v[116:119], v[180:183], v[156:159], v[116:119]
	v_mfma_f32_16x16x32_bf16 v[112:115], v[180:183], v[164:167], v[112:115]
	v_mfma_f32_16x16x32_bf16 v[108:111], v[188:191], v[156:159], v[108:111]
	v_mfma_f32_16x16x32_bf16 v[104:107], v[188:191], v[164:167], v[104:107]
	v_mfma_f32_16x16x32_bf16 v[100:103], v[196:199], v[156:159], v[100:103]
	v_mfma_f32_16x16x32_bf16 v[96:99], v[196:199], v[164:167], v[96:99]
	v_mfma_f32_16x16x32_bf16 v[124:127], v[176:179], v[160:163], v[124:127]
	v_mfma_f32_16x16x32_bf16 v[120:123], v[176:179], v[168:171], v[120:123]
	v_mfma_f32_16x16x32_bf16 v[116:119], v[184:187], v[160:163], v[116:119]
	v_mfma_f32_16x16x32_bf16 v[112:115], v[184:187], v[168:171], v[112:115]
	v_mfma_f32_16x16x32_bf16 v[108:111], v[192:195], v[160:163], v[108:111]
	v_mfma_f32_16x16x32_bf16 v[104:107], v[192:195], v[168:171], v[104:107]
	v_mfma_f32_16x16x32_bf16 v[100:103], v[200:203], v[160:163], v[100:103]
	v_mfma_f32_16x16x32_bf16 v[96:99], v[200:203], v[168:171], v[96:99]
	s_setprio 0
	s_barrier
	v_readfirstlane_b32 s11, v146
	v_lshl_add_u64 v[224:225], v[204:205], 0, s[28:29]
	s_mov_b32 m0, s11
	v_readfirstlane_b32 s11, v147
	ds_read_b128 v[208:211], v139
	ds_read_b128 v[212:215], v139 offset:1024
	ds_read_b128 v[216:219], v139 offset:2048
	ds_read_b128 v[220:223], v139 offset:3072
	global_load_lds_dwordx4 v[224:225], off
	v_lshl_add_u64 v[224:225], v[204:205], 0, s[30:31]
	s_mov_b32 m0, s11
	s_nop 0
	global_load_lds_dwordx4 v[224:225], off
	s_setprio 1
	s_barrier
	s_waitcnt lgkmcnt(0)
	s_waitcnt lgkmcnt(0)
	v_mfma_f32_16x16x32_bf16 v[92:95], v[172:175], v[208:211], v[92:95]
	v_mfma_f32_16x16x32_bf16 v[88:91], v[172:175], v[216:219], v[88:91]
	v_mfma_f32_16x16x32_bf16 v[84:87], v[180:183], v[208:211], v[84:87]
	v_mfma_f32_16x16x32_bf16 v[80:83], v[180:183], v[216:219], v[80:83]
	v_mfma_f32_16x16x32_bf16 v[76:79], v[188:191], v[208:211], v[76:79]
	v_mfma_f32_16x16x32_bf16 v[72:75], v[188:191], v[216:219], v[72:75]
	v_mfma_f32_16x16x32_bf16 v[68:71], v[196:199], v[208:211], v[68:71]
	v_mfma_f32_16x16x32_bf16 v[64:67], v[196:199], v[216:219], v[64:67]
	v_mfma_f32_16x16x32_bf16 v[92:95], v[176:179], v[212:215], v[92:95]
	v_mfma_f32_16x16x32_bf16 v[88:91], v[176:179], v[220:223], v[88:91]
	v_mfma_f32_16x16x32_bf16 v[84:87], v[184:187], v[212:215], v[84:87]
	v_mfma_f32_16x16x32_bf16 v[80:83], v[184:187], v[220:223], v[80:83]
	v_mfma_f32_16x16x32_bf16 v[76:79], v[192:195], v[212:215], v[76:79]
	v_mfma_f32_16x16x32_bf16 v[72:75], v[192:195], v[220:223], v[72:75]
	v_mfma_f32_16x16x32_bf16 v[68:71], v[200:203], v[212:215], v[68:71]
	v_mfma_f32_16x16x32_bf16 v[64:67], v[200:203], v[220:223], v[64:67]
	s_setprio 0
	v_readfirstlane_b32 s11, v148
	v_lshl_add_u64 v[224:225], v[130:131], 0, s[6:7]
	s_mov_b32 m0, s11
	v_readfirstlane_b32 s11, v149
	s_barrier
	ds_read_b128 v[172:175], v135 offset:49152
	ds_read_b128 v[176:179], v135 offset:50176
	ds_read_b128 v[180:183], v134 offset:49152
	ds_read_b128 v[184:187], v134 offset:50176
	ds_read_b128 v[188:191], v133 offset:49152
	ds_read_b128 v[192:195], v133 offset:50176
	ds_read_b128 v[196:199], v132 offset:49152
	ds_read_b128 v[200:203], v132 offset:50176
	global_load_lds_dwordx4 v[224:225], off
	v_lshl_add_u64 v[224:225], v[130:131], 0, s[34:35]
	s_mov_b32 m0, s11
	s_nop 0
	global_load_lds_dwordx4 v[224:225], off
	s_setprio 1
	s_barrier
; #define WAIT_V(n) asm volatile("s_waitcnt vmcnt(" #n ")" ::: "memory")
; #define WAIT_L(n) asm volatile("s_waitcnt lgkmcnt(" #n ")" ::: "memory")
; #define BAR __builtin_amdgcn_s_barrier()
; #define SCHED __builtin_amdgcn_sched_barrier(0)
; template <int EPI>
; __device__ __forceinline__ void gemm_tile(const Params& p, const bf16* __restrict__ A, const bf16* __restrict__ Bt, const int K,
;                                           const int nt, const int brow, const int bcol, int pm, int pn) {
;     ...
;     BAR; WAIT_L(0); MMA(1, 0, At, B0); BAR; SCHED;
;     STAGE(SB(1, 1), Bt, bcol + HALF, t + 3);
;     WAIT_V(6); BAR; MMA(1, 1, At, B1); BAR;
;   }
;   { LDB(B0, 0, 0); LDA(At, 0, 0); STAGE(SA(1, 1), A, brow + HALF, nt - 1);
;     BAR; WAIT_L(0); MMA(0, 0, At, B0); BAR;
;     LDB(B1, 0, 1); BAR; WAIT_L(0); MMA(0, 1, At, B1); BAR;
	s_waitcnt lgkmcnt(0)
	s_waitcnt lgkmcnt(0)
	v_mfma_f32_16x16x32_bf16 v[60:63], v[172:175], v[156:159], v[60:63]
	v_mfma_f32_16x16x32_bf16 v[56:59], v[172:175], v[164:167], v[56:59]
	v_mfma_f32_16x16x32_bf16 v[52:55], v[180:183], v[156:159], v[52:55]
	v_mfma_f32_16x16x32_bf16 v[48:51], v[180:183], v[164:167], v[48:51]
	v_mfma_f32_16x16x32_bf16 v[44:47], v[188:191], v[156:159], v[44:47]
	v_mfma_f32_16x16x32_bf16 v[40:43], v[188:191], v[164:167], v[40:43]
	v_mfma_f32_16x16x32_bf16 v[36:39], v[196:199], v[156:159], v[36:39]
	v_mfma_f32_16x16x32_bf16 v[32:35], v[196:199], v[164:167], v[32:35]
	v_mfma_f32_16x16x32_bf16 v[60:63], v[176:179], v[160:163], v[60:63]
	v_mfma_f32_16x16x32_bf16 v[56:59], v[176:179], v[168:171], v[56:59]
	v_mfma_f32_16x16x32_bf16 v[52:55], v[184:187], v[160:163], v[52:55]
	v_mfma_f32_16x16x32_bf16 v[48:51], v[184:187], v[168:171], v[48:51]
	v_mfma_f32_16x16x32_bf16 v[44:47], v[192:195], v[160:163], v[44:47]
	v_mfma_f32_16x16x32_bf16 v[40:43], v[192:195], v[168:171], v[40:43]
	v_mfma_f32_16x16x32_bf16 v[36:39], v[200:203], v[160:163], v[36:39]
	v_mfma_f32_16x16x32_bf16 v[32:35], v[200:203], v[168:171], v[32:35]
	s_setprio 0
	s_barrier
	v_readfirstlane_b32 s11, v150
	v_lshl_add_u64 v[156:157], v[204:205], 0, s[36:37]
	s_mov_b32 m0, s11
	v_readfirstlane_b32 s11, v152
	global_load_lds_dwordx4 v[156:157], off
	v_lshl_add_u64 v[156:157], v[204:205], 0, s[38:39]
	s_mov_b32 m0, s11
	s_nop 0
	global_load_lds_dwordx4 v[156:157], off
	s_waitcnt vmcnt(6)
	s_setprio 1
	s_barrier
	v_mfma_f32_16x16x32_bf16 v[28:31], v[172:175], v[208:211], v[28:31]
	v_mfma_f32_16x16x32_bf16 v[24:27], v[172:175], v[216:219], v[24:27]
	v_mfma_f32_16x16x32_bf16 v[20:23], v[180:183], v[208:211], v[20:23]
	v_mfma_f32_16x16x32_bf16 v[16:19], v[180:183], v[216:219], v[16:19]
	v_mfma_f32_16x16x32_bf16 v[12:15], v[188:191], v[208:211], v[12:15]
	v_mfma_f32_16x16x32_bf16 v[8:11], v[188:191], v[216:219], v[8:11]
	v_mfma_f32_16x16x32_bf16 v[4:7], v[196:199], v[208:211], v[4:7]
	v_mfma_f32_16x16x32_bf16 v[0:3], v[196:199], v[216:219], v[0:3]
	v_mfma_f32_16x16x32_bf16 v[28:31], v[176:179], v[212:215], v[28:31]
	v_mfma_f32_16x16x32_bf16 v[24:27], v[176:179], v[220:223], v[24:27]
	v_mfma_f32_16x16x32_bf16 v[20:23], v[184:187], v[212:215], v[20:23]
	v_mfma_f32_16x16x32_bf16 v[16:19], v[184:187], v[220:223], v[16:19]
	v_mfma_f32_16x16x32_bf16 v[12:15], v[192:195], v[212:215], v[12:15]
	v_mfma_f32_16x16x32_bf16 v[8:11], v[192:195], v[220:223], v[8:11]
	v_mfma_f32_16x16x32_bf16 v[4:7], v[200:203], v[212:215], v[4:7]
	v_mfma_f32_16x16x32_bf16 v[0:3], v[200:203], v[220:223], v[0:3]
	s_setprio 0
	s_add_i32 s10, s10, 2
	s_cmp_lt_u32 s10, 28
	v_lshl_add_u64 v[130:131], v[130:131], 0, s[40:41]
	s_barrier
	s_cbranch_scc1 .LBB0_116
	s_mov_b64 s[4:5], 0xa282f80
	v_add_u32_e32 v137, 0xc000, v136
	v_lshl_add_u64 v[130:131], v[128:129], 0, s[4:5]
	v_readfirstlane_b32 s4, v137
	s_mov_b32 m0, s4
	ds_read_b128 v[140:143], v153
	ds_read_b128 v[146:149], v153 offset:1024
	ds_read_b128 v[154:157], v153 offset:2048
	ds_read_b128 v[158:161], v153 offset:3072
	ds_read_b128 v[162:165], v135
	ds_read_b128 v[166:169], v135 offset:1024
	ds_read_b128 v[170:173], v134
	ds_read_b128 v[174:177], v134 offset:1024
	ds_read_b128 v[178:181], v133
	ds_read_b128 v[182:185], v133 offset:1024
	ds_read_b128 v[186:189], v132
	ds_read_b128 v[190:193], v132 offset:1024
	global_load_lds_dwordx4 v[130:131], off
	s_mov_b64 s[4:5], 0xa2c2f80
	v_add_u32_e32 v130, 0xe000, v136
	v_lshl_add_u64 v[128:129], v[128:129], 0, s[4:5]
	v_readfirstlane_b32 s4, v130
	s_mov_b32 m0, s4
	s_nop 0
	global_load_lds_dwordx4 v[128:129], off
	s_setprio 1
	s_barrier
	s_waitcnt lgkmcnt(0)
	s_waitcnt lgkmcnt(0)
	v_mfma_f32_16x16x32_bf16 v[124:127], v[162:165], v[140:143], v[124:127]
	v_mfma_f32_16x16x32_bf16 v[120:123], v[162:165], v[154:157], v[120:123]
	v_mfma_f32_16x16x32_bf16 v[108:111], v[178:181], v[140:143], v[108:111]
	v_mfma_f32_16x16x32_bf16 v[100:103], v[186:189], v[140:143], v[100:103]
	v_mfma_f32_16x16x32_bf16 v[124:127], v[166:169], v[146:149], v[124:127]
	v_mfma_f32_16x16x32_bf16 v[120:123], v[166:169], v[158:161], v[120:123]
	v_mfma_f32_16x16x32_bf16 v[116:119], v[170:173], v[140:143], v[116:119]
	v_mfma_f32_16x16x32_bf16 v[112:115], v[170:173], v[154:157], v[112:115]
	v_mfma_f32_16x16x32_bf16 v[108:111], v[182:185], v[146:149], v[108:111]
	v_mfma_f32_16x16x32_bf16 v[104:107], v[178:181], v[154:157], v[104:107]
	v_mfma_f32_16x16x32_bf16 v[100:103], v[190:193], v[146:149], v[100:103]
	v_mfma_f32_16x16x32_bf16 v[96:99], v[186:189], v[154:157], v[96:99]
	v_mfma_f32_16x16x32_bf16 v[128:131], v[174:177], v[146:149], v[116:119]
	v_mfma_f32_16x16x32_bf16 v[194:197], v[174:177], v[158:161], v[112:115]
	v_mfma_f32_16x16x32_bf16 v[198:201], v[182:185], v[158:161], v[104:107]
	v_mfma_f32_16x16x32_bf16 v[202:205], v[190:193], v[158:161], v[96:99]
	s_setprio 0
	s_barrier
	s_nop 1
	ds_read_b128 v[96:99], v151
	ds_read_b128 v[104:107], v151 offset:1024
	ds_read_b128 v[112:115], v151 offset:2048
	ds_read_b128 v[116:119], v151 offset:3072
	s_setprio 1
	s_barrier
; #define WAIT_V(n) asm volatile("s_waitcnt vmcnt(" #n ")" ::: "memory")
; #define WAIT_L(n) asm volatile("s_waitcnt lgkmcnt(" #n ")" ::: "memory")
; #define BAR __builtin_amdgcn_s_barrier()
; template <int EPI>
; __device__ __forceinline__ void gemm_tile(const Params& p, const bf16* __restrict__ A, const bf16* __restrict__ Bt, const int K,
;                                           const int nt, const int brow, const int bcol, int pm, int pn) {
;     ...
;     LDB(B1, 0, 1); BAR; WAIT_L(0); MMA(0, 1, At, B1); BAR;
;     LDA(At, 0, 1); WAIT_V(4); BAR; WAIT_L(0); MMA(1, 0, At, B0); MMA(1, 1, At, B1); BAR; }
;   { LDB(B0, 1, 0); LDA(At, 1, 0); WAIT_V(2); BAR; WAIT_L(0); MMA(0, 0, At, B0); BAR;
	s_waitcnt lgkmcnt(0)
	s_waitcnt lgkmcnt(0)
	v_mfma_f32_16x16x32_bf16 v[92:95], v[162:165], v[96:99], v[92:95]
	v_mfma_f32_16x16x32_bf16 v[88:91], v[162:165], v[112:115], v[88:91]
	v_mfma_f32_16x16x32_bf16 v[76:79], v[178:181], v[96:99], v[76:79]
	v_mfma_f32_16x16x32_bf16 v[68:71], v[186:189], v[96:99], v[68:71]
	v_mfma_f32_16x16x32_bf16 v[92:95], v[166:169], v[104:107], v[92:95]
	v_mfma_f32_16x16x32_bf16 v[88:91], v[166:169], v[116:119], v[88:91]
	v_mfma_f32_16x16x32_bf16 v[84:87], v[170:173], v[96:99], v[84:87]
	v_mfma_f32_16x16x32_bf16 v[80:83], v[170:173], v[112:115], v[80:83]
	v_mfma_f32_16x16x32_bf16 v[76:79], v[182:185], v[104:107], v[76:79]
	v_mfma_f32_16x16x32_bf16 v[72:75], v[178:181], v[112:115], v[72:75]
	v_mfma_f32_16x16x32_bf16 v[68:71], v[190:193], v[104:107], v[68:71]
	v_mfma_f32_16x16x32_bf16 v[64:67], v[186:189], v[112:115], v[64:67]
	v_mfma_f32_16x16x32_bf16 v[150:153], v[174:177], v[104:107], v[84:87]
	v_mfma_f32_16x16x32_bf16 v[162:165], v[174:177], v[116:119], v[80:83]
	v_mfma_f32_16x16x32_bf16 v[166:169], v[182:185], v[116:119], v[72:75]
	v_mfma_f32_16x16x32_bf16 v[170:173], v[190:193], v[116:119], v[64:67]
	s_setprio 0
	s_barrier
	s_nop 1
	ds_read_b128 v[64:67], v135 offset:16384
	ds_read_b128 v[72:75], v135 offset:17408
	ds_read_b128 v[80:83], v134 offset:16384
	ds_read_b128 v[84:87], v134 offset:17408
	ds_read_b128 v[174:177], v133 offset:16384
	ds_read_b128 v[178:181], v133 offset:17408
	ds_read_b128 v[182:185], v132 offset:16384
	ds_read_b128 v[186:189], v132 offset:17408
	s_waitcnt vmcnt(4)
	s_setprio 1
	s_barrier
	s_waitcnt lgkmcnt(0)
	s_waitcnt lgkmcnt(0)
	v_mfma_f32_16x16x32_bf16 v[60:63], v[64:67], v[140:143], v[60:63]
	v_mfma_f32_16x16x32_bf16 v[56:59], v[64:67], v[154:157], v[56:59]
	v_mfma_f32_16x16x32_bf16 v[44:47], v[174:177], v[140:143], v[44:47]
	v_mfma_f32_16x16x32_bf16 v[36:39], v[182:185], v[140:143], v[36:39]
	v_mfma_f32_16x16x32_bf16 v[60:63], v[72:75], v[146:149], v[60:63]
	v_mfma_f32_16x16x32_bf16 v[56:59], v[72:75], v[158:161], v[56:59]
	v_mfma_f32_16x16x32_bf16 v[52:55], v[80:83], v[140:143], v[52:55]
	v_mfma_f32_16x16x32_bf16 v[48:51], v[80:83], v[154:157], v[48:51]
	v_mfma_f32_16x16x32_bf16 v[44:47], v[178:181], v[146:149], v[44:47]
	v_mfma_f32_16x16x32_bf16 v[40:43], v[174:177], v[154:157], v[40:43]
	v_mfma_f32_16x16x32_bf16 v[36:39], v[186:189], v[146:149], v[36:39]
	v_mfma_f32_16x16x32_bf16 v[32:35], v[182:185], v[154:157], v[32:35]
	v_mfma_f32_16x16x32_bf16 v[190:193], v[84:87], v[146:149], v[52:55]
	v_mfma_f32_16x16x32_bf16 v[208:211], v[84:87], v[158:161], v[48:51]
	v_mfma_f32_16x16x32_bf16 v[212:215], v[178:181], v[158:161], v[40:43]
	v_mfma_f32_16x16x32_bf16 v[140:143], v[186:189], v[158:161], v[32:35]
	s_setprio 0
	s_setprio 1
	v_mfma_f32_16x16x32_bf16 v[28:31], v[64:67], v[96:99], v[28:31]
	v_mfma_f32_16x16x32_bf16 v[24:27], v[64:67], v[112:115], v[24:27]
	v_mfma_f32_16x16x32_bf16 v[12:15], v[174:177], v[96:99], v[12:15]
	v_mfma_f32_16x16x32_bf16 v[4:7], v[182:185], v[96:99], v[4:7]
	v_mfma_f32_16x16x32_bf16 v[28:31], v[72:75], v[104:107], v[28:31]
	v_mfma_f32_16x16x32_bf16 v[24:27], v[72:75], v[116:119], v[24:27]
	v_mfma_f32_16x16x32_bf16 v[20:23], v[80:83], v[96:99], v[20:23]
	v_mfma_f32_16x16x32_bf16 v[16:19], v[80:83], v[112:115], v[16:19]
	v_mfma_f32_16x16x32_bf16 v[12:15], v[178:181], v[104:107], v[12:15]
	v_mfma_f32_16x16x32_bf16 v[8:11], v[174:177], v[112:115], v[8:11]
	v_mfma_f32_16x16x32_bf16 v[4:7], v[186:189], v[104:107], v[4:7]
	v_mfma_f32_16x16x32_bf16 v[0:3], v[182:185], v[112:115], v[0:3]
	v_mfma_f32_16x16x32_bf16 v[146:149], v[84:87], v[104:107], v[20:23]
	v_mfma_f32_16x16x32_bf16 v[154:157], v[84:87], v[116:119], v[16:19]
	v_mfma_f32_16x16x32_bf16 v[158:161], v[178:181], v[116:119], v[8:11]
	v_mfma_f32_16x16x32_bf16 v[174:177], v[186:189], v[116:119], v[0:3]
	s_setprio 0
	s_barrier
	s_nop 1
	ds_read_b128 v[0:3], v144
	ds_read_b128 v[8:11], v144 offset:1024
	ds_read_b128 v[16:19], v144 offset:2048
	ds_read_b128 v[20:23], v144 offset:3072
	ds_read_b128 v[32:35], v135 offset:32768
	ds_read_b128 v[40:43], v135 offset:33792
	ds_read_b128 v[48:51], v134 offset:32768
	ds_read_b128 v[52:55], v134 offset:33792
	ds_read_b128 v[64:67], v133 offset:32768
	ds_read_b128 v[178:181], v133 offset:33792
	ds_read_b128 v[182:185], v132 offset:32768
	ds_read_b128 v[186:189], v132 offset:33792
	s_waitcnt vmcnt(2)
	s_setprio 1
	s_barrier
; #define WAIT_V(n) asm volatile("s_waitcnt vmcnt(" #n ")" ::: "memory")
; #define WAIT_L(n) asm volatile("s_waitcnt lgkmcnt(" #n ")" ::: "memory")
; #define BAR __builtin_amdgcn_s_barrier()
; template <int EPI>
; __device__ __forceinline__ void gemm_tile(const Params& p, const bf16* __restrict__ A, const bf16* __restrict__ Bt, const int K,
;                                           const int nt, const int brow, const int bcol, int pm, int pn) {
;     ...
;   { LDB(B0, 1, 0); LDA(At, 1, 0); WAIT_V(2); BAR; WAIT_L(0); MMA(0, 0, At, B0); BAR;
;     LDB(B1, 1, 1); WAIT_V(0); BAR; WAIT_L(0); MMA(0, 1, At, B1); BAR;
;     LDA(At, 1, 1); BAR; WAIT_L(0); MMA(1, 0, At, B0); MMA(1, 1, At, B1); BAR; }
;   if (wr == 0) BAR;
	s_waitcnt lgkmcnt(0)
	s_waitcnt lgkmcnt(0)
	v_mfma_f32_16x16x32_bf16 v[72:75], v[32:35], v[0:3], v[124:127]
	v_mfma_f32_16x16x32_bf16 v[116:119], v[40:43], v[8:11], v[72:75]
	v_mfma_f32_16x16x32_bf16 v[72:75], v[32:35], v[16:19], v[120:123]
	v_mfma_f32_16x16x32_bf16 v[124:127], v[40:43], v[20:23], v[72:75]
	v_mfma_f32_16x16x32_bf16 v[72:75], v[48:51], v[0:3], v[128:131]
	v_mfma_f32_16x16x32_bf16 v[112:115], v[52:55], v[8:11], v[72:75]
	v_mfma_f32_16x16x32_bf16 v[72:75], v[48:51], v[16:19], v[194:197]
	v_mfma_f32_16x16x32_bf16 v[120:123], v[52:55], v[20:23], v[72:75]
	v_mfma_f32_16x16x32_bf16 v[72:75], v[64:67], v[0:3], v[108:111]
	v_mfma_f32_16x16x32_bf16 v[104:107], v[178:181], v[8:11], v[72:75]
	v_mfma_f32_16x16x32_bf16 v[72:75], v[64:67], v[16:19], v[198:201]
	v_mfma_f32_16x16x32_bf16 v[108:111], v[178:181], v[20:23], v[72:75]
	v_mfma_f32_16x16x32_bf16 v[72:75], v[182:185], v[0:3], v[100:103]
	v_mfma_f32_16x16x32_bf16 v[96:99], v[186:189], v[8:11], v[72:75]
	v_mfma_f32_16x16x32_bf16 v[72:75], v[182:185], v[16:19], v[202:205]
	v_mfma_f32_16x16x32_bf16 v[100:103], v[186:189], v[20:23], v[72:75]
	s_setprio 0
	s_barrier
	ds_read_b128 v[128:131], v139
	ds_read_b128 v[194:197], v139 offset:1024
	ds_read_b128 v[198:201], v139 offset:2048
	ds_read_b128 v[136:139], v139 offset:3072
	s_waitcnt vmcnt(0)
	s_setprio 1
	s_barrier
	s_waitcnt lgkmcnt(0)
	s_waitcnt lgkmcnt(0)
	v_mfma_f32_16x16x32_bf16 v[72:75], v[32:35], v[128:131], v[92:95]
	v_mfma_f32_16x16x32_bf16 v[32:35], v[32:35], v[198:201], v[88:91]
	v_mfma_f32_16x16x32_bf16 v[92:95], v[40:43], v[136:139], v[32:35]
	v_mfma_f32_16x16x32_bf16 v[32:35], v[48:51], v[128:131], v[150:153]
	v_mfma_f32_16x16x32_bf16 v[80:83], v[52:55], v[194:197], v[32:35]
	v_mfma_f32_16x16x32_bf16 v[32:35], v[48:51], v[198:201], v[162:165]
	v_mfma_f32_16x16x32_bf16 v[88:91], v[52:55], v[136:139], v[32:35]
	v_mfma_f32_16x16x32_bf16 v[32:35], v[64:67], v[128:131], v[76:79]
	v_mfma_f32_16x16x32_bf16 v[84:87], v[40:43], v[194:197], v[72:75]
	v_mfma_f32_16x16x32_bf16 v[72:75], v[178:181], v[194:197], v[32:35]
	v_mfma_f32_16x16x32_bf16 v[32:35], v[64:67], v[198:201], v[166:169]
	v_mfma_f32_16x16x32_bf16 v[76:79], v[178:181], v[136:139], v[32:35]
	v_mfma_f32_16x16x32_bf16 v[32:35], v[182:185], v[128:131], v[68:71]
	v_mfma_f32_16x16x32_bf16 v[64:67], v[186:189], v[194:197], v[32:35]
	v_mfma_f32_16x16x32_bf16 v[32:35], v[182:185], v[198:201], v[170:173]
	v_mfma_f32_16x16x32_bf16 v[68:71], v[186:189], v[136:139], v[32:35]
	s_setprio 0
	s_barrier
	ds_read_b128 v[150:153], v135 offset:49152
	ds_read_b128 v[162:165], v135 offset:50176
	ds_read_b128 v[166:169], v134 offset:49152
	ds_read_b128 v[170:173], v134 offset:50176
	ds_read_b128 v[178:181], v133 offset:49152
	ds_read_b128 v[182:185], v133 offset:50176
	ds_read_b128 v[186:189], v132 offset:49152
	ds_read_b128 v[132:135], v132 offset:50176
	s_setprio 1
	s_barrier
	s_waitcnt lgkmcnt(0)
	s_waitcnt lgkmcnt(0)
	v_mfma_f32_16x16x32_bf16 v[32:35], v[150:153], v[0:3], v[60:63]
	v_mfma_f32_16x16x32_bf16 v[52:55], v[162:165], v[8:11], v[32:35]
	v_mfma_f32_16x16x32_bf16 v[32:35], v[150:153], v[16:19], v[56:59]
	v_mfma_f32_16x16x32_bf16 v[60:63], v[162:165], v[20:23], v[32:35]
	v_mfma_f32_16x16x32_bf16 v[32:35], v[166:169], v[0:3], v[190:193]
	v_mfma_f32_16x16x32_bf16 v[48:51], v[170:173], v[8:11], v[32:35]
	v_mfma_f32_16x16x32_bf16 v[32:35], v[166:169], v[16:19], v[208:211]
	v_mfma_f32_16x16x32_bf16 v[56:59], v[170:173], v[20:23], v[32:35]
	v_mfma_f32_16x16x32_bf16 v[32:35], v[178:181], v[0:3], v[44:47]
	v_mfma_f32_16x16x32_bf16 v[40:43], v[182:185], v[8:11], v[32:35]
	v_mfma_f32_16x16x32_bf16 v[32:35], v[178:181], v[16:19], v[212:215]
	v_mfma_f32_16x16x32_bf16 v[0:3], v[186:189], v[0:3], v[36:39]
	v_mfma_f32_16x16x32_bf16 v[44:47], v[182:185], v[20:23], v[32:35]
	v_mfma_f32_16x16x32_bf16 v[32:35], v[132:135], v[8:11], v[0:3]
	v_mfma_f32_16x16x32_bf16 v[0:3], v[186:189], v[16:19], v[140:143]
	v_mfma_f32_16x16x32_bf16 v[36:39], v[132:135], v[20:23], v[0:3]
	s_setprio 0
	s_setprio 1
	v_mfma_f32_16x16x32_bf16 v[0:3], v[150:153], v[128:131], v[28:31]
	v_mfma_f32_16x16x32_bf16 v[20:23], v[162:165], v[194:197], v[0:3]
	v_mfma_f32_16x16x32_bf16 v[0:3], v[150:153], v[198:201], v[24:27]
	v_mfma_f32_16x16x32_bf16 v[28:31], v[162:165], v[136:139], v[0:3]
	v_mfma_f32_16x16x32_bf16 v[0:3], v[166:169], v[128:131], v[146:149]
	v_mfma_f32_16x16x32_bf16 v[16:19], v[170:173], v[194:197], v[0:3]
	v_mfma_f32_16x16x32_bf16 v[0:3], v[166:169], v[198:201], v[154:157]
	v_mfma_f32_16x16x32_bf16 v[24:27], v[170:173], v[136:139], v[0:3]
	v_mfma_f32_16x16x32_bf16 v[0:3], v[178:181], v[128:131], v[12:15]
	v_mfma_f32_16x16x32_bf16 v[8:11], v[182:185], v[194:197], v[0:3]
	v_mfma_f32_16x16x32_bf16 v[0:3], v[178:181], v[198:201], v[158:161]
	v_mfma_f32_16x16x32_bf16 v[12:15], v[182:185], v[136:139], v[0:3]
	v_mfma_f32_16x16x32_bf16 v[0:3], v[186:189], v[128:131], v[4:7]
	v_mfma_f32_16x16x32_bf16 v[4:7], v[186:189], v[198:201], v[174:177]
	v_mfma_f32_16x16x32_bf16 v[0:3], v[132:135], v[194:197], v[0:3]
	v_mfma_f32_16x16x32_bf16 v[4:7], v[132:135], v[136:139], v[4:7]
	s_setprio 0
	s_cmpk_gt_u32 s2, 0xff
	s_barrier
	s_cbranch_scc1 .LBB0_119
	s_barrier

; #define WAIT_L(n) asm volatile("s_waitcnt lgkmcnt(" #n ")" ::: "memory")
; #define BAR __builtin_amdgcn_s_barrier()
; #define SCHED __builtin_amdgcn_sched_barrier(0)
; template <int EPI>
; __device__ __forceinline__ void gemm_tile(const Params& p, const bf16* __restrict__ A, const bf16* __restrict__ Bt, const int K,
;                                           const int nt, const int brow, const int bcol, int pm, int pn) {
;     ...
;     LDB(B0, 0, 0); SCHED; LDA(At, 0, 0); STAGE(SA(1, 1), A, brow + HALF, t + 1);
;     WAIT_L(8); BAR; WAIT_L(0); MMA(0, 0, At, B0); BAR; SCHED;
;     LDB(B1, 0, 1); STAGE(SB(0, 0), Bt, bcol, t + 2);
;     BAR; WAIT_L(0); MMA(0, 1, At, B1); BAR;
;     LDA(At, 0, 1); STAGE(SA(0, 0), A, brow, t + 2);
;     BAR; WAIT_L(0); MMA(1, 0, At, B0); BAR; SCHED;
.LBB0_415:
	ds_read_b128 v[162:165], v160
	ds_read_b128 v[166:169], v160 offset:1024
	ds_read_b128 v[170:173], v160 offset:2048
	ds_read_b128 v[174:177], v160 offset:3072
	v_lshl_add_u64 v[228:229], s[38:39], 0, v[128:129]
	s_mov_b64 s[40:41], 0x6282080
	v_readfirstlane_b32 s31, v159
	v_lshl_add_u64 v[212:213], v[228:229], 0, s[40:41]
	s_mov_b32 m0, s31
	s_mov_b64 s[40:41], 0x62c2080
	v_readfirstlane_b32 s31, v158
	ds_read_b128 v[178:181], v136
	ds_read_b128 v[182:185], v136 offset:1024
	ds_read_b128 v[186:189], v135
	ds_read_b128 v[190:193], v135 offset:1024
	ds_read_b128 v[194:197], v131
	ds_read_b128 v[198:201], v131 offset:1024
	ds_read_b128 v[202:205], v130
	ds_read_b128 v[208:211], v130 offset:1024
	global_load_lds_dwordx4 v[212:213], off
	v_lshl_add_u64 v[212:213], v[228:229], 0, s[40:41]
	s_mov_b32 m0, s31
	s_nop 0
	global_load_lds_dwordx4 v[212:213], off
	s_waitcnt lgkmcnt(8)
	s_setprio 1
	s_barrier
	s_waitcnt lgkmcnt(0)
	s_waitcnt lgkmcnt(0)
	v_mfma_f32_16x16x32_bf16 v[124:127], v[178:181], v[162:165], v[124:127]
	v_mfma_f32_16x16x32_bf16 v[120:123], v[178:181], v[170:173], v[120:123]
	v_mfma_f32_16x16x32_bf16 v[116:119], v[186:189], v[162:165], v[116:119]
	v_mfma_f32_16x16x32_bf16 v[112:115], v[186:189], v[170:173], v[112:115]
	v_mfma_f32_16x16x32_bf16 v[108:111], v[194:197], v[162:165], v[108:111]
	v_mfma_f32_16x16x32_bf16 v[104:107], v[194:197], v[170:173], v[104:107]
	v_mfma_f32_16x16x32_bf16 v[100:103], v[202:205], v[162:165], v[100:103]
	v_mfma_f32_16x16x32_bf16 v[96:99], v[202:205], v[170:173], v[96:99]
	v_mfma_f32_16x16x32_bf16 v[124:127], v[182:185], v[166:169], v[124:127]
	v_mfma_f32_16x16x32_bf16 v[120:123], v[182:185], v[174:177], v[120:123]
	v_mfma_f32_16x16x32_bf16 v[116:119], v[190:193], v[166:169], v[116:119]
	v_mfma_f32_16x16x32_bf16 v[112:115], v[190:193], v[174:177], v[112:115]
	v_mfma_f32_16x16x32_bf16 v[108:111], v[198:201], v[166:169], v[108:111]
	v_mfma_f32_16x16x32_bf16 v[104:107], v[198:201], v[174:177], v[104:107]
	v_mfma_f32_16x16x32_bf16 v[100:103], v[208:211], v[166:169], v[100:103]
	v_mfma_f32_16x16x32_bf16 v[96:99], v[208:211], v[174:177], v[96:99]
	s_setprio 0
	s_barrier
	v_lshl_add_u64 v[230:231], s[36:37], 0, v[128:129]
	s_mov_b64 s[40:41], 0x100
	v_readfirstlane_b32 s31, v134
	v_lshl_add_u64 v[232:233], v[230:231], 0, s[40:41]
	s_mov_b32 m0, s31
	s_mov_b64 s[40:41], 0x40100
	v_readfirstlane_b32 s31, v137
	ds_read_b128 v[212:215], v156
	ds_read_b128 v[216:219], v156 offset:1024
	ds_read_b128 v[220:223], v156 offset:2048
	ds_read_b128 v[224:227], v156 offset:3072
	global_load_lds_dwordx4 v[232:233], off
	v_lshl_add_u64 v[232:233], v[230:231], 0, s[40:41]
	s_mov_b32 m0, s31
	s_nop 0
	global_load_lds_dwordx4 v[232:233], off
	s_setprio 1
	s_barrier
	s_waitcnt lgkmcnt(0)
	s_waitcnt lgkmcnt(0)
	v_mfma_f32_16x16x32_bf16 v[92:95], v[178:181], v[212:215], v[92:95]
	v_mfma_f32_16x16x32_bf16 v[88:91], v[178:181], v[220:223], v[88:91]
	v_mfma_f32_16x16x32_bf16 v[84:87], v[186:189], v[212:215], v[84:87]
	v_mfma_f32_16x16x32_bf16 v[80:83], v[186:189], v[220:223], v[80:83]
	v_mfma_f32_16x16x32_bf16 v[76:79], v[194:197], v[212:215], v[76:79]
	v_mfma_f32_16x16x32_bf16 v[72:75], v[194:197], v[220:223], v[72:75]
	v_mfma_f32_16x16x32_bf16 v[68:71], v[202:205], v[212:215], v[68:71]
	v_mfma_f32_16x16x32_bf16 v[64:67], v[202:205], v[220:223], v[64:67]
	v_mfma_f32_16x16x32_bf16 v[92:95], v[182:185], v[216:219], v[92:95]
	v_mfma_f32_16x16x32_bf16 v[88:91], v[182:185], v[224:227], v[88:91]
	v_mfma_f32_16x16x32_bf16 v[84:87], v[190:193], v[216:219], v[84:87]
	v_mfma_f32_16x16x32_bf16 v[80:83], v[190:193], v[224:227], v[80:83]
	v_mfma_f32_16x16x32_bf16 v[76:79], v[198:201], v[216:219], v[76:79]
	v_mfma_f32_16x16x32_bf16 v[72:75], v[198:201], v[224:227], v[72:75]
	v_mfma_f32_16x16x32_bf16 v[68:71], v[208:211], v[216:219], v[68:71]
	v_mfma_f32_16x16x32_bf16 v[64:67], v[208:211], v[224:227], v[64:67]
	s_setprio 0
	s_mov_b64 s[40:41], 0x6202100
	v_readfirstlane_b32 s31, v138
	v_lshl_add_u64 v[232:233], v[228:229], 0, s[40:41]
	s_mov_b32 m0, s31
	s_mov_b64 s[40:41], 0x6242100
	v_readfirstlane_b32 s31, v140
	s_barrier
	ds_read_b128 v[178:181], v136 offset:16384
	ds_read_b128 v[182:185], v136 offset:17408
	ds_read_b128 v[186:189], v135 offset:16384
	ds_read_b128 v[190:193], v135 offset:17408
	ds_read_b128 v[194:197], v131 offset:16384
	ds_read_b128 v[198:201], v131 offset:17408
	ds_read_b128 v[202:205], v130 offset:16384
	ds_read_b128 v[208:211], v130 offset:17408
	global_load_lds_dwordx4 v[232:233], off
	v_lshl_add_u64 v[232:233], v[228:229], 0, s[40:41]
	s_mov_b32 m0, s31
	s_nop 0
	global_load_lds_dwordx4 v[232:233], off
	s_setprio 1
	s_barrier
	s_waitcnt lgkmcnt(0)
	s_waitcnt lgkmcnt(0)
	v_mfma_f32_16x16x32_bf16 v[60:63], v[178:181], v[162:165], v[60:63]
	v_mfma_f32_16x16x32_bf16 v[56:59], v[178:181], v[170:173], v[56:59]
	v_mfma_f32_16x16x32_bf16 v[52:55], v[186:189], v[162:165], v[52:55]
	v_mfma_f32_16x16x32_bf16 v[48:51], v[186:189], v[170:173], v[48:51]
	v_mfma_f32_16x16x32_bf16 v[44:47], v[194:197], v[162:165], v[44:47]
	v_mfma_f32_16x16x32_bf16 v[40:43], v[194:197], v[170:173], v[40:43]
	v_mfma_f32_16x16x32_bf16 v[36:39], v[202:205], v[162:165], v[36:39]
	v_mfma_f32_16x16x32_bf16 v[32:35], v[202:205], v[170:173], v[32:35]
	v_mfma_f32_16x16x32_bf16 v[60:63], v[182:185], v[166:169], v[60:63]
	v_mfma_f32_16x16x32_bf16 v[56:59], v[182:185], v[174:177], v[56:59]
	v_mfma_f32_16x16x32_bf16 v[52:55], v[190:193], v[166:169], v[52:55]
	v_mfma_f32_16x16x32_bf16 v[48:51], v[190:193], v[174:177], v[48:51]
	v_mfma_f32_16x16x32_bf16 v[44:47], v[198:201], v[166:169], v[44:47]
	v_mfma_f32_16x16x32_bf16 v[40:43], v[198:201], v[174:177], v[40:43]
	v_mfma_f32_16x16x32_bf16 v[36:39], v[208:211], v[166:169], v[36:39]
	v_mfma_f32_16x16x32_bf16 v[32:35], v[208:211], v[174:177], v[32:35]
	s_setprio 0
	s_barrier
; #define WAIT_V(n) asm volatile("s_waitcnt vmcnt(" #n ")" ::: "memory")
; #define WAIT_L(n) asm volatile("s_waitcnt lgkmcnt(" #n ")" ::: "memory")
; #define BAR __builtin_amdgcn_s_barrier()
; #define SCHED __builtin_amdgcn_sched_barrier(0)
; template <int EPI>
; __device__ __forceinline__ void gemm_tile(const Params& p, const bf16* __restrict__ A, const bf16* __restrict__ Bt, const int K,
;                                           const int nt, const int brow, const int bcol, int pm, int pn) {
;     ...
;     STAGE(SB(0, 1), Bt, bcol + HALF, t + 2);
;     WAIT_V(6); BAR; MMA(1, 1, At, B1); BAR;
;     LDB(B0, 1, 0); SCHED; LDA(At, 1, 0); STAGE(SA(0, 1), A, brow + HALF, t + 2);
;     WAIT_L(8); BAR; WAIT_L(0); MMA(0, 0, At, B0); BAR; SCHED;
;     LDB(B1, 1, 1); STAGE(SB(1, 0), Bt, bcol, t + 3);
;     BAR; WAIT_L(0); MMA(0, 1, At, B1); BAR;
;     LDA(At, 1, 1); STAGE(SA(1, 0), A, brow, t + 3);
	s_mov_b64 s[40:41], 0x80100
	v_readfirstlane_b32 s31, v141
	v_lshl_add_u64 v[162:163], v[230:231], 0, s[40:41]
	s_mov_b32 m0, s31
	s_mov_b64 s[40:41], 0xc0100
	v_readfirstlane_b32 s31, v147
	global_load_lds_dwordx4 v[162:163], off
	v_lshl_add_u64 v[162:163], v[230:231], 0, s[40:41]
	s_mov_b32 m0, s31
	s_nop 0
	global_load_lds_dwordx4 v[162:163], off
	s_waitcnt vmcnt(6)
	s_setprio 1
	s_barrier
	v_mfma_f32_16x16x32_bf16 v[28:31], v[178:181], v[212:215], v[28:31]
	v_mfma_f32_16x16x32_bf16 v[24:27], v[178:181], v[220:223], v[24:27]
	v_mfma_f32_16x16x32_bf16 v[20:23], v[186:189], v[212:215], v[20:23]
	v_mfma_f32_16x16x32_bf16 v[16:19], v[186:189], v[220:223], v[16:19]
	v_mfma_f32_16x16x32_bf16 v[12:15], v[194:197], v[212:215], v[12:15]
	v_mfma_f32_16x16x32_bf16 v[8:11], v[194:197], v[220:223], v[8:11]
	v_mfma_f32_16x16x32_bf16 v[4:7], v[202:205], v[212:215], v[4:7]
	v_mfma_f32_16x16x32_bf16 v[0:3], v[202:205], v[220:223], v[0:3]
	v_mfma_f32_16x16x32_bf16 v[28:31], v[182:185], v[216:219], v[28:31]
	v_mfma_f32_16x16x32_bf16 v[24:27], v[182:185], v[224:227], v[24:27]
	v_mfma_f32_16x16x32_bf16 v[20:23], v[190:193], v[216:219], v[20:23]
	v_mfma_f32_16x16x32_bf16 v[16:19], v[190:193], v[224:227], v[16:19]
	v_mfma_f32_16x16x32_bf16 v[12:15], v[198:201], v[216:219], v[12:15]
	v_mfma_f32_16x16x32_bf16 v[8:11], v[198:201], v[224:227], v[8:11]
	v_mfma_f32_16x16x32_bf16 v[4:7], v[208:211], v[216:219], v[4:7]
	v_mfma_f32_16x16x32_bf16 v[0:3], v[208:211], v[224:227], v[0:3]
	s_setprio 0
	s_barrier
	ds_read_b128 v[162:165], v149
	ds_read_b128 v[166:169], v149 offset:1024
	ds_read_b128 v[170:173], v149 offset:2048
	ds_read_b128 v[174:177], v149 offset:3072
	s_mov_b64 s[40:41], 0x6282100
	v_readfirstlane_b32 s31, v148
	v_lshl_add_u64 v[212:213], v[228:229], 0, s[40:41]
	s_mov_b32 m0, s31
	s_mov_b64 s[40:41], 0x62c2100
	v_readfirstlane_b32 s31, v150
	ds_read_b128 v[178:181], v136 offset:32768
	ds_read_b128 v[182:185], v136 offset:33792
	ds_read_b128 v[186:189], v135 offset:32768
	ds_read_b128 v[190:193], v135 offset:33792
	ds_read_b128 v[194:197], v131 offset:32768
	ds_read_b128 v[198:201], v131 offset:33792
	ds_read_b128 v[202:205], v130 offset:32768
	ds_read_b128 v[208:211], v130 offset:33792
	global_load_lds_dwordx4 v[212:213], off
	v_lshl_add_u64 v[212:213], v[228:229], 0, s[40:41]
	s_mov_b32 m0, s31
	s_nop 0
	global_load_lds_dwordx4 v[212:213], off
	s_waitcnt lgkmcnt(8)
	s_setprio 1
	s_barrier
	s_waitcnt lgkmcnt(0)
	s_waitcnt lgkmcnt(0)
	v_mfma_f32_16x16x32_bf16 v[124:127], v[178:181], v[162:165], v[124:127]
	v_mfma_f32_16x16x32_bf16 v[120:123], v[178:181], v[170:173], v[120:123]
	v_mfma_f32_16x16x32_bf16 v[116:119], v[186:189], v[162:165], v[116:119]
	v_mfma_f32_16x16x32_bf16 v[112:115], v[186:189], v[170:173], v[112:115]
	v_mfma_f32_16x16x32_bf16 v[108:111], v[194:197], v[162:165], v[108:111]
	v_mfma_f32_16x16x32_bf16 v[104:107], v[194:197], v[170:173], v[104:107]
	v_mfma_f32_16x16x32_bf16 v[100:103], v[202:205], v[162:165], v[100:103]
	v_mfma_f32_16x16x32_bf16 v[96:99], v[202:205], v[170:173], v[96:99]
	v_mfma_f32_16x16x32_bf16 v[124:127], v[182:185], v[166:169], v[124:127]
	v_mfma_f32_16x16x32_bf16 v[120:123], v[182:185], v[174:177], v[120:123]
	v_mfma_f32_16x16x32_bf16 v[116:119], v[190:193], v[166:169], v[116:119]
	v_mfma_f32_16x16x32_bf16 v[112:115], v[190:193], v[174:177], v[112:115]
	v_mfma_f32_16x16x32_bf16 v[108:111], v[198:201], v[166:169], v[108:111]
	v_mfma_f32_16x16x32_bf16 v[104:107], v[198:201], v[174:177], v[104:107]
	v_mfma_f32_16x16x32_bf16 v[100:103], v[208:211], v[166:169], v[100:103]
	v_mfma_f32_16x16x32_bf16 v[96:99], v[208:211], v[174:177], v[96:99]
	s_setprio 0
	s_barrier
	s_mov_b64 s[40:41], 0x180
	v_readfirstlane_b32 s31, v151
	v_lshl_add_u64 v[232:233], v[230:231], 0, s[40:41]
	s_mov_b32 m0, s31
	s_mov_b64 s[40:41], 0x40180
	v_readfirstlane_b32 s31, v152
	ds_read_b128 v[212:215], v139
	ds_read_b128 v[216:219], v139 offset:1024
	ds_read_b128 v[220:223], v139 offset:2048
	ds_read_b128 v[224:227], v139 offset:3072
	global_load_lds_dwordx4 v[232:233], off
	v_lshl_add_u64 v[232:233], v[230:231], 0, s[40:41]
	s_mov_b32 m0, s31
	s_nop 0
	global_load_lds_dwordx4 v[232:233], off
	s_setprio 1
	s_barrier
	s_waitcnt lgkmcnt(0)
	s_waitcnt lgkmcnt(0)
	v_mfma_f32_16x16x32_bf16 v[92:95], v[178:181], v[212:215], v[92:95]
	v_mfma_f32_16x16x32_bf16 v[88:91], v[178:181], v[220:223], v[88:91]
	v_mfma_f32_16x16x32_bf16 v[84:87], v[186:189], v[212:215], v[84:87]
	v_mfma_f32_16x16x32_bf16 v[80:83], v[186:189], v[220:223], v[80:83]
	v_mfma_f32_16x16x32_bf16 v[76:79], v[194:197], v[212:215], v[76:79]
	v_mfma_f32_16x16x32_bf16 v[72:75], v[194:197], v[220:223], v[72:75]
	v_mfma_f32_16x16x32_bf16 v[68:71], v[202:205], v[212:215], v[68:71]
	v_mfma_f32_16x16x32_bf16 v[64:67], v[202:205], v[220:223], v[64:67]
	v_mfma_f32_16x16x32_bf16 v[92:95], v[182:185], v[216:219], v[92:95]
	v_mfma_f32_16x16x32_bf16 v[88:91], v[182:185], v[224:227], v[88:91]
	v_mfma_f32_16x16x32_bf16 v[84:87], v[190:193], v[216:219], v[84:87]
	v_mfma_f32_16x16x32_bf16 v[80:83], v[190:193], v[224:227], v[80:83]
	v_mfma_f32_16x16x32_bf16 v[76:79], v[198:201], v[216:219], v[76:79]
	v_mfma_f32_16x16x32_bf16 v[72:75], v[198:201], v[224:227], v[72:75]
	v_mfma_f32_16x16x32_bf16 v[68:71], v[208:211], v[216:219], v[68:71]
	v_mfma_f32_16x16x32_bf16 v[64:67], v[208:211], v[224:227], v[64:67]
	s_setprio 0
	s_mov_b64 s[40:41], 0x6202180
	v_readfirstlane_b32 s31, v153
	v_lshl_add_u64 v[232:233], v[228:229], 0, s[40:41]
	s_mov_b32 m0, s31
	s_mov_b64 s[40:41], 0x6242180
	v_readfirstlane_b32 s31, v154
	s_barrier
; #define WAIT_V(n) asm volatile("s_waitcnt vmcnt(" #n ")" ::: "memory")
; #define WAIT_L(n) asm volatile("s_waitcnt lgkmcnt(" #n ")" ::: "memory")
; #define BAR __builtin_amdgcn_s_barrier()
; #define SCHED __builtin_amdgcn_sched_barrier(0)
; template <int EPI>
; __device__ __forceinline__ void gemm_tile(const Params& p, const bf16* __restrict__ A, const bf16* __restrict__ Bt, const int K,
;                                           const int nt, const int brow, const int bcol, int pm, int pn) {
;     ...
;     LDA(At, 1, 1); STAGE(SA(1, 0), A, brow, t + 3);
;     BAR; WAIT_L(0); MMA(1, 0, At, B0); BAR; SCHED;
;     STAGE(SB(1, 1), Bt, bcol + HALF, t + 3);
;     WAIT_V(6); BAR; MMA(1, 1, At, B1); BAR;
;   }
;   { LDB(B0, 0, 0); LDA(At, 0, 0); STAGE(SA(1, 1), A, brow + HALF, nt - 1);
;     BAR; WAIT_L(0); MMA(0, 0, At, B0); BAR;
	ds_read_b128 v[178:181], v136 offset:49152
	ds_read_b128 v[182:185], v136 offset:50176
	ds_read_b128 v[186:189], v135 offset:49152
	ds_read_b128 v[190:193], v135 offset:50176
	ds_read_b128 v[194:197], v131 offset:49152
	ds_read_b128 v[198:201], v131 offset:50176
	ds_read_b128 v[202:205], v130 offset:49152
	ds_read_b128 v[208:211], v130 offset:50176
	global_load_lds_dwordx4 v[232:233], off
	v_lshl_add_u64 v[228:229], v[228:229], 0, s[40:41]
	s_mov_b32 m0, s31
	s_nop 0
	global_load_lds_dwordx4 v[228:229], off
	s_setprio 1
	s_barrier
	s_waitcnt lgkmcnt(0)
	s_waitcnt lgkmcnt(0)
	v_mfma_f32_16x16x32_bf16 v[60:63], v[178:181], v[162:165], v[60:63]
	v_mfma_f32_16x16x32_bf16 v[56:59], v[178:181], v[170:173], v[56:59]
	v_mfma_f32_16x16x32_bf16 v[52:55], v[186:189], v[162:165], v[52:55]
	v_mfma_f32_16x16x32_bf16 v[48:51], v[186:189], v[170:173], v[48:51]
	v_mfma_f32_16x16x32_bf16 v[44:47], v[194:197], v[162:165], v[44:47]
	v_mfma_f32_16x16x32_bf16 v[40:43], v[194:197], v[170:173], v[40:43]
	v_mfma_f32_16x16x32_bf16 v[36:39], v[202:205], v[162:165], v[36:39]
	v_mfma_f32_16x16x32_bf16 v[32:35], v[202:205], v[170:173], v[32:35]
	v_mfma_f32_16x16x32_bf16 v[60:63], v[182:185], v[166:169], v[60:63]
	v_mfma_f32_16x16x32_bf16 v[56:59], v[182:185], v[174:177], v[56:59]
	v_mfma_f32_16x16x32_bf16 v[52:55], v[190:193], v[166:169], v[52:55]
	v_mfma_f32_16x16x32_bf16 v[48:51], v[190:193], v[174:177], v[48:51]
	v_mfma_f32_16x16x32_bf16 v[44:47], v[198:201], v[166:169], v[44:47]
	v_mfma_f32_16x16x32_bf16 v[40:43], v[198:201], v[174:177], v[40:43]
	v_mfma_f32_16x16x32_bf16 v[36:39], v[208:211], v[166:169], v[36:39]
	v_mfma_f32_16x16x32_bf16 v[32:35], v[208:211], v[174:177], v[32:35]
	s_setprio 0
	s_barrier
	s_mov_b64 s[40:41], 0x80180
	v_readfirstlane_b32 s31, v155
	v_lshl_add_u64 v[162:163], v[230:231], 0, s[40:41]
	s_mov_b32 m0, s31
	s_mov_b64 s[40:41], 0xc0180
	v_readfirstlane_b32 s31, v157
	global_load_lds_dwordx4 v[162:163], off
	v_lshl_add_u64 v[162:163], v[230:231], 0, s[40:41]
	s_mov_b32 m0, s31
	s_nop 0
	global_load_lds_dwordx4 v[162:163], off
	s_waitcnt vmcnt(6)
	s_setprio 1
	s_barrier
	v_mfma_f32_16x16x32_bf16 v[28:31], v[178:181], v[212:215], v[28:31]
	v_mfma_f32_16x16x32_bf16 v[24:27], v[178:181], v[220:223], v[24:27]
	v_mfma_f32_16x16x32_bf16 v[20:23], v[186:189], v[212:215], v[20:23]
	v_mfma_f32_16x16x32_bf16 v[16:19], v[186:189], v[220:223], v[16:19]
	v_mfma_f32_16x16x32_bf16 v[12:15], v[194:197], v[212:215], v[12:15]
	v_mfma_f32_16x16x32_bf16 v[8:11], v[194:197], v[220:223], v[8:11]
	v_mfma_f32_16x16x32_bf16 v[4:7], v[202:205], v[212:215], v[4:7]
	v_mfma_f32_16x16x32_bf16 v[0:3], v[202:205], v[220:223], v[0:3]
	v_mfma_f32_16x16x32_bf16 v[28:31], v[182:185], v[216:219], v[28:31]
	v_mfma_f32_16x16x32_bf16 v[24:27], v[182:185], v[224:227], v[24:27]
	v_mfma_f32_16x16x32_bf16 v[20:23], v[190:193], v[216:219], v[20:23]
	v_mfma_f32_16x16x32_bf16 v[16:19], v[190:193], v[224:227], v[16:19]
	v_mfma_f32_16x16x32_bf16 v[12:15], v[198:201], v[216:219], v[12:15]
	v_mfma_f32_16x16x32_bf16 v[8:11], v[198:201], v[224:227], v[8:11]
	v_mfma_f32_16x16x32_bf16 v[4:7], v[208:211], v[216:219], v[4:7]
	v_mfma_f32_16x16x32_bf16 v[0:3], v[208:211], v[224:227], v[0:3]
	s_setprio 0
	s_add_i32 s9, s9, 2
	s_add_u32 s38, s38, 0x100
	s_addc_u32 s39, s39, 0
	s_add_u32 s36, s36, 0x100
	s_addc_u32 s37, s37, 0
	s_cmp_lt_u32 s9, 28
	s_barrier
	s_cbranch_scc1 .LBB0_415
	s_add_u32 s6, s60, s6
	s_addc_u32 s7, s61, s7
	v_lshl_add_u64 v[128:129], s[6:7], 0, v[132:133]
	v_readfirstlane_b32 s6, v159
	s_mov_b32 m0, s6
	s_add_u32 s6, s60, s34
	v_lshl_add_u64 v[128:129], v[128:129], 0, s[28:29]
	s_addc_u32 s7, s61, s35
	ds_read_b128 v[150:153], v160
	ds_read_b128 v[162:165], v160 offset:1024
	ds_read_b128 v[166:169], v160 offset:2048
	ds_read_b128 v[170:173], v160 offset:3072
	ds_read_b128 v[174:177], v136
	ds_read_b128 v[178:181], v136 offset:1024
	ds_read_b128 v[182:185], v135
	ds_read_b128 v[186:189], v135 offset:1024
	ds_read_b128 v[190:193], v131
	ds_read_b128 v[194:197], v131 offset:1024
	ds_read_b128 v[198:201], v130
	ds_read_b128 v[202:205], v130 offset:1024
	global_load_lds_dwordx4 v[128:129], off
	v_lshl_add_u64 v[128:129], s[6:7], 0, v[132:133]
	v_readfirstlane_b32 s6, v158
	v_lshl_add_u64 v[128:129], v[128:129], 0, s[28:29]
	s_mov_b32 m0, s6
	s_nop 0
	global_load_lds_dwordx4 v[128:129], off
	s_setprio 1
	s_barrier
	s_waitcnt lgkmcnt(0)
	s_waitcnt lgkmcnt(0)
	v_mfma_f32_16x16x32_bf16 v[124:127], v[174:177], v[150:153], v[124:127]
	v_mfma_f32_16x16x32_bf16 v[120:123], v[174:177], v[166:169], v[120:123]
	v_mfma_f32_16x16x32_bf16 v[116:119], v[182:185], v[150:153], v[116:119]
	v_mfma_f32_16x16x32_bf16 v[108:111], v[190:193], v[150:153], v[108:111]
	v_mfma_f32_16x16x32_bf16 v[124:127], v[178:181], v[162:165], v[124:127]
	v_mfma_f32_16x16x32_bf16 v[120:123], v[178:181], v[170:173], v[120:123]
	v_mfma_f32_16x16x32_bf16 v[116:119], v[186:189], v[162:165], v[116:119]
	v_mfma_f32_16x16x32_bf16 v[112:115], v[182:185], v[166:169], v[112:115]
	v_mfma_f32_16x16x32_bf16 v[108:111], v[194:197], v[162:165], v[108:111]
	v_mfma_f32_16x16x32_bf16 v[104:107], v[190:193], v[166:169], v[104:107]
	v_mfma_f32_16x16x32_bf16 v[100:103], v[198:201], v[150:153], v[100:103]
	v_mfma_f32_16x16x32_bf16 v[96:99], v[198:201], v[166:169], v[96:99]
	v_mfma_f32_16x16x32_bf16 v[158:161], v[186:189], v[170:173], v[112:115]
	v_mfma_f32_16x16x32_bf16 v[208:211], v[194:197], v[170:173], v[104:107]
	v_mfma_f32_16x16x32_bf16 v[212:215], v[202:205], v[162:165], v[100:103]
	v_mfma_f32_16x16x32_bf16 v[216:219], v[202:205], v[170:173], v[96:99]
	s_setprio 0
	s_barrier
; #define WAIT_V(n) asm volatile("s_waitcnt vmcnt(" #n ")" ::: "memory")
; #define WAIT_L(n) asm volatile("s_waitcnt lgkmcnt(" #n ")" ::: "memory")
; #define BAR __builtin_amdgcn_s_barrier()
; template <int EPI>
; __device__ __forceinline__ void gemm_tile(const Params& p, const bf16* __restrict__ A, const bf16* __restrict__ Bt, const int K,
;                                           const int nt, const int brow, const int bcol, int pm, int pn) {
;     ...
;     LDB(B1, 0, 1); BAR; WAIT_L(0); MMA(0, 1, At, B1); BAR;
;     LDA(At, 0, 1); WAIT_V(4); BAR; WAIT_L(0); MMA(1, 0, At, B0); MMA(1, 1, At, B1); BAR; }
;   { LDB(B0, 1, 0); LDA(At, 1, 0); WAIT_V(2); BAR; WAIT_L(0); MMA(0, 0, At, B0); BAR;
	s_nop 1
	ds_read_b128 v[96:99], v156
	ds_read_b128 v[100:103], v156 offset:1024
	ds_read_b128 v[104:107], v156 offset:2048
	ds_read_b128 v[112:115], v156 offset:3072
	s_setprio 1
	s_barrier
	s_waitcnt lgkmcnt(0)
	s_waitcnt lgkmcnt(0)
	v_mfma_f32_16x16x32_bf16 v[92:95], v[174:177], v[96:99], v[92:95]
	v_mfma_f32_16x16x32_bf16 v[88:91], v[174:177], v[104:107], v[88:91]
	v_mfma_f32_16x16x32_bf16 v[84:87], v[182:185], v[96:99], v[84:87]
	v_mfma_f32_16x16x32_bf16 v[76:79], v[190:193], v[96:99], v[76:79]
	v_mfma_f32_16x16x32_bf16 v[92:95], v[178:181], v[100:103], v[92:95]
	v_mfma_f32_16x16x32_bf16 v[88:91], v[178:181], v[112:115], v[88:91]
	v_mfma_f32_16x16x32_bf16 v[84:87], v[186:189], v[100:103], v[84:87]
	v_mfma_f32_16x16x32_bf16 v[80:83], v[182:185], v[104:107], v[80:83]
	v_mfma_f32_16x16x32_bf16 v[76:79], v[194:197], v[100:103], v[76:79]
	v_mfma_f32_16x16x32_bf16 v[72:75], v[190:193], v[104:107], v[72:75]
	v_mfma_f32_16x16x32_bf16 v[68:71], v[198:201], v[96:99], v[68:71]
	v_mfma_f32_16x16x32_bf16 v[64:67], v[198:201], v[104:107], v[64:67]
	v_mfma_f32_16x16x32_bf16 v[154:157], v[186:189], v[112:115], v[80:83]
	v_mfma_f32_16x16x32_bf16 v[174:177], v[194:197], v[112:115], v[72:75]
	v_mfma_f32_16x16x32_bf16 v[178:181], v[202:205], v[100:103], v[68:71]
	v_mfma_f32_16x16x32_bf16 v[182:185], v[202:205], v[112:115], v[64:67]
	s_setprio 0
	s_barrier
	s_nop 1
	ds_read_b128 v[64:67], v136 offset:16384
	ds_read_b128 v[68:71], v136 offset:17408
	ds_read_b128 v[72:75], v135 offset:16384
	ds_read_b128 v[80:83], v135 offset:17408
	ds_read_b128 v[186:189], v131 offset:16384
	ds_read_b128 v[190:193], v131 offset:17408
	ds_read_b128 v[194:197], v130 offset:16384
	ds_read_b128 v[198:201], v130 offset:17408
	s_waitcnt vmcnt(4)
	s_setprio 1
	s_barrier
	s_waitcnt lgkmcnt(0)
	s_waitcnt lgkmcnt(0)
	v_mfma_f32_16x16x32_bf16 v[60:63], v[64:67], v[150:153], v[60:63]
	v_mfma_f32_16x16x32_bf16 v[56:59], v[64:67], v[166:169], v[56:59]
	v_mfma_f32_16x16x32_bf16 v[52:55], v[72:75], v[150:153], v[52:55]
	v_mfma_f32_16x16x32_bf16 v[44:47], v[186:189], v[150:153], v[44:47]
	v_mfma_f32_16x16x32_bf16 v[60:63], v[68:71], v[162:165], v[60:63]
	v_mfma_f32_16x16x32_bf16 v[56:59], v[68:71], v[170:173], v[56:59]
	v_mfma_f32_16x16x32_bf16 v[52:55], v[80:83], v[162:165], v[52:55]
	v_mfma_f32_16x16x32_bf16 v[48:51], v[72:75], v[166:169], v[48:51]
	v_mfma_f32_16x16x32_bf16 v[44:47], v[190:193], v[162:165], v[44:47]
	v_mfma_f32_16x16x32_bf16 v[40:43], v[186:189], v[166:169], v[40:43]
	v_mfma_f32_16x16x32_bf16 v[36:39], v[194:197], v[150:153], v[36:39]
	v_mfma_f32_16x16x32_bf16 v[32:35], v[194:197], v[166:169], v[32:35]
	v_mfma_f32_16x16x32_bf16 v[202:205], v[80:83], v[170:173], v[48:51]
	v_mfma_f32_16x16x32_bf16 v[220:223], v[190:193], v[170:173], v[40:43]
	v_mfma_f32_16x16x32_bf16 v[150:153], v[198:201], v[162:165], v[36:39]
	v_mfma_f32_16x16x32_bf16 v[162:165], v[198:201], v[170:173], v[32:35]
	s_setprio 0
	s_setprio 1
	v_mfma_f32_16x16x32_bf16 v[28:31], v[64:67], v[96:99], v[28:31]
	v_mfma_f32_16x16x32_bf16 v[24:27], v[64:67], v[104:107], v[24:27]
	v_mfma_f32_16x16x32_bf16 v[20:23], v[72:75], v[96:99], v[20:23]
	v_mfma_f32_16x16x32_bf16 v[12:15], v[186:189], v[96:99], v[12:15]
	v_mfma_f32_16x16x32_bf16 v[28:31], v[68:71], v[100:103], v[28:31]
	v_mfma_f32_16x16x32_bf16 v[24:27], v[68:71], v[112:115], v[24:27]
	v_mfma_f32_16x16x32_bf16 v[20:23], v[80:83], v[100:103], v[20:23]
	v_mfma_f32_16x16x32_bf16 v[16:19], v[72:75], v[104:107], v[16:19]
	v_mfma_f32_16x16x32_bf16 v[12:15], v[190:193], v[100:103], v[12:15]
	v_mfma_f32_16x16x32_bf16 v[8:11], v[186:189], v[104:107], v[8:11]
	v_mfma_f32_16x16x32_bf16 v[4:7], v[194:197], v[96:99], v[4:7]
	v_mfma_f32_16x16x32_bf16 v[0:3], v[194:197], v[104:107], v[0:3]
	v_mfma_f32_16x16x32_bf16 v[166:169], v[80:83], v[112:115], v[16:19]
	v_mfma_f32_16x16x32_bf16 v[170:173], v[190:193], v[112:115], v[8:11]
	v_mfma_f32_16x16x32_bf16 v[186:189], v[198:201], v[100:103], v[4:7]
	v_mfma_f32_16x16x32_bf16 v[190:193], v[198:201], v[112:115], v[0:3]
	s_setprio 0
	s_barrier
	s_nop 1
	ds_read_b128 v[0:3], v149
	ds_read_b128 v[4:7], v149 offset:1024
	ds_read_b128 v[8:11], v149 offset:2048
	ds_read_b128 v[16:19], v149 offset:3072
	ds_read_b128 v[32:35], v136 offset:32768
	ds_read_b128 v[36:39], v136 offset:33792
	ds_read_b128 v[40:43], v135 offset:32768
	ds_read_b128 v[48:51], v135 offset:33792
	ds_read_b128 v[194:197], v131 offset:32768
	ds_read_b128 v[198:201], v131 offset:33792
	ds_read_b128 v[224:227], v130 offset:32768
	ds_read_b128 v[228:231], v130 offset:33792
	s_waitcnt vmcnt(2)
	s_setprio 1
	s_barrier
; #define WAIT_V(n) asm volatile("s_waitcnt vmcnt(" #n ")" ::: "memory")
; #define WAIT_L(n) asm volatile("s_waitcnt lgkmcnt(" #n ")" ::: "memory")
; #define BAR __builtin_amdgcn_s_barrier()
; template <int EPI>
; __device__ __forceinline__ void gemm_tile(const Params& p, const bf16* __restrict__ A, const bf16* __restrict__ Bt, const int K,
;                                           const int nt, const int brow, const int bcol, int pm, int pn) {
;     ...
;   { LDB(B0, 1, 0); LDA(At, 1, 0); WAIT_V(2); BAR; WAIT_L(0); MMA(0, 0, At, B0); BAR;
;     LDB(B1, 1, 1); WAIT_V(0); BAR; WAIT_L(0); MMA(0, 1, At, B1); BAR;
;     LDA(At, 1, 1); BAR; WAIT_L(0); MMA(1, 0, At, B0); MMA(1, 1, At, B1); BAR; }
;   if (wr == 0) BAR;
	s_waitcnt lgkmcnt(0)
	s_waitcnt lgkmcnt(0)
	v_mfma_f32_16x16x32_bf16 v[64:67], v[32:35], v[0:3], v[124:127]
	v_mfma_f32_16x16x32_bf16 v[96:99], v[36:39], v[4:7], v[64:67]
	v_mfma_f32_16x16x32_bf16 v[64:67], v[32:35], v[8:11], v[120:123]
	v_mfma_f32_16x16x32_bf16 v[112:115], v[36:39], v[16:19], v[64:67]
	v_mfma_f32_16x16x32_bf16 v[64:67], v[40:43], v[0:3], v[116:119]
	v_mfma_f32_16x16x32_bf16 v[100:103], v[48:51], v[4:7], v[64:67]
	v_mfma_f32_16x16x32_bf16 v[64:67], v[40:43], v[8:11], v[158:161]
	v_mfma_f32_16x16x32_bf16 v[116:119], v[48:51], v[16:19], v[64:67]
	v_mfma_f32_16x16x32_bf16 v[64:67], v[194:197], v[0:3], v[108:111]
	v_mfma_f32_16x16x32_bf16 v[104:107], v[198:201], v[4:7], v[64:67]
	v_mfma_f32_16x16x32_bf16 v[64:67], v[194:197], v[8:11], v[208:211]
	v_mfma_f32_16x16x32_bf16 v[120:123], v[198:201], v[16:19], v[64:67]
	v_mfma_f32_16x16x32_bf16 v[64:67], v[224:227], v[0:3], v[212:215]
	v_mfma_f32_16x16x32_bf16 v[108:111], v[228:231], v[4:7], v[64:67]
	v_mfma_f32_16x16x32_bf16 v[64:67], v[224:227], v[8:11], v[216:219]
	v_mfma_f32_16x16x32_bf16 v[124:127], v[228:231], v[16:19], v[64:67]
	s_setprio 0
	s_barrier
	ds_read_b128 v[158:161], v139
	ds_read_b128 v[208:211], v139 offset:1024
	ds_read_b128 v[212:215], v139 offset:2048
	ds_read_b128 v[138:141], v139 offset:3072
	s_waitcnt vmcnt(0)
	s_setprio 1
	s_barrier
	s_waitcnt lgkmcnt(0)
	s_waitcnt lgkmcnt(0)
	v_mfma_f32_16x16x32_bf16 v[64:67], v[32:35], v[158:161], v[92:95]
	v_mfma_f32_16x16x32_bf16 v[32:35], v[32:35], v[212:215], v[88:91]
	v_mfma_f32_16x16x32_bf16 v[80:83], v[36:39], v[138:141], v[32:35]
	v_mfma_f32_16x16x32_bf16 v[32:35], v[40:43], v[158:161], v[84:87]
	v_mfma_f32_16x16x32_bf16 v[68:71], v[48:51], v[208:211], v[32:35]
	v_mfma_f32_16x16x32_bf16 v[32:35], v[40:43], v[212:215], v[154:157]
	v_mfma_f32_16x16x32_bf16 v[84:87], v[48:51], v[138:141], v[32:35]
	v_mfma_f32_16x16x32_bf16 v[32:35], v[194:197], v[158:161], v[76:79]
	v_mfma_f32_16x16x32_bf16 v[72:75], v[198:201], v[208:211], v[32:35]
	v_mfma_f32_16x16x32_bf16 v[32:35], v[194:197], v[212:215], v[174:177]
	v_mfma_f32_16x16x32_bf16 v[88:91], v[198:201], v[138:141], v[32:35]
	v_mfma_f32_16x16x32_bf16 v[32:35], v[224:227], v[158:161], v[178:181]
	v_mfma_f32_16x16x32_bf16 v[76:79], v[228:231], v[208:211], v[32:35]
	v_mfma_f32_16x16x32_bf16 v[32:35], v[224:227], v[212:215], v[182:185]
	v_mfma_f32_16x16x32_bf16 v[64:67], v[36:39], v[208:211], v[64:67]
	v_mfma_f32_16x16x32_bf16 v[92:95], v[228:231], v[138:141], v[32:35]
	s_setprio 0
	s_barrier
	ds_read_b128 v[154:157], v136 offset:49152
	ds_read_b128 v[174:177], v136 offset:50176
	ds_read_b128 v[178:181], v135 offset:49152
	ds_read_b128 v[134:137], v135 offset:50176
	ds_read_b128 v[182:185], v131 offset:49152
	ds_read_b128 v[194:197], v131 offset:50176
	ds_read_b128 v[198:201], v130 offset:49152
	ds_read_b128 v[128:131], v130 offset:50176
	s_setprio 1
	s_barrier
	s_waitcnt lgkmcnt(0)
	s_waitcnt lgkmcnt(0)
	v_mfma_f32_16x16x32_bf16 v[36:39], v[154:157], v[8:11], v[56:59]
	v_mfma_f32_16x16x32_bf16 v[40:43], v[178:181], v[8:11], v[202:205]
	v_mfma_f32_16x16x32_bf16 v[32:35], v[154:157], v[0:3], v[60:63]
	v_mfma_f32_16x16x32_bf16 v[48:51], v[174:177], v[16:19], v[36:39]
	v_mfma_f32_16x16x32_bf16 v[36:39], v[178:181], v[0:3], v[52:55]
	v_mfma_f32_16x16x32_bf16 v[52:55], v[134:137], v[16:19], v[40:43]
	v_mfma_f32_16x16x32_bf16 v[40:43], v[182:185], v[0:3], v[44:47]
	v_mfma_f32_16x16x32_bf16 v[44:47], v[182:185], v[8:11], v[220:223]
	v_mfma_f32_16x16x32_bf16 v[0:3], v[198:201], v[0:3], v[150:153]
	v_mfma_f32_16x16x32_bf16 v[56:59], v[194:197], v[16:19], v[44:47]
	v_mfma_f32_16x16x32_bf16 v[44:47], v[128:131], v[4:7], v[0:3]
	v_mfma_f32_16x16x32_bf16 v[0:3], v[198:201], v[8:11], v[162:165]
	v_mfma_f32_16x16x32_bf16 v[32:35], v[174:177], v[4:7], v[32:35]
	v_mfma_f32_16x16x32_bf16 v[36:39], v[134:137], v[4:7], v[36:39]
	v_mfma_f32_16x16x32_bf16 v[40:43], v[194:197], v[4:7], v[40:43]
	v_mfma_f32_16x16x32_bf16 v[60:63], v[128:131], v[16:19], v[0:3]
	s_setprio 0
	s_setprio 1
	v_mfma_f32_16x16x32_bf16 v[4:7], v[154:157], v[212:215], v[24:27]
	v_mfma_f32_16x16x32_bf16 v[8:11], v[178:181], v[212:215], v[166:169]
	v_mfma_f32_16x16x32_bf16 v[16:19], v[174:177], v[138:141], v[4:7]
	v_mfma_f32_16x16x32_bf16 v[4:7], v[178:181], v[158:161], v[20:23]
	v_mfma_f32_16x16x32_bf16 v[20:23], v[134:137], v[138:141], v[8:11]
	v_mfma_f32_16x16x32_bf16 v[8:11], v[182:185], v[158:161], v[12:15]
	v_mfma_f32_16x16x32_bf16 v[12:15], v[182:185], v[212:215], v[170:173]
	v_mfma_f32_16x16x32_bf16 v[0:3], v[154:157], v[158:161], v[28:31]
	v_mfma_f32_16x16x32_bf16 v[24:27], v[194:197], v[138:141], v[12:15]
	v_mfma_f32_16x16x32_bf16 v[12:15], v[198:201], v[158:161], v[186:189]
	v_mfma_f32_16x16x32_bf16 v[28:31], v[198:201], v[212:215], v[190:193]
	v_mfma_f32_16x16x32_bf16 v[0:3], v[174:177], v[208:211], v[0:3]
	v_mfma_f32_16x16x32_bf16 v[4:7], v[134:137], v[208:211], v[4:7]
	v_mfma_f32_16x16x32_bf16 v[8:11], v[194:197], v[208:211], v[8:11]
	v_mfma_f32_16x16x32_bf16 v[12:15], v[128:131], v[208:211], v[12:15]
	v_mfma_f32_16x16x32_bf16 v[28:31], v[128:131], v[138:141], v[28:31]
	s_setprio 0
	s_cmpk_gt_u32 s5, 0xff
	s_barrier
	s_cbranch_scc1 .LBB0_418
	s_barrier

; #define WAIT_L(n) asm volatile("s_waitcnt lgkmcnt(" #n ")" ::: "memory")
; #define BAR __builtin_amdgcn_s_barrier()
; #define SCHED __builtin_amdgcn_sched_barrier(0)
; template <int EPI>
; __device__ __forceinline__ void gemm_tile(const Params& p, const bf16* __restrict__ A, const bf16* __restrict__ Bt, const int K,
;                                           const int nt, const int brow, const int bcol, int pm, int pn) {
;     ...
;     LDB(B0, 0, 0); SCHED; LDA(At, 0, 0); STAGE(SA(1, 1), A, brow + HALF, t + 1);
;     WAIT_L(8); BAR; WAIT_L(0); MMA(0, 0, At, B0); BAR; SCHED;
;     LDB(B1, 0, 1); STAGE(SB(0, 0), Bt, bcol, t + 2);
;     BAR; WAIT_L(0); MMA(0, 1, At, B1); BAR;
;     LDA(At, 0, 1); STAGE(SA(0, 0), A, brow, t + 2);
;     BAR; WAIT_L(0); MMA(1, 0, At, B0); BAR; SCHED;
.LBB0_1378:
	ds_read_b128 v[158:161], v153
	ds_read_b128 v[162:165], v153 offset:1024
	ds_read_b128 v[166:169], v153 offset:2048
	ds_read_b128 v[170:173], v153 offset:3072
	v_lshl_add_u64 v[154:155], s[52:53], 0, v[128:129]
	s_mov_b64 s[66:67], 0x14602080
	v_readfirstlane_b32 s57, v151
	v_lshl_add_u64 v[204:205], v[154:155], 0, s[66:67]
	s_mov_b32 m0, s57
	s_mov_b64 s[66:67], 0x14642080
	v_readfirstlane_b32 s57, v150
	ds_read_b128 v[174:177], v147
	ds_read_b128 v[178:181], v147 offset:1024
	ds_read_b128 v[182:185], v146
	ds_read_b128 v[186:189], v146 offset:1024
	ds_read_b128 v[190:193], v145
	ds_read_b128 v[196:199], v145 offset:1024
	ds_read_b128 v[200:203], v144
	ds_read_b128 v[208:211], v144 offset:1024
	global_load_lds_dwordx4 v[204:205], off
	v_lshl_add_u64 v[204:205], v[154:155], 0, s[66:67]
	s_mov_b32 m0, s57
	s_nop 0
	global_load_lds_dwordx4 v[204:205], off
	s_waitcnt lgkmcnt(8)
	s_setprio 1
	s_barrier
	s_waitcnt lgkmcnt(0)
	s_waitcnt lgkmcnt(0)
	v_mfma_f32_16x16x32_bf16 v[124:127], v[174:177], v[158:161], v[124:127]
	v_mfma_f32_16x16x32_bf16 v[120:123], v[174:177], v[166:169], v[120:123]
	v_mfma_f32_16x16x32_bf16 v[116:119], v[182:185], v[158:161], v[116:119]
	v_mfma_f32_16x16x32_bf16 v[112:115], v[182:185], v[166:169], v[112:115]
	v_mfma_f32_16x16x32_bf16 v[108:111], v[190:193], v[158:161], v[108:111]
	v_mfma_f32_16x16x32_bf16 v[104:107], v[190:193], v[166:169], v[104:107]
	v_mfma_f32_16x16x32_bf16 v[100:103], v[200:203], v[158:161], v[100:103]
	v_mfma_f32_16x16x32_bf16 v[96:99], v[200:203], v[166:169], v[96:99]
	v_mfma_f32_16x16x32_bf16 v[124:127], v[178:181], v[162:165], v[124:127]
	v_mfma_f32_16x16x32_bf16 v[120:123], v[178:181], v[170:173], v[120:123]
	v_mfma_f32_16x16x32_bf16 v[116:119], v[186:189], v[162:165], v[116:119]
	v_mfma_f32_16x16x32_bf16 v[112:115], v[186:189], v[170:173], v[112:115]
	v_mfma_f32_16x16x32_bf16 v[108:111], v[196:199], v[162:165], v[108:111]
	v_mfma_f32_16x16x32_bf16 v[104:107], v[196:199], v[170:173], v[104:107]
	v_mfma_f32_16x16x32_bf16 v[100:103], v[208:211], v[162:165], v[100:103]
	v_mfma_f32_16x16x32_bf16 v[96:99], v[208:211], v[170:173], v[96:99]
	s_setprio 0
	s_barrier
	v_lshl_add_u64 v[204:205], s[54:55], 0, v[128:129]
	s_mov_b64 s[66:67], 0x1800100
	v_readfirstlane_b32 s57, v130
	v_lshl_add_u64 v[228:229], v[204:205], 0, s[66:67]
	s_mov_b32 m0, s57
	s_mov_b64 s[66:67], 0x1840100
	v_readfirstlane_b32 s57, v131
	ds_read_b128 v[212:215], v149
	ds_read_b128 v[216:219], v149 offset:1024
	ds_read_b128 v[220:223], v149 offset:2048
	ds_read_b128 v[224:227], v149 offset:3072
	global_load_lds_dwordx4 v[228:229], off
	v_lshl_add_u64 v[228:229], v[204:205], 0, s[66:67]
	s_mov_b32 m0, s57
	s_nop 0
	global_load_lds_dwordx4 v[228:229], off
	s_setprio 1
	s_barrier
	s_waitcnt lgkmcnt(0)
	s_waitcnt lgkmcnt(0)
	v_mfma_f32_16x16x32_bf16 v[92:95], v[174:177], v[212:215], v[92:95]
	v_mfma_f32_16x16x32_bf16 v[88:91], v[174:177], v[220:223], v[88:91]
	v_mfma_f32_16x16x32_bf16 v[84:87], v[182:185], v[212:215], v[84:87]
	v_mfma_f32_16x16x32_bf16 v[80:83], v[182:185], v[220:223], v[80:83]
	v_mfma_f32_16x16x32_bf16 v[76:79], v[190:193], v[212:215], v[76:79]
	v_mfma_f32_16x16x32_bf16 v[72:75], v[190:193], v[220:223], v[72:75]
	v_mfma_f32_16x16x32_bf16 v[68:71], v[200:203], v[212:215], v[68:71]
	v_mfma_f32_16x16x32_bf16 v[64:67], v[200:203], v[220:223], v[64:67]
	v_mfma_f32_16x16x32_bf16 v[92:95], v[178:181], v[216:219], v[92:95]
	v_mfma_f32_16x16x32_bf16 v[88:91], v[178:181], v[224:227], v[88:91]
	v_mfma_f32_16x16x32_bf16 v[84:87], v[186:189], v[216:219], v[84:87]
	v_mfma_f32_16x16x32_bf16 v[80:83], v[186:189], v[224:227], v[80:83]
	v_mfma_f32_16x16x32_bf16 v[76:79], v[196:199], v[216:219], v[76:79]
	v_mfma_f32_16x16x32_bf16 v[72:75], v[196:199], v[224:227], v[72:75]
	v_mfma_f32_16x16x32_bf16 v[68:71], v[208:211], v[216:219], v[68:71]
	v_mfma_f32_16x16x32_bf16 v[64:67], v[208:211], v[224:227], v[64:67]
	s_setprio 0
	s_mov_b64 s[66:67], 0x14582100
	v_readfirstlane_b32 s57, v132
	v_lshl_add_u64 v[228:229], v[154:155], 0, s[66:67]
	s_mov_b32 m0, s57
	v_readfirstlane_b32 s57, v133
	s_barrier
	ds_read_b128 v[174:177], v147 offset:16384
	ds_read_b128 v[178:181], v147 offset:17408
	ds_read_b128 v[182:185], v146 offset:16384
	ds_read_b128 v[186:189], v146 offset:17408
	ds_read_b128 v[190:193], v145 offset:16384
	ds_read_b128 v[196:199], v145 offset:17408
	ds_read_b128 v[200:203], v144 offset:16384
	ds_read_b128 v[208:211], v144 offset:17408
	global_load_lds_dwordx4 v[228:229], off
	v_lshl_add_u64 v[228:229], v[154:155], 0, s[14:15]
	s_mov_b32 m0, s57
	s_nop 0
	global_load_lds_dwordx4 v[228:229], off
	s_setprio 1
	s_barrier
	s_waitcnt lgkmcnt(0)
	s_waitcnt lgkmcnt(0)
	v_mfma_f32_16x16x32_bf16 v[60:63], v[174:177], v[158:161], v[60:63]
	v_mfma_f32_16x16x32_bf16 v[56:59], v[174:177], v[166:169], v[56:59]
	v_mfma_f32_16x16x32_bf16 v[52:55], v[182:185], v[158:161], v[52:55]
	v_mfma_f32_16x16x32_bf16 v[48:51], v[182:185], v[166:169], v[48:51]
	v_mfma_f32_16x16x32_bf16 v[44:47], v[190:193], v[158:161], v[44:47]
	v_mfma_f32_16x16x32_bf16 v[40:43], v[190:193], v[166:169], v[40:43]
	v_mfma_f32_16x16x32_bf16 v[36:39], v[200:203], v[158:161], v[36:39]
	v_mfma_f32_16x16x32_bf16 v[32:35], v[200:203], v[166:169], v[32:35]
	v_mfma_f32_16x16x32_bf16 v[60:63], v[178:181], v[162:165], v[60:63]
	v_mfma_f32_16x16x32_bf16 v[56:59], v[178:181], v[170:173], v[56:59]
	v_mfma_f32_16x16x32_bf16 v[52:55], v[186:189], v[162:165], v[52:55]
	v_mfma_f32_16x16x32_bf16 v[48:51], v[186:189], v[170:173], v[48:51]
	v_mfma_f32_16x16x32_bf16 v[44:47], v[196:199], v[162:165], v[44:47]
	v_mfma_f32_16x16x32_bf16 v[40:43], v[196:199], v[170:173], v[40:43]
	v_mfma_f32_16x16x32_bf16 v[36:39], v[208:211], v[162:165], v[36:39]
	v_mfma_f32_16x16x32_bf16 v[32:35], v[208:211], v[170:173], v[32:35]
	s_setprio 0
	s_barrier
; #define WAIT_V(n) asm volatile("s_waitcnt vmcnt(" #n ")" ::: "memory")
; #define WAIT_L(n) asm volatile("s_waitcnt lgkmcnt(" #n ")" ::: "memory")
; #define BAR __builtin_amdgcn_s_barrier()
; #define SCHED __builtin_amdgcn_sched_barrier(0)
; template <int EPI>
; __device__ __forceinline__ void gemm_tile(const Params& p, const bf16* __restrict__ A, const bf16* __restrict__ Bt, const int K,
;                                           const int nt, const int brow, const int bcol, int pm, int pn) {
;     ...
;     STAGE(SB(0, 1), Bt, bcol + HALF, t + 2);
;     WAIT_V(6); BAR; MMA(1, 1, At, B1); BAR;
;     LDB(B0, 1, 0); SCHED; LDA(At, 1, 0); STAGE(SA(0, 1), A, brow + HALF, t + 2);
;     WAIT_L(8); BAR; WAIT_L(0); MMA(0, 0, At, B0); BAR; SCHED;
;     LDB(B1, 1, 1); STAGE(SB(1, 0), Bt, bcol, t + 3);
;     BAR; WAIT_L(0); MMA(0, 1, At, B1); BAR;
;     LDA(At, 1, 1); STAGE(SA(1, 0), A, brow, t + 3);
	v_readfirstlane_b32 s57, v134
	v_lshl_add_u64 v[158:159], v[204:205], 0, s[16:17]
	s_mov_b32 m0, s57
	v_readfirstlane_b32 s57, v135
	global_load_lds_dwordx4 v[158:159], off
	v_lshl_add_u64 v[158:159], v[204:205], 0, s[18:19]
	s_mov_b32 m0, s57
	s_nop 0
	global_load_lds_dwordx4 v[158:159], off
	s_waitcnt vmcnt(6)
	s_setprio 1
	s_barrier
	v_mfma_f32_16x16x32_bf16 v[28:31], v[174:177], v[212:215], v[28:31]
	v_mfma_f32_16x16x32_bf16 v[24:27], v[174:177], v[220:223], v[24:27]
	v_mfma_f32_16x16x32_bf16 v[20:23], v[182:185], v[212:215], v[20:23]
	v_mfma_f32_16x16x32_bf16 v[16:19], v[182:185], v[220:223], v[16:19]
	v_mfma_f32_16x16x32_bf16 v[12:15], v[190:193], v[212:215], v[12:15]
	v_mfma_f32_16x16x32_bf16 v[8:11], v[190:193], v[220:223], v[8:11]
	v_mfma_f32_16x16x32_bf16 v[4:7], v[200:203], v[212:215], v[4:7]
	v_mfma_f32_16x16x32_bf16 v[0:3], v[200:203], v[220:223], v[0:3]
	v_mfma_f32_16x16x32_bf16 v[28:31], v[178:181], v[216:219], v[28:31]
	v_mfma_f32_16x16x32_bf16 v[24:27], v[178:181], v[224:227], v[24:27]
	v_mfma_f32_16x16x32_bf16 v[20:23], v[186:189], v[216:219], v[20:23]
	v_mfma_f32_16x16x32_bf16 v[16:19], v[186:189], v[224:227], v[16:19]
	v_mfma_f32_16x16x32_bf16 v[12:15], v[196:199], v[216:219], v[12:15]
	v_mfma_f32_16x16x32_bf16 v[8:11], v[196:199], v[224:227], v[8:11]
	v_mfma_f32_16x16x32_bf16 v[4:7], v[208:211], v[216:219], v[4:7]
	v_mfma_f32_16x16x32_bf16 v[0:3], v[208:211], v[224:227], v[0:3]
	s_setprio 0
	s_barrier
	ds_read_b128 v[158:161], v138
	ds_read_b128 v[162:165], v138 offset:1024
	ds_read_b128 v[166:169], v138 offset:2048
	ds_read_b128 v[170:173], v138 offset:3072
	v_readfirstlane_b32 s57, v136
	v_lshl_add_u64 v[212:213], v[154:155], 0, s[20:21]
	s_mov_b32 m0, s57
	v_readfirstlane_b32 s57, v137
	ds_read_b128 v[174:177], v147 offset:32768
	ds_read_b128 v[178:181], v147 offset:33792
	ds_read_b128 v[182:185], v146 offset:32768
	ds_read_b128 v[186:189], v146 offset:33792
	ds_read_b128 v[190:193], v145 offset:32768
	ds_read_b128 v[196:199], v145 offset:33792
	ds_read_b128 v[200:203], v144 offset:32768
	ds_read_b128 v[208:211], v144 offset:33792
	global_load_lds_dwordx4 v[212:213], off
	v_lshl_add_u64 v[212:213], v[154:155], 0, s[22:23]
	s_mov_b32 m0, s57
	s_nop 0
	global_load_lds_dwordx4 v[212:213], off
	s_waitcnt lgkmcnt(8)
	s_setprio 1
	s_barrier
	s_waitcnt lgkmcnt(0)
	s_waitcnt lgkmcnt(0)
	v_mfma_f32_16x16x32_bf16 v[124:127], v[174:177], v[158:161], v[124:127]
	v_mfma_f32_16x16x32_bf16 v[120:123], v[174:177], v[166:169], v[120:123]
	v_mfma_f32_16x16x32_bf16 v[116:119], v[182:185], v[158:161], v[116:119]
	v_mfma_f32_16x16x32_bf16 v[112:115], v[182:185], v[166:169], v[112:115]
	v_mfma_f32_16x16x32_bf16 v[108:111], v[190:193], v[158:161], v[108:111]
	v_mfma_f32_16x16x32_bf16 v[104:107], v[190:193], v[166:169], v[104:107]
	v_mfma_f32_16x16x32_bf16 v[100:103], v[200:203], v[158:161], v[100:103]
	v_mfma_f32_16x16x32_bf16 v[96:99], v[200:203], v[166:169], v[96:99]
	v_mfma_f32_16x16x32_bf16 v[124:127], v[178:181], v[162:165], v[124:127]
	v_mfma_f32_16x16x32_bf16 v[120:123], v[178:181], v[170:173], v[120:123]
	v_mfma_f32_16x16x32_bf16 v[116:119], v[186:189], v[162:165], v[116:119]
	v_mfma_f32_16x16x32_bf16 v[112:115], v[186:189], v[170:173], v[112:115]
	v_mfma_f32_16x16x32_bf16 v[108:111], v[196:199], v[162:165], v[108:111]
	v_mfma_f32_16x16x32_bf16 v[104:107], v[196:199], v[170:173], v[104:107]
	v_mfma_f32_16x16x32_bf16 v[100:103], v[208:211], v[162:165], v[100:103]
	v_mfma_f32_16x16x32_bf16 v[96:99], v[208:211], v[170:173], v[96:99]
	s_setprio 0
	s_barrier
	v_readfirstlane_b32 s57, v139
	v_lshl_add_u64 v[228:229], v[204:205], 0, s[24:25]
	s_mov_b32 m0, s57
	v_readfirstlane_b32 s57, v140
	ds_read_b128 v[212:215], v152
	ds_read_b128 v[216:219], v152 offset:1024
	ds_read_b128 v[220:223], v152 offset:2048
	ds_read_b128 v[224:227], v152 offset:3072
	global_load_lds_dwordx4 v[228:229], off
	v_lshl_add_u64 v[228:229], v[204:205], 0, s[26:27]
	s_mov_b32 m0, s57
	s_nop 0
	global_load_lds_dwordx4 v[228:229], off
	s_setprio 1
	s_barrier
	s_waitcnt lgkmcnt(0)
	s_waitcnt lgkmcnt(0)
	v_mfma_f32_16x16x32_bf16 v[92:95], v[174:177], v[212:215], v[92:95]
	v_mfma_f32_16x16x32_bf16 v[88:91], v[174:177], v[220:223], v[88:91]
	v_mfma_f32_16x16x32_bf16 v[84:87], v[182:185], v[212:215], v[84:87]
	v_mfma_f32_16x16x32_bf16 v[80:83], v[182:185], v[220:223], v[80:83]
	v_mfma_f32_16x16x32_bf16 v[76:79], v[190:193], v[212:215], v[76:79]
	v_mfma_f32_16x16x32_bf16 v[72:75], v[190:193], v[220:223], v[72:75]
	v_mfma_f32_16x16x32_bf16 v[68:71], v[200:203], v[212:215], v[68:71]
	v_mfma_f32_16x16x32_bf16 v[64:67], v[200:203], v[220:223], v[64:67]
	v_mfma_f32_16x16x32_bf16 v[92:95], v[178:181], v[216:219], v[92:95]
	v_mfma_f32_16x16x32_bf16 v[88:91], v[178:181], v[224:227], v[88:91]
	v_mfma_f32_16x16x32_bf16 v[84:87], v[186:189], v[216:219], v[84:87]
	v_mfma_f32_16x16x32_bf16 v[80:83], v[186:189], v[224:227], v[80:83]
	v_mfma_f32_16x16x32_bf16 v[76:79], v[196:199], v[216:219], v[76:79]
	v_mfma_f32_16x16x32_bf16 v[72:75], v[196:199], v[224:227], v[72:75]
	v_mfma_f32_16x16x32_bf16 v[68:71], v[208:211], v[216:219], v[68:71]
	v_mfma_f32_16x16x32_bf16 v[64:67], v[208:211], v[224:227], v[64:67]
	s_setprio 0
	v_readfirstlane_b32 s57, v141
	v_lshl_add_u64 v[228:229], v[154:155], 0, s[28:29]
	s_mov_b32 m0, s57
	v_readfirstlane_b32 s57, v142
	s_barrier
	ds_read_b128 v[174:177], v147 offset:49152
	ds_read_b128 v[178:181], v147 offset:50176
	ds_read_b128 v[182:185], v146 offset:49152
	ds_read_b128 v[186:189], v146 offset:50176
	ds_read_b128 v[190:193], v145 offset:49152
	ds_read_b128 v[196:199], v145 offset:50176
	ds_read_b128 v[200:203], v144 offset:49152
	ds_read_b128 v[208:211], v144 offset:50176
	global_load_lds_dwordx4 v[228:229], off
	v_lshl_add_u64 v[154:155], v[154:155], 0, s[30:31]
	s_mov_b32 m0, s57
	s_nop 0
	global_load_lds_dwordx4 v[154:155], off
	s_setprio 1
	s_barrier
; #define WAIT_V(n) asm volatile("s_waitcnt vmcnt(" #n ")" ::: "memory")
; #define WAIT_L(n) asm volatile("s_waitcnt lgkmcnt(" #n ")" ::: "memory")
; #define BAR __builtin_amdgcn_s_barrier()
; #define SCHED __builtin_amdgcn_sched_barrier(0)
; template <int EPI>
; __device__ __forceinline__ void gemm_tile(const Params& p, const bf16* __restrict__ A, const bf16* __restrict__ Bt, const int K,
;                                           const int nt, const int brow, const int bcol, int pm, int pn) {
;     ...
;     BAR; WAIT_L(0); MMA(1, 0, At, B0); BAR; SCHED;
;     STAGE(SB(1, 1), Bt, bcol + HALF, t + 3);
;     WAIT_V(6); BAR; MMA(1, 1, At, B1); BAR;
;   }
;   { LDB(B0, 0, 0); LDA(At, 0, 0); STAGE(SA(1, 1), A, brow + HALF, nt - 1);
;     BAR; WAIT_L(0); MMA(0, 0, At, B0); BAR;
;     LDB(B1, 0, 1); BAR; WAIT_L(0); MMA(0, 1, At, B1); BAR;
	s_waitcnt lgkmcnt(0)
	s_waitcnt lgkmcnt(0)
	v_mfma_f32_16x16x32_bf16 v[60:63], v[174:177], v[158:161], v[60:63]
	v_mfma_f32_16x16x32_bf16 v[56:59], v[174:177], v[166:169], v[56:59]
	v_mfma_f32_16x16x32_bf16 v[52:55], v[182:185], v[158:161], v[52:55]
	v_mfma_f32_16x16x32_bf16 v[48:51], v[182:185], v[166:169], v[48:51]
	v_mfma_f32_16x16x32_bf16 v[44:47], v[190:193], v[158:161], v[44:47]
	v_mfma_f32_16x16x32_bf16 v[40:43], v[190:193], v[166:169], v[40:43]
	v_mfma_f32_16x16x32_bf16 v[36:39], v[200:203], v[158:161], v[36:39]
	v_mfma_f32_16x16x32_bf16 v[32:35], v[200:203], v[166:169], v[32:35]
	v_mfma_f32_16x16x32_bf16 v[60:63], v[178:181], v[162:165], v[60:63]
	v_mfma_f32_16x16x32_bf16 v[56:59], v[178:181], v[170:173], v[56:59]
	v_mfma_f32_16x16x32_bf16 v[52:55], v[186:189], v[162:165], v[52:55]
	v_mfma_f32_16x16x32_bf16 v[48:51], v[186:189], v[170:173], v[48:51]
	v_mfma_f32_16x16x32_bf16 v[44:47], v[196:199], v[162:165], v[44:47]
	v_mfma_f32_16x16x32_bf16 v[40:43], v[196:199], v[170:173], v[40:43]
	v_mfma_f32_16x16x32_bf16 v[36:39], v[208:211], v[162:165], v[36:39]
	v_mfma_f32_16x16x32_bf16 v[32:35], v[208:211], v[170:173], v[32:35]
	s_setprio 0
	s_barrier
	v_readfirstlane_b32 s57, v143
	v_lshl_add_u64 v[154:155], v[204:205], 0, s[34:35]
	s_mov_b32 m0, s57
	v_readfirstlane_b32 s57, v148
	global_load_lds_dwordx4 v[154:155], off
	v_lshl_add_u64 v[154:155], v[204:205], 0, s[36:37]
	s_mov_b32 m0, s57
	s_nop 0
	global_load_lds_dwordx4 v[154:155], off
	s_waitcnt vmcnt(6)
	s_setprio 1
	s_barrier
	v_mfma_f32_16x16x32_bf16 v[28:31], v[174:177], v[212:215], v[28:31]
	v_mfma_f32_16x16x32_bf16 v[24:27], v[174:177], v[220:223], v[24:27]
	v_mfma_f32_16x16x32_bf16 v[20:23], v[182:185], v[212:215], v[20:23]
	v_mfma_f32_16x16x32_bf16 v[16:19], v[182:185], v[220:223], v[16:19]
	v_mfma_f32_16x16x32_bf16 v[12:15], v[190:193], v[212:215], v[12:15]
	v_mfma_f32_16x16x32_bf16 v[8:11], v[190:193], v[220:223], v[8:11]
	v_mfma_f32_16x16x32_bf16 v[4:7], v[200:203], v[212:215], v[4:7]
	v_mfma_f32_16x16x32_bf16 v[0:3], v[200:203], v[220:223], v[0:3]
	v_mfma_f32_16x16x32_bf16 v[28:31], v[178:181], v[216:219], v[28:31]
	v_mfma_f32_16x16x32_bf16 v[24:27], v[178:181], v[224:227], v[24:27]
	v_mfma_f32_16x16x32_bf16 v[20:23], v[186:189], v[216:219], v[20:23]
	v_mfma_f32_16x16x32_bf16 v[16:19], v[186:189], v[224:227], v[16:19]
	v_mfma_f32_16x16x32_bf16 v[12:15], v[196:199], v[216:219], v[12:15]
	v_mfma_f32_16x16x32_bf16 v[8:11], v[196:199], v[224:227], v[8:11]
	v_mfma_f32_16x16x32_bf16 v[4:7], v[208:211], v[216:219], v[4:7]
	v_mfma_f32_16x16x32_bf16 v[0:3], v[208:211], v[224:227], v[0:3]
	s_setprio 0
	s_add_i32 s56, s56, 2
	s_add_u32 s52, s52, 0x100
	s_addc_u32 s53, s53, 0
	s_add_u32 s54, s54, 0x100
	s_addc_u32 s55, s55, 0
	s_cmp_lt_u32 s56, 28
	s_barrier
	s_cbranch_scc1 .LBB0_1378
	s_add_u32 s6, s64, s6
	s_addc_u32 s7, s65, s7
	v_lshl_add_u64 v[136:137], s[6:7], 0, v[156:157]
	v_readfirstlane_b32 s6, v151
	s_mov_b32 m0, s6
	s_add_u32 s6, s64, s42
	v_lshl_add_u64 v[136:137], v[136:137], 0, s[38:39]
	s_addc_u32 s7, s65, s43
	ds_read_b128 v[128:131], v153
	ds_read_b128 v[132:135], v153 offset:1024
	ds_read_b128 v[140:143], v153 offset:2048
	ds_read_b128 v[158:161], v153 offset:3072
	ds_read_b128 v[162:165], v147
	ds_read_b128 v[166:169], v147 offset:1024
	ds_read_b128 v[170:173], v146
	ds_read_b128 v[174:177], v146 offset:1024
	ds_read_b128 v[178:181], v145
	ds_read_b128 v[182:185], v145 offset:1024
	ds_read_b128 v[186:189], v144
	ds_read_b128 v[190:193], v144 offset:1024
	global_load_lds_dwordx4 v[136:137], off
	v_lshl_add_u64 v[136:137], s[6:7], 0, v[156:157]
	v_readfirstlane_b32 s6, v150
	v_lshl_add_u64 v[136:137], v[136:137], 0, s[38:39]
	s_mov_b32 m0, s6
	s_nop 0
	global_load_lds_dwordx4 v[136:137], off
	s_setprio 1
	s_barrier
	s_waitcnt lgkmcnt(0)
	s_waitcnt lgkmcnt(0)
	v_mfma_f32_16x16x32_bf16 v[124:127], v[162:165], v[128:131], v[124:127]
	v_mfma_f32_16x16x32_bf16 v[120:123], v[162:165], v[140:143], v[120:123]
	v_mfma_f32_16x16x32_bf16 v[116:119], v[170:173], v[128:131], v[116:119]
	v_mfma_f32_16x16x32_bf16 v[124:127], v[166:169], v[132:135], v[124:127]
	v_mfma_f32_16x16x32_bf16 v[120:123], v[166:169], v[158:161], v[120:123]
	v_mfma_f32_16x16x32_bf16 v[116:119], v[174:177], v[132:135], v[116:119]
	v_mfma_f32_16x16x32_bf16 v[112:115], v[170:173], v[140:143], v[112:115]
	v_mfma_f32_16x16x32_bf16 v[108:111], v[178:181], v[128:131], v[108:111]
	v_mfma_f32_16x16x32_bf16 v[104:107], v[178:181], v[140:143], v[104:107]
	v_mfma_f32_16x16x32_bf16 v[100:103], v[186:189], v[128:131], v[100:103]
	v_mfma_f32_16x16x32_bf16 v[96:99], v[186:189], v[140:143], v[96:99]
	v_mfma_f32_16x16x32_bf16 v[112:115], v[174:177], v[158:161], v[112:115]
	v_mfma_f32_16x16x32_bf16 v[108:111], v[182:185], v[132:135], v[108:111]
	v_mfma_f32_16x16x32_bf16 v[104:107], v[182:185], v[158:161], v[104:107]
	v_mfma_f32_16x16x32_bf16 v[100:103], v[190:193], v[132:135], v[100:103]
	v_mfma_f32_16x16x32_bf16 v[96:99], v[190:193], v[158:161], v[96:99]
	s_setprio 0
	s_barrier
	ds_read_b128 v[196:199], v149
	ds_read_b128 v[200:203], v149 offset:1024
	ds_read_b128 v[208:211], v149 offset:2048
	ds_read_b128 v[148:151], v149 offset:3072
	s_setprio 1
	s_barrier
; #define WAIT_V(n) asm volatile("s_waitcnt vmcnt(" #n ")" ::: "memory")
; #define WAIT_L(n) asm volatile("s_waitcnt lgkmcnt(" #n ")" ::: "memory")
; #define BAR __builtin_amdgcn_s_barrier()
; template <int EPI>
; __device__ __forceinline__ void gemm_tile(const Params& p, const bf16* __restrict__ A, const bf16* __restrict__ Bt, const int K,
;                                           const int nt, const int brow, const int bcol, int pm, int pn) {
;     ...
;     LDB(B1, 0, 1); BAR; WAIT_L(0); MMA(0, 1, At, B1); BAR;
;     LDA(At, 0, 1); WAIT_V(4); BAR; WAIT_L(0); MMA(1, 0, At, B0); MMA(1, 1, At, B1); BAR; }
;   { LDB(B0, 1, 0); LDA(At, 1, 0); WAIT_V(2); BAR; WAIT_L(0); MMA(0, 0, At, B0); BAR;
;     LDB(B1, 1, 1); WAIT_V(0); BAR; WAIT_L(0); MMA(0, 1, At, B1); BAR;
	s_waitcnt lgkmcnt(0)
	s_waitcnt lgkmcnt(0)
	v_mfma_f32_16x16x32_bf16 v[92:95], v[162:165], v[196:199], v[92:95]
	v_mfma_f32_16x16x32_bf16 v[88:91], v[162:165], v[208:211], v[88:91]
	v_mfma_f32_16x16x32_bf16 v[84:87], v[170:173], v[196:199], v[84:87]
	v_mfma_f32_16x16x32_bf16 v[76:79], v[178:181], v[196:199], v[76:79]
	v_mfma_f32_16x16x32_bf16 v[92:95], v[166:169], v[200:203], v[92:95]
	v_mfma_f32_16x16x32_bf16 v[88:91], v[166:169], v[148:151], v[88:91]
	v_mfma_f32_16x16x32_bf16 v[84:87], v[174:177], v[200:203], v[84:87]
	v_mfma_f32_16x16x32_bf16 v[80:83], v[170:173], v[208:211], v[80:83]
	v_mfma_f32_16x16x32_bf16 v[76:79], v[182:185], v[200:203], v[76:79]
	v_mfma_f32_16x16x32_bf16 v[72:75], v[178:181], v[208:211], v[72:75]
	v_mfma_f32_16x16x32_bf16 v[68:71], v[186:189], v[196:199], v[68:71]
	v_mfma_f32_16x16x32_bf16 v[64:67], v[186:189], v[208:211], v[64:67]
	v_mfma_f32_16x16x32_bf16 v[162:165], v[174:177], v[148:151], v[80:83]
	v_mfma_f32_16x16x32_bf16 v[166:169], v[182:185], v[148:151], v[72:75]
	v_mfma_f32_16x16x32_bf16 v[170:173], v[190:193], v[200:203], v[68:71]
	v_mfma_f32_16x16x32_bf16 v[174:177], v[190:193], v[148:151], v[64:67]
	s_setprio 0
	s_barrier
	s_nop 1
	ds_read_b128 v[64:67], v147 offset:16384
	ds_read_b128 v[68:71], v147 offset:17408
	ds_read_b128 v[72:75], v146 offset:16384
	ds_read_b128 v[80:83], v146 offset:17408
	ds_read_b128 v[178:181], v145 offset:16384
	ds_read_b128 v[182:185], v145 offset:17408
	ds_read_b128 v[186:189], v144 offset:16384
	ds_read_b128 v[190:193], v144 offset:17408
	s_waitcnt vmcnt(4)
	s_setprio 1
	s_barrier
	s_waitcnt lgkmcnt(0)
	s_waitcnt lgkmcnt(0)
	v_mfma_f32_16x16x32_bf16 v[60:63], v[64:67], v[128:131], v[60:63]
	v_mfma_f32_16x16x32_bf16 v[56:59], v[64:67], v[140:143], v[56:59]
	v_mfma_f32_16x16x32_bf16 v[52:55], v[72:75], v[128:131], v[52:55]
	v_mfma_f32_16x16x32_bf16 v[44:47], v[178:181], v[128:131], v[44:47]
	v_mfma_f32_16x16x32_bf16 v[60:63], v[68:71], v[132:135], v[60:63]
	v_mfma_f32_16x16x32_bf16 v[56:59], v[68:71], v[158:161], v[56:59]
	v_mfma_f32_16x16x32_bf16 v[52:55], v[80:83], v[132:135], v[52:55]
	v_mfma_f32_16x16x32_bf16 v[48:51], v[72:75], v[140:143], v[48:51]
	v_mfma_f32_16x16x32_bf16 v[44:47], v[182:185], v[132:135], v[44:47]
	v_mfma_f32_16x16x32_bf16 v[40:43], v[178:181], v[140:143], v[40:43]
	v_mfma_f32_16x16x32_bf16 v[36:39], v[186:189], v[128:131], v[36:39]
	v_mfma_f32_16x16x32_bf16 v[32:35], v[186:189], v[140:143], v[32:35]
	v_mfma_f32_16x16x32_bf16 v[212:215], v[80:83], v[158:161], v[48:51]
	v_mfma_f32_16x16x32_bf16 v[216:219], v[182:185], v[158:161], v[40:43]
	v_mfma_f32_16x16x32_bf16 v[220:223], v[190:193], v[132:135], v[36:39]
	v_mfma_f32_16x16x32_bf16 v[158:161], v[190:193], v[158:161], v[32:35]
	s_setprio 0
	s_setprio 1
	v_mfma_f32_16x16x32_bf16 v[28:31], v[64:67], v[196:199], v[28:31]
	v_mfma_f32_16x16x32_bf16 v[24:27], v[64:67], v[208:211], v[24:27]
	v_mfma_f32_16x16x32_bf16 v[20:23], v[72:75], v[196:199], v[20:23]
	v_mfma_f32_16x16x32_bf16 v[12:15], v[178:181], v[196:199], v[12:15]
	v_mfma_f32_16x16x32_bf16 v[28:31], v[68:71], v[200:203], v[28:31]
	v_mfma_f32_16x16x32_bf16 v[24:27], v[68:71], v[148:151], v[24:27]
	v_mfma_f32_16x16x32_bf16 v[20:23], v[80:83], v[200:203], v[20:23]
	v_mfma_f32_16x16x32_bf16 v[16:19], v[72:75], v[208:211], v[16:19]
	v_mfma_f32_16x16x32_bf16 v[12:15], v[182:185], v[200:203], v[12:15]
	v_mfma_f32_16x16x32_bf16 v[8:11], v[178:181], v[208:211], v[8:11]
	v_mfma_f32_16x16x32_bf16 v[4:7], v[186:189], v[196:199], v[4:7]
	v_mfma_f32_16x16x32_bf16 v[0:3], v[186:189], v[208:211], v[0:3]
	v_mfma_f32_16x16x32_bf16 v[224:227], v[80:83], v[148:151], v[16:19]
	v_mfma_f32_16x16x32_bf16 v[178:181], v[182:185], v[148:151], v[8:11]
	v_mfma_f32_16x16x32_bf16 v[182:185], v[190:193], v[200:203], v[4:7]
	v_mfma_f32_16x16x32_bf16 v[186:189], v[190:193], v[148:151], v[0:3]
	s_setprio 0
	s_barrier
	s_nop 1
	ds_read_b128 v[0:3], v138
	ds_read_b128 v[4:7], v138 offset:1024
	ds_read_b128 v[8:11], v138 offset:2048
	ds_read_b128 v[16:19], v138 offset:3072
	ds_read_b128 v[32:35], v147 offset:32768
	ds_read_b128 v[36:39], v147 offset:33792
	ds_read_b128 v[40:43], v146 offset:32768
	ds_read_b128 v[48:51], v146 offset:33792
	ds_read_b128 v[190:193], v145 offset:32768
	ds_read_b128 v[196:199], v145 offset:33792
	ds_read_b128 v[200:203], v144 offset:32768
	ds_read_b128 v[208:211], v144 offset:33792
	s_waitcnt vmcnt(2)
	s_setprio 1
	s_barrier
; #define WAIT_V(n) asm volatile("s_waitcnt vmcnt(" #n ")" ::: "memory")
; #define WAIT_L(n) asm volatile("s_waitcnt lgkmcnt(" #n ")" ::: "memory")
; #define BAR __builtin_amdgcn_s_barrier()
; template <int EPI>
; __device__ __forceinline__ void gemm_tile(const Params& p, const bf16* __restrict__ A, const bf16* __restrict__ Bt, const int K,
;                                           const int nt, const int brow, const int bcol, int pm, int pn) {
;     ...
;     LDB(B1, 1, 1); WAIT_V(0); BAR; WAIT_L(0); MMA(0, 1, At, B1); BAR;
;     LDA(At, 1, 1); BAR; WAIT_L(0); MMA(1, 0, At, B0); MMA(1, 1, At, B1); BAR; }
;   if (wr == 0) BAR;
	s_waitcnt lgkmcnt(0)
	s_waitcnt lgkmcnt(0)
	v_mfma_f32_16x16x32_bf16 v[64:67], v[32:35], v[0:3], v[124:127]
	v_mfma_f32_16x16x32_bf16 v[136:139], v[36:39], v[4:7], v[64:67]
	v_mfma_f32_16x16x32_bf16 v[64:67], v[32:35], v[8:11], v[120:123]
	v_mfma_f32_16x16x32_bf16 v[148:151], v[36:39], v[16:19], v[64:67]
	v_mfma_f32_16x16x32_bf16 v[64:67], v[40:43], v[0:3], v[116:119]
	v_mfma_f32_16x16x32_bf16 v[132:135], v[48:51], v[4:7], v[64:67]
	v_mfma_f32_16x16x32_bf16 v[64:67], v[40:43], v[8:11], v[112:115]
	v_mfma_f32_16x16x32_bf16 v[140:143], v[48:51], v[16:19], v[64:67]
	v_mfma_f32_16x16x32_bf16 v[64:67], v[190:193], v[0:3], v[108:111]
	v_mfma_f32_16x16x32_bf16 v[124:127], v[196:199], v[4:7], v[64:67]
	v_mfma_f32_16x16x32_bf16 v[64:67], v[190:193], v[8:11], v[104:107]
	v_mfma_f32_16x16x32_bf16 v[128:131], v[196:199], v[16:19], v[64:67]
	v_mfma_f32_16x16x32_bf16 v[64:67], v[200:203], v[0:3], v[100:103]
	v_mfma_f32_16x16x32_bf16 v[116:119], v[208:211], v[4:7], v[64:67]
	v_mfma_f32_16x16x32_bf16 v[64:67], v[200:203], v[8:11], v[96:99]
	v_mfma_f32_16x16x32_bf16 v[120:123], v[208:211], v[16:19], v[64:67]
	s_setprio 0
	s_barrier
	ds_read_b128 v[96:99], v152
	ds_read_b128 v[100:103], v152 offset:1024
	ds_read_b128 v[104:107], v152 offset:2048
	ds_read_b128 v[108:111], v152 offset:3072
	s_waitcnt vmcnt(0)
	s_setprio 1
	s_barrier
	s_waitcnt lgkmcnt(0)
	s_waitcnt lgkmcnt(0)
	v_mfma_f32_16x16x32_bf16 v[64:67], v[32:35], v[96:99], v[92:95]
	v_mfma_f32_16x16x32_bf16 v[32:35], v[32:35], v[104:107], v[88:91]
	v_mfma_f32_16x16x32_bf16 v[80:83], v[36:39], v[108:111], v[32:35]
	v_mfma_f32_16x16x32_bf16 v[32:35], v[40:43], v[96:99], v[84:87]
	v_mfma_f32_16x16x32_bf16 v[68:71], v[48:51], v[100:103], v[32:35]
	v_mfma_f32_16x16x32_bf16 v[32:35], v[40:43], v[104:107], v[162:165]
	v_mfma_f32_16x16x32_bf16 v[84:87], v[48:51], v[108:111], v[32:35]
	v_mfma_f32_16x16x32_bf16 v[32:35], v[190:193], v[96:99], v[76:79]
	v_mfma_f32_16x16x32_bf16 v[72:75], v[196:199], v[100:103], v[32:35]
	v_mfma_f32_16x16x32_bf16 v[32:35], v[190:193], v[104:107], v[166:169]
	v_mfma_f32_16x16x32_bf16 v[88:91], v[196:199], v[108:111], v[32:35]
	v_mfma_f32_16x16x32_bf16 v[32:35], v[200:203], v[96:99], v[170:173]
	v_mfma_f32_16x16x32_bf16 v[76:79], v[208:211], v[100:103], v[32:35]
	v_mfma_f32_16x16x32_bf16 v[32:35], v[200:203], v[104:107], v[174:177]
	v_mfma_f32_16x16x32_bf16 v[64:67], v[36:39], v[100:103], v[64:67]
	v_mfma_f32_16x16x32_bf16 v[92:95], v[208:211], v[108:111], v[32:35]
	s_setprio 0
	s_barrier
	ds_read_b128 v[112:115], v147 offset:49152
	ds_read_b128 v[152:155], v147 offset:50176
	ds_read_b128 v[162:165], v146 offset:49152
	ds_read_b128 v[166:169], v146 offset:50176
	ds_read_b128 v[170:173], v145 offset:49152
	ds_read_b128 v[174:177], v145 offset:50176
	ds_read_b128 v[190:193], v144 offset:49152
	ds_read_b128 v[144:147], v144 offset:50176
	s_setprio 1
	s_barrier
	s_waitcnt lgkmcnt(0)
	s_waitcnt lgkmcnt(0)
	v_mfma_f32_16x16x32_bf16 v[36:39], v[112:115], v[8:11], v[56:59]
	v_mfma_f32_16x16x32_bf16 v[40:43], v[162:165], v[8:11], v[212:215]
	v_mfma_f32_16x16x32_bf16 v[32:35], v[112:115], v[0:3], v[60:63]
	v_mfma_f32_16x16x32_bf16 v[48:51], v[152:155], v[16:19], v[36:39]
	v_mfma_f32_16x16x32_bf16 v[36:39], v[162:165], v[0:3], v[52:55]
	v_mfma_f32_16x16x32_bf16 v[52:55], v[166:169], v[16:19], v[40:43]
	v_mfma_f32_16x16x32_bf16 v[40:43], v[170:173], v[0:3], v[44:47]
	v_mfma_f32_16x16x32_bf16 v[44:47], v[170:173], v[8:11], v[216:219]
	v_mfma_f32_16x16x32_bf16 v[0:3], v[190:193], v[0:3], v[220:223]
	v_mfma_f32_16x16x32_bf16 v[56:59], v[174:177], v[16:19], v[44:47]
	v_mfma_f32_16x16x32_bf16 v[44:47], v[144:147], v[4:7], v[0:3]
	v_mfma_f32_16x16x32_bf16 v[0:3], v[190:193], v[8:11], v[158:161]
	v_mfma_f32_16x16x32_bf16 v[32:35], v[152:155], v[4:7], v[32:35]
	v_mfma_f32_16x16x32_bf16 v[36:39], v[166:169], v[4:7], v[36:39]
	v_mfma_f32_16x16x32_bf16 v[40:43], v[174:177], v[4:7], v[40:43]
	v_mfma_f32_16x16x32_bf16 v[60:63], v[144:147], v[16:19], v[0:3]
	s_setprio 0
	s_setprio 1
	v_mfma_f32_16x16x32_bf16 v[4:7], v[112:115], v[104:107], v[24:27]
	v_mfma_f32_16x16x32_bf16 v[8:11], v[162:165], v[104:107], v[224:227]
	v_mfma_f32_16x16x32_bf16 v[16:19], v[152:155], v[108:111], v[4:7]
	v_mfma_f32_16x16x32_bf16 v[4:7], v[162:165], v[96:99], v[20:23]
	v_mfma_f32_16x16x32_bf16 v[20:23], v[166:169], v[108:111], v[8:11]
	v_mfma_f32_16x16x32_bf16 v[8:11], v[170:173], v[96:99], v[12:15]
	v_mfma_f32_16x16x32_bf16 v[12:15], v[170:173], v[104:107], v[178:181]
	v_mfma_f32_16x16x32_bf16 v[0:3], v[112:115], v[96:99], v[28:31]
	v_mfma_f32_16x16x32_bf16 v[24:27], v[174:177], v[108:111], v[12:15]
	v_mfma_f32_16x16x32_bf16 v[12:15], v[190:193], v[96:99], v[182:185]
	v_mfma_f32_16x16x32_bf16 v[28:31], v[190:193], v[104:107], v[186:189]
	v_mfma_f32_16x16x32_bf16 v[0:3], v[152:155], v[100:103], v[0:3]
	v_mfma_f32_16x16x32_bf16 v[4:7], v[166:169], v[100:103], v[4:7]
	v_mfma_f32_16x16x32_bf16 v[8:11], v[174:177], v[100:103], v[8:11]
	v_mfma_f32_16x16x32_bf16 v[12:15], v[144:147], v[100:103], v[12:15]
	v_mfma_f32_16x16x32_bf16 v[28:31], v[144:147], v[108:111], v[28:31]
	s_setprio 0
	s_cmpk_gt_u32 s89, 0xff
	s_barrier
	s_cbranch_scc1 .LBB0_1381
	s_barrier

; template <int EPI>
; __device__ __forceinline__ void gemm_tile(const Params& p, const bf16* __restrict__ A, const bf16* __restrict__ Bt, const int K,
;                                           const int nt, const int brow, const int bcol, int pm, int pn) {
;     ...
;   __syncthreads();
; template <int EPI>
; __device__ __forceinline__ void gemm_phase(const Params& p, const bf16* A, const bf16* Bt, int K, int nM, int nN) {
;     ...
;   for (int t = blockIdx.x; t < ntile; t += gridDim.x) {
;     int pm, pn;
;     tile_map(t, nM, nN, pm, pn);
;     int brow;
;     if constexpr (EPI == EPI_GU) brow = (pm == 65) ? SEQ : 254 * pm - 2;
;     else brow = pm * BM;
;     gemm_tile<EPI>(p, A, Bt, K, K / BK, brow, pn * BM, pm, pn);
;   }
.LBB0_1552:
	s_or_b64 exec, exec, s[4:5]
	s_waitcnt vmcnt(0)
	s_barrier
	s_load_dword s4, s[12:13], 0x0
	s_waitcnt lgkmcnt(0)
	s_add_i32 s91, s4, s91
	s_cmpk_lt_i32 s91, 0xb58
	s_cbranch_scc0 .LBB0_1649

; #define WAIT_V(n) asm volatile("s_waitcnt vmcnt(" #n ")" ::: "memory")
; #define BAR __builtin_amdgcn_s_barrier()
; template <int EPI>
; __device__ __forceinline__ void gemm_tile(const Params& p, const bf16* __restrict__ A, const bf16* __restrict__ Bt, const int K,
;                                           const int nt, const int brow, const int bcol, int pm, int pn) {
;     ...
;   { int _r, _c; stage_rc(tid * 16, _r, _c); toff = (unsigned)(_r * K + _c) * 2u; }
;   f32x4 acc[2][2][4][2] = {};
;   float pre0 = 0.f, pre1 = 0.f, pre2 = 0.f;
;   if constexpr (EPI == EPI_GU) {
;     const int base = (pm == 65) ? SEQ : 254 * pm - 2;
;     if (tid < 256) pre0 = P_SSQ(p)[max(base + tid, 0)];
;     else if (tid < 384) { const int c = pn * 128 + tid - 256; pre0 = p.w_ffn_conv[c]; pre1 = p.w_ffn_conv[DFF + c]; pre2 = p.w_ffn_conv[2 * DFF + c]; }
;   }
;   bf16x8 At[4][2], B0[2][2], B1[2][2];
;   STAGE(SB(0, 0), Bt, bcol, 0); STAGE(SA(0, 0), A, brow, 0);
;   STAGE(SB(0, 1), Bt, bcol + HALF, 0); STAGE(SA(0, 1), A, brow + HALF, 0);
;   if (wr == 1) BAR;
;   WAIT_V(4); BAR;
;   STAGE(SB(1, 0), Bt, bcol, 1); STAGE(SA(1, 0), A, brow, 1); STAGE(SB(1, 1), Bt, bcol + HALF, 1);
;   WAIT_V(6); BAR;
.LBB0_1561:
	s_add_u32 s84, s10, s54
	v_add_u32_e32 v146, s67, v4
	s_addc_u32 s85, s11, s55
	v_lshl_add_u64 v[6:7], s[84:85], 0, v[136:137]
	v_readfirstlane_b32 s39, v146
	s_add_u32 s42, s10, s42
	v_lshl_add_u64 v[6:7], v[6:7], 0, s[18:19]
	s_mov_b32 m0, s39
	s_addc_u32 s43, s11, s43
	v_add_u32_e32 v147, 0x2000, v146
	s_waitcnt vmcnt(4)
	s_barrier
	global_load_lds_dwordx4 v[6:7], off
	v_lshl_add_u64 v[6:7], s[42:43], 0, v[136:137]
	v_readfirstlane_b32 s39, v147
	s_add_u32 s42, s60, s50
	v_lshl_add_u64 v[6:7], v[6:7], 0, s[18:19]
	s_mov_b32 m0, s39
	s_addc_u32 s43, s61, s51
	v_add_u32_e32 v148, 0x8000, v132
	global_load_lds_dwordx4 v[6:7], off
	v_lshl_add_u64 v[6:7], s[42:43], 0, v[136:137]
	v_readfirstlane_b32 s39, v148
	s_add_u32 s42, s60, s52
	v_lshl_add_u64 v[6:7], v[6:7], 0, s[18:19]
	s_mov_b32 m0, s39
	s_addc_u32 s43, s61, s53
	global_load_lds_dwordx4 v[6:7], off
	v_lshl_add_u64 v[6:7], s[42:43], 0, v[136:137]
	v_add_u32_e32 v149, 0xa000, v132
	s_add_u32 s42, s10, s48
	v_readfirstlane_b32 s39, v149
	v_add_u32_e32 v150, s68, v4
	s_addc_u32 s43, s11, s49
	v_lshl_add_u64 v[6:7], v[6:7], 0, s[18:19]
	s_mov_b32 m0, s39
	v_lshl_add_u64 v[4:5], s[42:43], 0, v[136:137]
	v_readfirstlane_b32 s39, v150
	s_add_u32 s42, s10, s56
	global_load_lds_dwordx4 v[6:7], off
	v_lshl_add_u64 v[4:5], v[4:5], 0, s[18:19]
	s_mov_b32 m0, s39
	s_addc_u32 s43, s11, s57
	v_add_u32_e32 v151, 0x2000, v150
	global_load_lds_dwordx4 v[4:5], off
	v_lshl_add_u64 v[4:5], s[42:43], 0, v[136:137]
	v_readfirstlane_b32 s39, v151
	v_lshl_add_u64 v[4:5], v[4:5], 0, s[18:19]
	s_mov_b32 m0, s39
	v_and_b32_e32 v8, 15, v0
	global_load_lds_dwordx4 v[4:5], off
	v_and_b32_e32 v9, 48, v0
	v_lshlrev_b32_e32 v5, 2, v0
	s_lshl_b32 s39, s94, 6
	s_lshl_b32 s84, s37, 13
	v_lshlrev_b32_e32 v0, 6, v0
	s_movk_i32 s37, 0x3c0
	s_and_b32 s57, s39, 0x3000
	v_and_or_b32 v0, v0, s37, v9
	s_or_b32 s37, s84, 0x800
	s_or_b32 s39, s84, 0x1000
	s_or_b32 s41, s84, 0x1800
	s_add_u32 s42, s46, s4
	s_addc_u32 s43, s47, s5
	s_add_u32 s48, s46, s6
	v_and_b32_e32 v5, 32, v5
	s_addc_u32 s49, s47, s7
	v_xad_u32 v153, v0, v5, 16
	v_lshlrev_b32_e32 v0, 15, v1
	s_add_u32 s50, s46, s50
	v_and_b32_e32 v0, 0xffff0000, v0
	s_addc_u32 s51, s47, s51
	v_lshlrev_b32_e32 v4, 6, v8
	v_lshl_add_u32 v0, v2, 12, v0
	v_and_b32_e32 v1, 1, v1
	s_add_u32 s52, s46, s52
	s_waitcnt vmcnt(6)
	v_bitop3_b32 v4, v4, v5, v9 bitop3:0x36
	v_lshl_or_b32 v0, v1, 6, v0
	s_addc_u32 s53, s47, s53
	v_add_u32_e32 v6, s65, v4
	v_add_u32_e32 v7, s66, v4
	v_add_u32_e32 v8, s67, v4
	v_add_u32_e32 v10, s68, v4
	v_add_u32_e32 v4, 16, v4
	v_lshl_add_u32 v128, v3, 1, v0
	s_add_u32 s54, s46, s54
	v_mov_b32_e32 v0, 0
	v_mov_b32_e32 v129, v137
	s_addc_u32 s55, s47, s55
	s_mov_b32 s56, -2
	v_add_u32_e32 v154, s57, v6
	v_add_u32_e32 v141, s84, v4
	v_add_u32_e32 v152, s57, v7
	v_add_u32_e32 v145, s57, v8
	v_add_u32_e32 v142, s57, v10
	v_mov_b32_e32 v1, v0
	v_mov_b32_e32 v2, v0
	v_mov_b32_e32 v3, v0
	v_mov_b32_e32 v4, v0
	v_mov_b32_e32 v5, v0
	v_mov_b32_e32 v6, v0
	v_mov_b32_e32 v7, v0
	v_mov_b32_e32 v8, v0
	v_mov_b32_e32 v9, v0
	v_mov_b32_e32 v10, v0
	v_mov_b32_e32 v11, v0
	v_mov_b32_e32 v12, v0
	v_mov_b32_e32 v13, v0
	v_mov_b32_e32 v14, v0
	v_mov_b32_e32 v15, v0
	v_mov_b32_e32 v16, v0
	v_mov_b32_e32 v17, v0
	v_mov_b32_e32 v18, v0
	v_mov_b32_e32 v19, v0
	v_mov_b32_e32 v20, v0
	v_mov_b32_e32 v21, v0
	v_mov_b32_e32 v22, v0
	v_mov_b32_e32 v23, v0
	v_mov_b32_e32 v24, v0
	v_mov_b32_e32 v25, v0
	v_mov_b32_e32 v26, v0
	v_mov_b32_e32 v27, v0
	v_mov_b32_e32 v28, v0
	v_mov_b32_e32 v29, v0
	v_mov_b32_e32 v30, v0
	v_mov_b32_e32 v31, v0
	v_mov_b32_e32 v32, v0
	v_mov_b32_e32 v33, v0
	v_mov_b32_e32 v34, v0
	v_mov_b32_e32 v35, v0
	v_mov_b32_e32 v36, v0
	v_mov_b32_e32 v37, v0
	v_mov_b32_e32 v38, v0
	v_mov_b32_e32 v39, v0
	v_mov_b32_e32 v40, v0
	v_mov_b32_e32 v41, v0
	v_mov_b32_e32 v42, v0
	v_mov_b32_e32 v43, v0
	v_mov_b32_e32 v44, v0
	v_mov_b32_e32 v45, v0
	v_mov_b32_e32 v46, v0
	v_mov_b32_e32 v47, v0
	v_mov_b32_e32 v48, v0
	v_mov_b32_e32 v49, v0
	v_mov_b32_e32 v50, v0
	v_mov_b32_e32 v51, v0
	v_mov_b32_e32 v52, v0
	v_mov_b32_e32 v53, v0
	v_mov_b32_e32 v54, v0
	v_mov_b32_e32 v55, v0
	v_mov_b32_e32 v56, v0
	v_mov_b32_e32 v57, v0
	v_mov_b32_e32 v58, v0
	v_mov_b32_e32 v59, v0
	v_mov_b32_e32 v60, v0
	v_mov_b32_e32 v61, v0
	v_mov_b32_e32 v62, v0
	v_mov_b32_e32 v63, v0
	v_mov_b32_e32 v64, v0
	v_mov_b32_e32 v65, v0
	v_mov_b32_e32 v66, v0
	v_mov_b32_e32 v67, v0
	v_mov_b32_e32 v68, v0
	v_mov_b32_e32 v69, v0
	v_mov_b32_e32 v70, v0
	v_mov_b32_e32 v71, v0
	v_mov_b32_e32 v72, v0
	v_mov_b32_e32 v73, v0
	v_mov_b32_e32 v74, v0
	v_mov_b32_e32 v75, v0
	v_mov_b32_e32 v76, v0
	v_mov_b32_e32 v77, v0
	v_mov_b32_e32 v78, v0
	v_mov_b32_e32 v79, v0
	v_mov_b32_e32 v80, v0
	v_mov_b32_e32 v81, v0
	v_mov_b32_e32 v82, v0
	v_mov_b32_e32 v83, v0
	v_mov_b32_e32 v84, v0
	v_mov_b32_e32 v85, v0
	v_mov_b32_e32 v86, v0
	v_mov_b32_e32 v87, v0
	v_mov_b32_e32 v88, v0
	v_mov_b32_e32 v89, v0
	v_mov_b32_e32 v90, v0
	v_mov_b32_e32 v91, v0
	v_mov_b32_e32 v92, v0
	v_mov_b32_e32 v93, v0
	v_mov_b32_e32 v94, v0
	v_mov_b32_e32 v95, v0
	v_mov_b32_e32 v96, v0
	v_mov_b32_e32 v97, v0
	v_mov_b32_e32 v98, v0
	v_mov_b32_e32 v99, v0
	v_mov_b32_e32 v100, v0
	v_mov_b32_e32 v101, v0
	v_mov_b32_e32 v102, v0
	v_mov_b32_e32 v103, v0
	v_mov_b32_e32 v104, v0
	v_mov_b32_e32 v105, v0
	v_mov_b32_e32 v106, v0
	v_mov_b32_e32 v107, v0
	v_mov_b32_e32 v108, v0
	v_mov_b32_e32 v109, v0
	v_mov_b32_e32 v110, v0
	v_mov_b32_e32 v111, v0
	v_mov_b32_e32 v112, v0
	v_mov_b32_e32 v113, v0
	v_mov_b32_e32 v114, v0
	v_mov_b32_e32 v115, v0
	v_mov_b32_e32 v116, v0
	v_mov_b32_e32 v117, v0
	v_mov_b32_e32 v118, v0
	v_mov_b32_e32 v119, v0
	v_mov_b32_e32 v120, v0
	v_mov_b32_e32 v121, v0
	v_mov_b32_e32 v122, v0
	v_mov_b32_e32 v123, v0
	v_mov_b32_e32 v124, v0
	v_mov_b32_e32 v125, v0
	v_mov_b32_e32 v126, v0
	v_mov_b32_e32 v127, v0
	s_barrier
	v_add_u32_e32 v159, 0xc000, v132
	v_add_u32_e32 v158, 0xe000, v132
	v_add_u32_e32 v155, s37, v153
	v_add_u32_e32 v156, s39, v153
	v_add_u32_e32 v157, s41, v153
; #define WAIT_L(n) asm volatile("s_waitcnt lgkmcnt(" #n ")" ::: "memory")
; #define BAR __builtin_amdgcn_s_barrier()
; #define SCHED __builtin_amdgcn_sched_barrier(0)
; template <int EPI>
; __device__ __forceinline__ void gemm_tile(const Params& p, const bf16* __restrict__ A, const bf16* __restrict__ Bt, const int K,
;                                           const int nt, const int brow, const int bcol, int pm, int pn) {
;     ...
;     LDB(B0, 0, 0); SCHED; LDA(At, 0, 0); STAGE(SA(1, 1), A, brow + HALF, t + 1);
;     WAIT_L(8); BAR; WAIT_L(0); MMA(0, 0, At, B0); BAR; SCHED;
;     LDB(B1, 0, 1); STAGE(SB(0, 0), Bt, bcol, t + 2);
;     BAR; WAIT_L(0); MMA(0, 1, At, B1); BAR;
;     LDA(At, 0, 1); STAGE(SA(0, 0), A, brow, t + 2);
;     BAR; WAIT_L(0); MMA(1, 0, At, B0); BAR; SCHED;
.LBB0_1562:
	ds_read_b128 v[162:165], v154
	ds_read_b128 v[166:169], v154 offset:1024
	ds_read_b128 v[170:173], v154 offset:2048
	ds_read_b128 v[174:177], v154 offset:3072
	v_lshl_add_u64 v[204:205], s[42:43], 0, v[128:129]
	v_readfirstlane_b32 s57, v159
	v_lshl_add_u64 v[216:217], v[204:205], 0, s[20:21]
	s_mov_b32 m0, s57
	v_lshl_add_u64 v[232:233], s[48:49], 0, v[128:129]
	v_readfirstlane_b32 s57, v158
	ds_read_b128 v[178:181], v141
	ds_read_b128 v[182:185], v141 offset:1024
	ds_read_b128 v[186:189], v155
	ds_read_b128 v[190:193], v155 offset:1024
	ds_read_b128 v[196:199], v156
	ds_read_b128 v[200:203], v156 offset:1024
	ds_read_b128 v[208:211], v157
	ds_read_b128 v[212:215], v157 offset:1024
	global_load_lds_dwordx4 v[216:217], off
	v_lshl_add_u64 v[216:217], v[232:233], 0, s[20:21]
	s_mov_b32 m0, s57
	s_nop 0
	global_load_lds_dwordx4 v[216:217], off
	s_waitcnt lgkmcnt(8)
	s_setprio 1
	s_barrier
	s_waitcnt lgkmcnt(0)
	s_waitcnt lgkmcnt(0)
	v_mfma_f32_16x16x32_bf16 v[124:127], v[178:181], v[162:165], v[124:127]
	v_mfma_f32_16x16x32_bf16 v[120:123], v[178:181], v[170:173], v[120:123]
	v_mfma_f32_16x16x32_bf16 v[116:119], v[186:189], v[162:165], v[116:119]
	v_mfma_f32_16x16x32_bf16 v[112:115], v[186:189], v[170:173], v[112:115]
	v_mfma_f32_16x16x32_bf16 v[108:111], v[196:199], v[162:165], v[108:111]
	v_mfma_f32_16x16x32_bf16 v[104:107], v[196:199], v[170:173], v[104:107]
	v_mfma_f32_16x16x32_bf16 v[100:103], v[208:211], v[162:165], v[100:103]
	v_mfma_f32_16x16x32_bf16 v[96:99], v[208:211], v[170:173], v[96:99]
	v_mfma_f32_16x16x32_bf16 v[124:127], v[182:185], v[166:169], v[124:127]
	v_mfma_f32_16x16x32_bf16 v[120:123], v[182:185], v[174:177], v[120:123]
	v_mfma_f32_16x16x32_bf16 v[116:119], v[190:193], v[166:169], v[116:119]
	v_mfma_f32_16x16x32_bf16 v[112:115], v[190:193], v[174:177], v[112:115]
	v_mfma_f32_16x16x32_bf16 v[108:111], v[200:203], v[166:169], v[108:111]
	v_mfma_f32_16x16x32_bf16 v[104:107], v[200:203], v[174:177], v[104:107]
	v_mfma_f32_16x16x32_bf16 v[100:103], v[212:215], v[166:169], v[100:103]
	v_mfma_f32_16x16x32_bf16 v[96:99], v[212:215], v[174:177], v[96:99]
	s_setprio 0
	s_barrier
	v_lshl_add_u64 v[234:235], s[54:55], 0, v[128:129]
	s_mov_b64 s[84:85], 0x2000100
	v_readfirstlane_b32 s57, v130
	v_lshl_add_u64 v[236:237], v[234:235], 0, s[84:85]
	s_mov_b32 m0, s57
	s_mov_b64 s[84:85], 0x2040100
	v_readfirstlane_b32 s57, v131
	ds_read_b128 v[216:219], v152
	ds_read_b128 v[220:223], v152 offset:1024
	ds_read_b128 v[224:227], v152 offset:2048
	ds_read_b128 v[228:231], v152 offset:3072
	global_load_lds_dwordx4 v[236:237], off
	v_lshl_add_u64 v[236:237], v[234:235], 0, s[84:85]
	s_mov_b32 m0, s57
	s_nop 0
	global_load_lds_dwordx4 v[236:237], off
	s_setprio 1
	s_barrier
	s_waitcnt lgkmcnt(0)
	s_waitcnt lgkmcnt(0)
	v_mfma_f32_16x16x32_bf16 v[92:95], v[178:181], v[216:219], v[92:95]
	v_mfma_f32_16x16x32_bf16 v[88:91], v[178:181], v[224:227], v[88:91]
	v_mfma_f32_16x16x32_bf16 v[84:87], v[186:189], v[216:219], v[84:87]
	v_mfma_f32_16x16x32_bf16 v[80:83], v[186:189], v[224:227], v[80:83]
	v_mfma_f32_16x16x32_bf16 v[76:79], v[196:199], v[216:219], v[76:79]
	v_mfma_f32_16x16x32_bf16 v[72:75], v[196:199], v[224:227], v[72:75]
	v_mfma_f32_16x16x32_bf16 v[68:71], v[208:211], v[216:219], v[68:71]
	v_mfma_f32_16x16x32_bf16 v[64:67], v[208:211], v[224:227], v[64:67]
	v_mfma_f32_16x16x32_bf16 v[92:95], v[182:185], v[220:223], v[92:95]
	v_mfma_f32_16x16x32_bf16 v[88:91], v[182:185], v[228:231], v[88:91]
	v_mfma_f32_16x16x32_bf16 v[84:87], v[190:193], v[220:223], v[84:87]
	v_mfma_f32_16x16x32_bf16 v[80:83], v[190:193], v[228:231], v[80:83]
	v_mfma_f32_16x16x32_bf16 v[76:79], v[200:203], v[220:223], v[76:79]
	v_mfma_f32_16x16x32_bf16 v[72:75], v[200:203], v[228:231], v[72:75]
	v_mfma_f32_16x16x32_bf16 v[68:71], v[212:215], v[220:223], v[68:71]
	v_mfma_f32_16x16x32_bf16 v[64:67], v[212:215], v[228:231], v[64:67]
	s_setprio 0
	v_lshl_add_u64 v[236:237], s[50:51], 0, v[128:129]
	v_readfirstlane_b32 s57, v132
	v_lshl_add_u64 v[238:239], v[236:237], 0, s[22:23]
	s_mov_b32 m0, s57
	s_barrier
	ds_read_b128 v[178:181], v141 offset:16384
	ds_read_b128 v[182:185], v141 offset:17408
	ds_read_b128 v[186:189], v155 offset:16384
	ds_read_b128 v[190:193], v155 offset:17408
	ds_read_b128 v[196:199], v156 offset:16384
	ds_read_b128 v[200:203], v156 offset:17408
	ds_read_b128 v[208:211], v157 offset:16384
	ds_read_b128 v[212:215], v157 offset:17408
	global_load_lds_dwordx4 v[238:239], off
	v_lshl_add_u64 v[238:239], s[52:53], 0, v[128:129]
	v_readfirstlane_b32 s57, v133
	v_lshl_add_u64 v[240:241], v[238:239], 0, s[22:23]
	s_mov_b32 m0, s57
	s_nop 0
	global_load_lds_dwordx4 v[240:241], off
	s_setprio 1
	s_barrier
	s_waitcnt lgkmcnt(0)
	s_waitcnt lgkmcnt(0)
	v_mfma_f32_16x16x32_bf16 v[60:63], v[178:181], v[162:165], v[60:63]
	v_mfma_f32_16x16x32_bf16 v[56:59], v[178:181], v[170:173], v[56:59]
	v_mfma_f32_16x16x32_bf16 v[52:55], v[186:189], v[162:165], v[52:55]
	v_mfma_f32_16x16x32_bf16 v[48:51], v[186:189], v[170:173], v[48:51]
	v_mfma_f32_16x16x32_bf16 v[44:47], v[196:199], v[162:165], v[44:47]
	v_mfma_f32_16x16x32_bf16 v[40:43], v[196:199], v[170:173], v[40:43]
	v_mfma_f32_16x16x32_bf16 v[36:39], v[208:211], v[162:165], v[36:39]
	v_mfma_f32_16x16x32_bf16 v[32:35], v[208:211], v[170:173], v[32:35]
	v_mfma_f32_16x16x32_bf16 v[60:63], v[182:185], v[166:169], v[60:63]
	v_mfma_f32_16x16x32_bf16 v[56:59], v[182:185], v[174:177], v[56:59]
	v_mfma_f32_16x16x32_bf16 v[52:55], v[190:193], v[166:169], v[52:55]
	v_mfma_f32_16x16x32_bf16 v[48:51], v[190:193], v[174:177], v[48:51]
	v_mfma_f32_16x16x32_bf16 v[44:47], v[200:203], v[166:169], v[44:47]
	v_mfma_f32_16x16x32_bf16 v[40:43], v[200:203], v[174:177], v[40:43]
	v_mfma_f32_16x16x32_bf16 v[36:39], v[212:215], v[166:169], v[36:39]
	v_mfma_f32_16x16x32_bf16 v[32:35], v[212:215], v[174:177], v[32:35]
	s_setprio 0
	s_barrier
; #define WAIT_V(n) asm volatile("s_waitcnt vmcnt(" #n ")" ::: "memory")
; #define WAIT_L(n) asm volatile("s_waitcnt lgkmcnt(" #n ")" ::: "memory")
; #define BAR __builtin_amdgcn_s_barrier()
; #define SCHED __builtin_amdgcn_sched_barrier(0)
; template <int EPI>
; __device__ __forceinline__ void gemm_tile(const Params& p, const bf16* __restrict__ A, const bf16* __restrict__ Bt, const int K,
;                                           const int nt, const int brow, const int bcol, int pm, int pn) {
;     ...
;     STAGE(SB(0, 1), Bt, bcol + HALF, t + 2);
;     WAIT_V(6); BAR; MMA(1, 1, At, B1); BAR;
;     LDB(B0, 1, 0); SCHED; LDA(At, 1, 0); STAGE(SA(0, 1), A, brow + HALF, t + 2);
;     WAIT_L(8); BAR; WAIT_L(0); MMA(0, 0, At, B0); BAR; SCHED;
;     LDB(B1, 1, 1); STAGE(SB(1, 0), Bt, bcol, t + 3);
;     BAR; WAIT_L(0); MMA(0, 1, At, B1); BAR;
;     LDA(At, 1, 1); STAGE(SA(1, 0), A, brow, t + 3);
	s_mov_b64 s[84:85], 0x2080100
	v_readfirstlane_b32 s57, v134
	v_lshl_add_u64 v[162:163], v[234:235], 0, s[84:85]
	s_mov_b32 m0, s57
	s_mov_b64 s[84:85], 0x20c0100
	v_readfirstlane_b32 s57, v135
	global_load_lds_dwordx4 v[162:163], off
	v_lshl_add_u64 v[162:163], v[234:235], 0, s[84:85]
	s_mov_b32 m0, s57
	s_nop 0
	global_load_lds_dwordx4 v[162:163], off
	s_waitcnt vmcnt(6)
	s_setprio 1
	s_barrier
	v_mfma_f32_16x16x32_bf16 v[28:31], v[178:181], v[216:219], v[28:31]
	v_mfma_f32_16x16x32_bf16 v[24:27], v[178:181], v[224:227], v[24:27]
	v_mfma_f32_16x16x32_bf16 v[20:23], v[186:189], v[216:219], v[20:23]
	v_mfma_f32_16x16x32_bf16 v[16:19], v[186:189], v[224:227], v[16:19]
	v_mfma_f32_16x16x32_bf16 v[12:15], v[196:199], v[216:219], v[12:15]
	v_mfma_f32_16x16x32_bf16 v[8:11], v[196:199], v[224:227], v[8:11]
	v_mfma_f32_16x16x32_bf16 v[4:7], v[208:211], v[216:219], v[4:7]
	v_mfma_f32_16x16x32_bf16 v[0:3], v[208:211], v[224:227], v[0:3]
	v_mfma_f32_16x16x32_bf16 v[28:31], v[182:185], v[220:223], v[28:31]
	v_mfma_f32_16x16x32_bf16 v[24:27], v[182:185], v[228:231], v[24:27]
	v_mfma_f32_16x16x32_bf16 v[20:23], v[190:193], v[220:223], v[20:23]
	v_mfma_f32_16x16x32_bf16 v[16:19], v[190:193], v[228:231], v[16:19]
	v_mfma_f32_16x16x32_bf16 v[12:15], v[200:203], v[220:223], v[12:15]
	v_mfma_f32_16x16x32_bf16 v[8:11], v[200:203], v[228:231], v[8:11]
	v_mfma_f32_16x16x32_bf16 v[4:7], v[212:215], v[220:223], v[4:7]
	v_mfma_f32_16x16x32_bf16 v[0:3], v[212:215], v[228:231], v[0:3]
	s_setprio 0
	s_barrier
	ds_read_b128 v[162:165], v145
	ds_read_b128 v[166:169], v145 offset:1024
	ds_read_b128 v[170:173], v145 offset:2048
	ds_read_b128 v[174:177], v145 offset:3072
	v_readfirstlane_b32 s57, v143
	v_lshl_add_u64 v[204:205], v[204:205], 0, s[22:23]
	s_mov_b32 m0, s57
	v_readfirstlane_b32 s57, v144
	ds_read_b128 v[178:181], v141 offset:32768
	ds_read_b128 v[182:185], v141 offset:33792
	ds_read_b128 v[186:189], v155 offset:32768
	ds_read_b128 v[190:193], v155 offset:33792
	ds_read_b128 v[196:199], v156 offset:32768
	ds_read_b128 v[200:203], v156 offset:33792
	ds_read_b128 v[208:211], v157 offset:32768
	ds_read_b128 v[212:215], v157 offset:33792
	global_load_lds_dwordx4 v[204:205], off
	v_lshl_add_u64 v[204:205], v[232:233], 0, s[22:23]
	s_mov_b32 m0, s57
	s_nop 0
	global_load_lds_dwordx4 v[204:205], off
	s_waitcnt lgkmcnt(8)
	s_setprio 1
	s_barrier
	s_waitcnt lgkmcnt(0)
	s_waitcnt lgkmcnt(0)
	v_mfma_f32_16x16x32_bf16 v[124:127], v[178:181], v[162:165], v[124:127]
	v_mfma_f32_16x16x32_bf16 v[120:123], v[178:181], v[170:173], v[120:123]
	v_mfma_f32_16x16x32_bf16 v[116:119], v[186:189], v[162:165], v[116:119]
	v_mfma_f32_16x16x32_bf16 v[112:115], v[186:189], v[170:173], v[112:115]
	v_mfma_f32_16x16x32_bf16 v[108:111], v[196:199], v[162:165], v[108:111]
	v_mfma_f32_16x16x32_bf16 v[104:107], v[196:199], v[170:173], v[104:107]
	v_mfma_f32_16x16x32_bf16 v[100:103], v[208:211], v[162:165], v[100:103]
	v_mfma_f32_16x16x32_bf16 v[96:99], v[208:211], v[170:173], v[96:99]
	v_mfma_f32_16x16x32_bf16 v[124:127], v[182:185], v[166:169], v[124:127]
	v_mfma_f32_16x16x32_bf16 v[120:123], v[182:185], v[174:177], v[120:123]
	v_mfma_f32_16x16x32_bf16 v[116:119], v[190:193], v[166:169], v[116:119]
	v_mfma_f32_16x16x32_bf16 v[112:115], v[190:193], v[174:177], v[112:115]
	v_mfma_f32_16x16x32_bf16 v[108:111], v[200:203], v[166:169], v[108:111]
	v_mfma_f32_16x16x32_bf16 v[104:107], v[200:203], v[174:177], v[104:107]
	v_mfma_f32_16x16x32_bf16 v[100:103], v[212:215], v[166:169], v[100:103]
	v_mfma_f32_16x16x32_bf16 v[96:99], v[212:215], v[174:177], v[96:99]
	s_setprio 0
	s_barrier
	s_mov_b64 s[84:85], 0x2000180
	v_readfirstlane_b32 s57, v146
	v_lshl_add_u64 v[204:205], v[234:235], 0, s[84:85]
	s_mov_b32 m0, s57
	s_mov_b64 s[84:85], 0x2040180
	v_readfirstlane_b32 s57, v147
	ds_read_b128 v[216:219], v142
	ds_read_b128 v[220:223], v142 offset:1024
	ds_read_b128 v[224:227], v142 offset:2048
	ds_read_b128 v[228:231], v142 offset:3072
	global_load_lds_dwordx4 v[204:205], off
	v_lshl_add_u64 v[204:205], v[234:235], 0, s[84:85]
	s_mov_b32 m0, s57
	s_nop 0
	global_load_lds_dwordx4 v[204:205], off
	s_setprio 1
	s_barrier
	s_waitcnt lgkmcnt(0)
	s_waitcnt lgkmcnt(0)
	v_mfma_f32_16x16x32_bf16 v[92:95], v[178:181], v[216:219], v[92:95]
	v_mfma_f32_16x16x32_bf16 v[88:91], v[178:181], v[224:227], v[88:91]
	v_mfma_f32_16x16x32_bf16 v[84:87], v[186:189], v[216:219], v[84:87]
	v_mfma_f32_16x16x32_bf16 v[80:83], v[186:189], v[224:227], v[80:83]
	v_mfma_f32_16x16x32_bf16 v[76:79], v[196:199], v[216:219], v[76:79]
	v_mfma_f32_16x16x32_bf16 v[72:75], v[196:199], v[224:227], v[72:75]
	v_mfma_f32_16x16x32_bf16 v[68:71], v[208:211], v[216:219], v[68:71]
	v_mfma_f32_16x16x32_bf16 v[64:67], v[208:211], v[224:227], v[64:67]
	v_mfma_f32_16x16x32_bf16 v[92:95], v[182:185], v[220:223], v[92:95]
	v_mfma_f32_16x16x32_bf16 v[88:91], v[182:185], v[228:231], v[88:91]
	v_mfma_f32_16x16x32_bf16 v[84:87], v[190:193], v[220:223], v[84:87]
	v_mfma_f32_16x16x32_bf16 v[80:83], v[190:193], v[228:231], v[80:83]
	v_mfma_f32_16x16x32_bf16 v[76:79], v[200:203], v[220:223], v[76:79]
	v_mfma_f32_16x16x32_bf16 v[72:75], v[200:203], v[228:231], v[72:75]
	v_mfma_f32_16x16x32_bf16 v[68:71], v[212:215], v[220:223], v[68:71]
	v_mfma_f32_16x16x32_bf16 v[64:67], v[212:215], v[228:231], v[64:67]
	s_setprio 0
	v_readfirstlane_b32 s57, v148
	v_lshl_add_u64 v[204:205], v[236:237], 0, s[24:25]
	s_mov_b32 m0, s57
	v_readfirstlane_b32 s57, v149
	s_barrier
; #define WAIT_V(n) asm volatile("s_waitcnt vmcnt(" #n ")" ::: "memory")
; #define WAIT_L(n) asm volatile("s_waitcnt lgkmcnt(" #n ")" ::: "memory")
; #define BAR __builtin_amdgcn_s_barrier()
; #define SCHED __builtin_amdgcn_sched_barrier(0)
; template <int EPI>
; __device__ __forceinline__ void gemm_tile(const Params& p, const bf16* __restrict__ A, const bf16* __restrict__ Bt, const int K,
;                                           const int nt, const int brow, const int bcol, int pm, int pn) {
;     ...
;     LDA(At, 1, 1); STAGE(SA(1, 0), A, brow, t + 3);
;     BAR; WAIT_L(0); MMA(1, 0, At, B0); BAR; SCHED;
;     STAGE(SB(1, 1), Bt, bcol + HALF, t + 3);
;     WAIT_V(6); BAR; MMA(1, 1, At, B1); BAR;
;   }
;   { LDB(B0, 0, 0); LDA(At, 0, 0); STAGE(SA(1, 1), A, brow + HALF, nt - 1);
;     BAR; WAIT_L(0); MMA(0, 0, At, B0); BAR;
	ds_read_b128 v[178:181], v141 offset:49152
	ds_read_b128 v[182:185], v141 offset:50176
	ds_read_b128 v[186:189], v155 offset:49152
	ds_read_b128 v[190:193], v155 offset:50176
	ds_read_b128 v[196:199], v156 offset:49152
	ds_read_b128 v[200:203], v156 offset:50176
	ds_read_b128 v[208:211], v157 offset:49152
	ds_read_b128 v[212:215], v157 offset:50176
	global_load_lds_dwordx4 v[204:205], off
	v_lshl_add_u64 v[204:205], v[238:239], 0, s[24:25]
	s_mov_b32 m0, s57
	s_nop 0
	global_load_lds_dwordx4 v[204:205], off
	s_setprio 1
	s_barrier
	s_waitcnt lgkmcnt(0)
	s_waitcnt lgkmcnt(0)
	v_mfma_f32_16x16x32_bf16 v[60:63], v[178:181], v[162:165], v[60:63]
	v_mfma_f32_16x16x32_bf16 v[56:59], v[178:181], v[170:173], v[56:59]
	v_mfma_f32_16x16x32_bf16 v[52:55], v[186:189], v[162:165], v[52:55]
	v_mfma_f32_16x16x32_bf16 v[48:51], v[186:189], v[170:173], v[48:51]
	v_mfma_f32_16x16x32_bf16 v[44:47], v[196:199], v[162:165], v[44:47]
	v_mfma_f32_16x16x32_bf16 v[40:43], v[196:199], v[170:173], v[40:43]
	v_mfma_f32_16x16x32_bf16 v[36:39], v[208:211], v[162:165], v[36:39]
	v_mfma_f32_16x16x32_bf16 v[32:35], v[208:211], v[170:173], v[32:35]
	v_mfma_f32_16x16x32_bf16 v[60:63], v[182:185], v[166:169], v[60:63]
	v_mfma_f32_16x16x32_bf16 v[56:59], v[182:185], v[174:177], v[56:59]
	v_mfma_f32_16x16x32_bf16 v[52:55], v[190:193], v[166:169], v[52:55]
	v_mfma_f32_16x16x32_bf16 v[48:51], v[190:193], v[174:177], v[48:51]
	v_mfma_f32_16x16x32_bf16 v[44:47], v[200:203], v[166:169], v[44:47]
	v_mfma_f32_16x16x32_bf16 v[40:43], v[200:203], v[174:177], v[40:43]
	v_mfma_f32_16x16x32_bf16 v[36:39], v[212:215], v[166:169], v[36:39]
	v_mfma_f32_16x16x32_bf16 v[32:35], v[212:215], v[174:177], v[32:35]
	s_setprio 0
	s_barrier
	s_mov_b64 s[84:85], 0x2080180
	v_readfirstlane_b32 s57, v150
	v_lshl_add_u64 v[162:163], v[234:235], 0, s[84:85]
	s_mov_b32 m0, s57
	v_readfirstlane_b32 s57, v151
	global_load_lds_dwordx4 v[162:163], off
	v_lshl_add_u64 v[162:163], v[234:235], 0, s[26:27]
	s_mov_b32 m0, s57
	s_nop 0
	global_load_lds_dwordx4 v[162:163], off
	s_waitcnt vmcnt(6)
	s_setprio 1
	s_barrier
	v_mfma_f32_16x16x32_bf16 v[28:31], v[178:181], v[216:219], v[28:31]
	v_mfma_f32_16x16x32_bf16 v[24:27], v[178:181], v[224:227], v[24:27]
	v_mfma_f32_16x16x32_bf16 v[20:23], v[186:189], v[216:219], v[20:23]
	v_mfma_f32_16x16x32_bf16 v[16:19], v[186:189], v[224:227], v[16:19]
	v_mfma_f32_16x16x32_bf16 v[12:15], v[196:199], v[216:219], v[12:15]
	v_mfma_f32_16x16x32_bf16 v[8:11], v[196:199], v[224:227], v[8:11]
	v_mfma_f32_16x16x32_bf16 v[4:7], v[208:211], v[216:219], v[4:7]
	v_mfma_f32_16x16x32_bf16 v[0:3], v[208:211], v[224:227], v[0:3]
	v_mfma_f32_16x16x32_bf16 v[28:31], v[182:185], v[220:223], v[28:31]
	v_mfma_f32_16x16x32_bf16 v[24:27], v[182:185], v[228:231], v[24:27]
	v_mfma_f32_16x16x32_bf16 v[20:23], v[190:193], v[220:223], v[20:23]
	v_mfma_f32_16x16x32_bf16 v[16:19], v[190:193], v[228:231], v[16:19]
	v_mfma_f32_16x16x32_bf16 v[12:15], v[200:203], v[220:223], v[12:15]
	v_mfma_f32_16x16x32_bf16 v[8:11], v[200:203], v[228:231], v[8:11]
	v_mfma_f32_16x16x32_bf16 v[4:7], v[212:215], v[220:223], v[4:7]
	v_mfma_f32_16x16x32_bf16 v[0:3], v[212:215], v[228:231], v[0:3]
	s_setprio 0
	s_add_i32 s56, s56, 2
	s_add_u32 s42, s42, 0x100
	s_addc_u32 s43, s43, 0
	s_add_u32 s48, s48, 0x100
	s_addc_u32 s49, s49, 0
	s_add_u32 s50, s50, 0x100
	s_addc_u32 s51, s51, 0
	s_add_u32 s52, s52, 0x100
	s_addc_u32 s53, s53, 0
	s_add_u32 s54, s54, 0x100
	s_addc_u32 s55, s55, 0
	s_cmp_lt_u32 s56, 28
	s_barrier
	s_cbranch_scc1 .LBB0_1562
	s_add_u32 s4, s60, s4
	s_addc_u32 s5, s61, s5
	v_lshl_add_u64 v[150:151], s[4:5], 0, v[136:137]
	v_readfirstlane_b32 s4, v159
	s_mov_b32 m0, s4
	s_add_u32 s4, s60, s6
	v_lshl_add_u64 v[150:151], v[150:151], 0, s[28:29]
	s_addc_u32 s5, s61, s7
	ds_read_b128 v[128:131], v154
	ds_read_b128 v[132:135], v154 offset:1024
	ds_read_b128 v[146:149], v154 offset:2048
	ds_read_b128 v[162:165], v154 offset:3072
	ds_read_b128 v[166:169], v141
	ds_read_b128 v[170:173], v141 offset:1024
	ds_read_b128 v[174:177], v155
	ds_read_b128 v[178:181], v155 offset:1024
	ds_read_b128 v[182:185], v156
	ds_read_b128 v[186:189], v156 offset:1024
	ds_read_b128 v[190:193], v157
	ds_read_b128 v[196:199], v157 offset:1024
	global_load_lds_dwordx4 v[150:151], off
	v_lshl_add_u64 v[150:151], s[4:5], 0, v[136:137]
	v_readfirstlane_b32 s4, v158
	v_lshl_add_u64 v[150:151], v[150:151], 0, s[28:29]
	s_mov_b32 m0, s4
	s_nop 0
	global_load_lds_dwordx4 v[150:151], off
	s_setprio 1
	s_barrier
	s_waitcnt lgkmcnt(0)
	s_waitcnt lgkmcnt(0)
	v_mfma_f32_16x16x32_bf16 v[124:127], v[166:169], v[128:131], v[124:127]
	v_mfma_f32_16x16x32_bf16 v[120:123], v[166:169], v[146:149], v[120:123]
	v_mfma_f32_16x16x32_bf16 v[116:119], v[174:177], v[128:131], v[116:119]
	v_mfma_f32_16x16x32_bf16 v[112:115], v[174:177], v[146:149], v[112:115]
	v_mfma_f32_16x16x32_bf16 v[108:111], v[182:185], v[128:131], v[108:111]
	v_mfma_f32_16x16x32_bf16 v[104:107], v[182:185], v[146:149], v[104:107]
	v_mfma_f32_16x16x32_bf16 v[124:127], v[170:173], v[132:135], v[124:127]
	v_mfma_f32_16x16x32_bf16 v[120:123], v[170:173], v[162:165], v[120:123]
	v_mfma_f32_16x16x32_bf16 v[116:119], v[178:181], v[132:135], v[116:119]
	v_mfma_f32_16x16x32_bf16 v[112:115], v[178:181], v[162:165], v[112:115]
	v_mfma_f32_16x16x32_bf16 v[108:111], v[186:189], v[132:135], v[108:111]
	v_mfma_f32_16x16x32_bf16 v[104:107], v[186:189], v[162:165], v[104:107]
	v_mfma_f32_16x16x32_bf16 v[100:103], v[190:193], v[128:131], v[100:103]
	v_mfma_f32_16x16x32_bf16 v[96:99], v[190:193], v[146:149], v[96:99]
	v_mfma_f32_16x16x32_bf16 v[100:103], v[196:199], v[132:135], v[100:103]
	v_mfma_f32_16x16x32_bf16 v[96:99], v[196:199], v[162:165], v[96:99]
	s_setprio 0
	s_barrier
; #define WAIT_V(n) asm volatile("s_waitcnt vmcnt(" #n ")" ::: "memory")
; #define WAIT_L(n) asm volatile("s_waitcnt lgkmcnt(" #n ")" ::: "memory")
; #define BAR __builtin_amdgcn_s_barrier()
; template <int EPI>
; __device__ __forceinline__ void gemm_tile(const Params& p, const bf16* __restrict__ A, const bf16* __restrict__ Bt, const int K,
;                                           const int nt, const int brow, const int bcol, int pm, int pn) {
;     ...
;     LDB(B1, 0, 1); BAR; WAIT_L(0); MMA(0, 1, At, B1); BAR;
;     LDA(At, 0, 1); WAIT_V(4); BAR; WAIT_L(0); MMA(1, 0, At, B0); MMA(1, 1, At, B1); BAR; }
;   { LDB(B0, 1, 0); LDA(At, 1, 0); WAIT_V(2); BAR; WAIT_L(0); MMA(0, 0, At, B0); BAR;
	ds_read_b128 v[200:203], v152
	ds_read_b128 v[208:211], v152 offset:1024
	ds_read_b128 v[212:215], v152 offset:2048
	ds_read_b128 v[150:153], v152 offset:3072
	s_setprio 1
	s_barrier
	s_waitcnt lgkmcnt(0)
	s_waitcnt lgkmcnt(0)
	v_mfma_f32_16x16x32_bf16 v[92:95], v[166:169], v[200:203], v[92:95]
	v_mfma_f32_16x16x32_bf16 v[88:91], v[166:169], v[212:215], v[88:91]
	v_mfma_f32_16x16x32_bf16 v[68:71], v[190:193], v[200:203], v[68:71]
	v_mfma_f32_16x16x32_bf16 v[92:95], v[170:173], v[208:211], v[92:95]
	v_mfma_f32_16x16x32_bf16 v[88:91], v[170:173], v[150:153], v[88:91]
	v_mfma_f32_16x16x32_bf16 v[84:87], v[174:177], v[200:203], v[84:87]
	v_mfma_f32_16x16x32_bf16 v[80:83], v[174:177], v[212:215], v[80:83]
	v_mfma_f32_16x16x32_bf16 v[76:79], v[182:185], v[200:203], v[76:79]
	v_mfma_f32_16x16x32_bf16 v[72:75], v[182:185], v[212:215], v[72:75]
	v_mfma_f32_16x16x32_bf16 v[68:71], v[196:199], v[208:211], v[68:71]
	v_mfma_f32_16x16x32_bf16 v[64:67], v[190:193], v[212:215], v[64:67]
	v_mfma_f32_16x16x32_bf16 v[166:169], v[178:181], v[208:211], v[84:87]
	v_mfma_f32_16x16x32_bf16 v[170:173], v[178:181], v[150:153], v[80:83]
	v_mfma_f32_16x16x32_bf16 v[174:177], v[186:189], v[208:211], v[76:79]
	v_mfma_f32_16x16x32_bf16 v[178:181], v[186:189], v[150:153], v[72:75]
	v_mfma_f32_16x16x32_bf16 v[182:185], v[196:199], v[150:153], v[64:67]
	s_setprio 0
	s_barrier
	s_nop 0
	ds_read_b128 v[64:67], v141 offset:16384
	ds_read_b128 v[72:75], v141 offset:17408
	ds_read_b128 v[76:79], v155 offset:16384
	ds_read_b128 v[80:83], v155 offset:17408
	ds_read_b128 v[84:87], v156 offset:16384
	ds_read_b128 v[186:189], v156 offset:17408
	ds_read_b128 v[190:193], v157 offset:16384
	ds_read_b128 v[196:199], v157 offset:17408
	s_waitcnt vmcnt(4)
	s_setprio 1
	s_barrier
	s_waitcnt lgkmcnt(0)
	s_waitcnt lgkmcnt(0)
	v_mfma_f32_16x16x32_bf16 v[60:63], v[64:67], v[128:131], v[60:63]
	v_mfma_f32_16x16x32_bf16 v[52:55], v[76:79], v[128:131], v[52:55]
	v_mfma_f32_16x16x32_bf16 v[44:47], v[84:87], v[128:131], v[44:47]
	v_mfma_f32_16x16x32_bf16 v[36:39], v[190:193], v[128:131], v[36:39]
	v_mfma_f32_16x16x32_bf16 v[32:35], v[190:193], v[146:149], v[32:35]
	v_mfma_f32_16x16x32_bf16 v[60:63], v[72:75], v[132:135], v[60:63]
	v_mfma_f32_16x16x32_bf16 v[56:59], v[64:67], v[146:149], v[56:59]
	v_mfma_f32_16x16x32_bf16 v[52:55], v[80:83], v[132:135], v[52:55]
	v_mfma_f32_16x16x32_bf16 v[48:51], v[76:79], v[146:149], v[48:51]
	v_mfma_f32_16x16x32_bf16 v[44:47], v[186:189], v[132:135], v[44:47]
	v_mfma_f32_16x16x32_bf16 v[40:43], v[84:87], v[146:149], v[40:43]
	v_mfma_f32_16x16x32_bf16 v[36:39], v[196:199], v[132:135], v[36:39]
	v_mfma_f32_16x16x32_bf16 v[32:35], v[196:199], v[162:165], v[32:35]
	v_mfma_f32_16x16x32_bf16 v[216:219], v[72:75], v[162:165], v[56:59]
	v_mfma_f32_16x16x32_bf16 v[220:223], v[80:83], v[162:165], v[48:51]
	v_mfma_f32_16x16x32_bf16 v[224:227], v[186:189], v[162:165], v[40:43]
	s_setprio 0
	s_setprio 1
	v_mfma_f32_16x16x32_bf16 v[28:31], v[64:67], v[200:203], v[28:31]
	v_mfma_f32_16x16x32_bf16 v[24:27], v[64:67], v[212:215], v[24:27]
	v_mfma_f32_16x16x32_bf16 v[20:23], v[76:79], v[200:203], v[20:23]
	v_mfma_f32_16x16x32_bf16 v[16:19], v[76:79], v[212:215], v[16:19]
	v_mfma_f32_16x16x32_bf16 v[4:7], v[190:193], v[200:203], v[4:7]
	v_mfma_f32_16x16x32_bf16 v[28:31], v[72:75], v[208:211], v[28:31]
	v_mfma_f32_16x16x32_bf16 v[24:27], v[72:75], v[150:153], v[24:27]
	v_mfma_f32_16x16x32_bf16 v[20:23], v[80:83], v[208:211], v[20:23]
	v_mfma_f32_16x16x32_bf16 v[16:19], v[80:83], v[150:153], v[16:19]
	v_mfma_f32_16x16x32_bf16 v[12:15], v[84:87], v[200:203], v[12:15]
	v_mfma_f32_16x16x32_bf16 v[8:11], v[84:87], v[212:215], v[8:11]
	v_mfma_f32_16x16x32_bf16 v[4:7], v[196:199], v[208:211], v[4:7]
	v_mfma_f32_16x16x32_bf16 v[0:3], v[190:193], v[212:215], v[0:3]
	v_mfma_f32_16x16x32_bf16 v[146:149], v[186:189], v[208:211], v[12:15]
	v_mfma_f32_16x16x32_bf16 v[162:165], v[186:189], v[150:153], v[8:11]
	v_mfma_f32_16x16x32_bf16 v[150:153], v[196:199], v[150:153], v[0:3]
	s_setprio 0
	s_barrier
	s_nop 2
	ds_read_b128 v[0:3], v145
	ds_read_b128 v[8:11], v145 offset:1024
	ds_read_b128 v[12:15], v145 offset:2048
	ds_read_b128 v[186:189], v145 offset:3072
	ds_read_b128 v[40:43], v141 offset:32768
	ds_read_b128 v[48:51], v141 offset:33792
	ds_read_b128 v[56:59], v155 offset:32768
	ds_read_b128 v[64:67], v155 offset:33792
	ds_read_b128 v[190:193], v156 offset:32768
	ds_read_b128 v[196:199], v156 offset:33792
	ds_read_b128 v[200:203], v157 offset:32768
	ds_read_b128 v[208:211], v157 offset:33792
	s_waitcnt vmcnt(2)
	s_setprio 1
	s_barrier
; #define WAIT_V(n) asm volatile("s_waitcnt vmcnt(" #n ")" ::: "memory")
; #define WAIT_L(n) asm volatile("s_waitcnt lgkmcnt(" #n ")" ::: "memory")
; #define BAR __builtin_amdgcn_s_barrier()
; template <int EPI>
; __device__ __forceinline__ void gemm_tile(const Params& p, const bf16* __restrict__ A, const bf16* __restrict__ Bt, const int K,
;                                           const int nt, const int brow, const int bcol, int pm, int pn) {
;     ...
;   { LDB(B0, 1, 0); LDA(At, 1, 0); WAIT_V(2); BAR; WAIT_L(0); MMA(0, 0, At, B0); BAR;
;     LDB(B1, 1, 1); WAIT_V(0); BAR; WAIT_L(0); MMA(0, 1, At, B1); BAR;
;     LDA(At, 1, 1); BAR; WAIT_L(0); MMA(1, 0, At, B0); MMA(1, 1, At, B1); BAR; }
;   if (wr == 0) BAR;
	s_waitcnt lgkmcnt(0)
	s_waitcnt lgkmcnt(0)
	v_mfma_f32_16x16x32_bf16 v[72:75], v[40:43], v[0:3], v[124:127]
	v_mfma_f32_16x16x32_bf16 v[80:83], v[48:51], v[8:11], v[72:75]
	v_mfma_f32_16x16x32_bf16 v[72:75], v[40:43], v[12:15], v[120:123]
	v_mfma_f32_16x16x32_bf16 v[132:135], v[48:51], v[186:189], v[72:75]
	v_mfma_f32_16x16x32_bf16 v[72:75], v[56:59], v[0:3], v[116:119]
	v_mfma_f32_16x16x32_bf16 v[84:87], v[64:67], v[8:11], v[72:75]
	v_mfma_f32_16x16x32_bf16 v[72:75], v[56:59], v[12:15], v[112:115]
	v_mfma_f32_16x16x32_bf16 v[128:131], v[64:67], v[186:189], v[72:75]
	v_mfma_f32_16x16x32_bf16 v[72:75], v[190:193], v[0:3], v[108:111]
	v_mfma_f32_16x16x32_bf16 v[120:123], v[196:199], v[8:11], v[72:75]
	v_mfma_f32_16x16x32_bf16 v[72:75], v[190:193], v[12:15], v[104:107]
	v_mfma_f32_16x16x32_bf16 v[124:127], v[196:199], v[186:189], v[72:75]
	v_mfma_f32_16x16x32_bf16 v[72:75], v[200:203], v[0:3], v[100:103]
	v_mfma_f32_16x16x32_bf16 v[116:119], v[208:211], v[8:11], v[72:75]
	v_mfma_f32_16x16x32_bf16 v[72:75], v[200:203], v[12:15], v[96:99]
	v_mfma_f32_16x16x32_bf16 v[112:115], v[208:211], v[186:189], v[72:75]
	s_setprio 0
	s_barrier
	ds_read_b128 v[96:99], v142
	ds_read_b128 v[100:103], v142 offset:1024
	ds_read_b128 v[212:215], v142 offset:2048
	ds_read_b128 v[142:145], v142 offset:3072
	s_waitcnt vmcnt(0)
	s_setprio 1
	s_barrier
	s_waitcnt lgkmcnt(0)
	s_waitcnt lgkmcnt(0)
	v_mfma_f32_16x16x32_bf16 v[72:75], v[40:43], v[96:99], v[92:95]
	v_mfma_f32_16x16x32_bf16 v[40:43], v[40:43], v[212:215], v[88:91]
	v_mfma_f32_16x16x32_bf16 v[108:111], v[48:51], v[142:145], v[40:43]
	v_mfma_f32_16x16x32_bf16 v[40:43], v[56:59], v[96:99], v[166:169]
	v_mfma_f32_16x16x32_bf16 v[76:79], v[64:67], v[100:103], v[40:43]
	v_mfma_f32_16x16x32_bf16 v[40:43], v[56:59], v[212:215], v[170:173]
	v_mfma_f32_16x16x32_bf16 v[104:107], v[64:67], v[142:145], v[40:43]
	v_mfma_f32_16x16x32_bf16 v[40:43], v[190:193], v[96:99], v[174:177]
	v_mfma_f32_16x16x32_bf16 v[92:95], v[196:199], v[100:103], v[40:43]
	v_mfma_f32_16x16x32_bf16 v[40:43], v[190:193], v[212:215], v[178:181]
	v_mfma_f32_16x16x32_bf16 v[64:67], v[196:199], v[142:145], v[40:43]
	v_mfma_f32_16x16x32_bf16 v[40:43], v[200:203], v[96:99], v[68:71]
	v_mfma_f32_16x16x32_bf16 v[88:91], v[208:211], v[100:103], v[40:43]
	v_mfma_f32_16x16x32_bf16 v[40:43], v[200:203], v[212:215], v[182:185]
	v_mfma_f32_16x16x32_bf16 v[72:75], v[48:51], v[100:103], v[72:75]
	v_mfma_f32_16x16x32_bf16 v[68:71], v[208:211], v[142:145], v[40:43]
	s_setprio 0
	s_barrier
	ds_read_b128 v[166:169], v141 offset:49152
	ds_read_b128 v[170:173], v141 offset:50176
	ds_read_b128 v[174:177], v155 offset:49152
	ds_read_b128 v[178:181], v155 offset:50176
	ds_read_b128 v[182:185], v156 offset:49152
	ds_read_b128 v[190:193], v156 offset:50176
	ds_read_b128 v[196:199], v157 offset:49152
	ds_read_b128 v[154:157], v157 offset:50176
	s_setprio 1
	s_barrier
	s_waitcnt lgkmcnt(0)
	s_waitcnt lgkmcnt(0)
	v_mfma_f32_16x16x32_bf16 v[40:43], v[166:169], v[0:3], v[60:63]
	v_mfma_f32_16x16x32_bf16 v[56:59], v[170:173], v[8:11], v[40:43]
	v_mfma_f32_16x16x32_bf16 v[40:43], v[166:169], v[12:15], v[216:219]
	v_mfma_f32_16x16x32_bf16 v[60:63], v[170:173], v[186:189], v[40:43]
	v_mfma_f32_16x16x32_bf16 v[40:43], v[174:177], v[0:3], v[52:55]
	v_mfma_f32_16x16x32_bf16 v[48:51], v[178:181], v[8:11], v[40:43]
	v_mfma_f32_16x16x32_bf16 v[40:43], v[174:177], v[12:15], v[220:223]
	v_mfma_f32_16x16x32_bf16 v[52:55], v[178:181], v[186:189], v[40:43]
	v_mfma_f32_16x16x32_bf16 v[40:43], v[182:185], v[0:3], v[44:47]
	v_mfma_f32_16x16x32_bf16 v[0:3], v[196:199], v[0:3], v[36:39]
	v_mfma_f32_16x16x32_bf16 v[44:47], v[182:185], v[12:15], v[224:227]
	v_mfma_f32_16x16x32_bf16 v[36:39], v[154:157], v[8:11], v[0:3]
	v_mfma_f32_16x16x32_bf16 v[0:3], v[196:199], v[12:15], v[32:35]
	v_mfma_f32_16x16x32_bf16 v[40:43], v[190:193], v[8:11], v[40:43]
	v_mfma_f32_16x16x32_bf16 v[44:47], v[190:193], v[186:189], v[44:47]
	v_mfma_f32_16x16x32_bf16 v[32:35], v[154:157], v[186:189], v[0:3]
	s_setprio 0
	s_setprio 1
	v_mfma_f32_16x16x32_bf16 v[0:3], v[166:169], v[96:99], v[28:31]
	v_mfma_f32_16x16x32_bf16 v[8:11], v[170:173], v[100:103], v[0:3]
	v_mfma_f32_16x16x32_bf16 v[0:3], v[166:169], v[212:215], v[24:27]
	v_mfma_f32_16x16x32_bf16 v[28:31], v[170:173], v[142:145], v[0:3]
	v_mfma_f32_16x16x32_bf16 v[0:3], v[174:177], v[96:99], v[20:23]
	v_mfma_f32_16x16x32_bf16 v[12:15], v[178:181], v[100:103], v[0:3]
	v_mfma_f32_16x16x32_bf16 v[0:3], v[174:177], v[212:215], v[16:19]
	v_mfma_f32_16x16x32_bf16 v[24:27], v[178:181], v[142:145], v[0:3]
	v_mfma_f32_16x16x32_bf16 v[0:3], v[182:185], v[96:99], v[146:149]
	v_mfma_f32_16x16x32_bf16 v[4:7], v[196:199], v[96:99], v[4:7]
	v_mfma_f32_16x16x32_bf16 v[20:23], v[190:193], v[100:103], v[0:3]
	v_mfma_f32_16x16x32_bf16 v[0:3], v[182:185], v[212:215], v[162:165]
	v_mfma_f32_16x16x32_bf16 v[16:19], v[154:157], v[100:103], v[4:7]
	v_mfma_f32_16x16x32_bf16 v[4:7], v[196:199], v[212:215], v[150:153]
	v_mfma_f32_16x16x32_bf16 v[0:3], v[190:193], v[142:145], v[0:3]
	v_mfma_f32_16x16x32_bf16 v[4:7], v[154:157], v[142:145], v[4:7]
	s_setprio 0
	s_cmpk_gt_u32 s94, 0xff
	s_barrier
	s_cbranch_scc1 .LBB0_1565
	s_barrier

; #define WAIT_L(n) asm volatile("s_waitcnt lgkmcnt(" #n ")" ::: "memory")
; #define BAR __builtin_amdgcn_s_barrier()
; #define SCHED __builtin_amdgcn_sched_barrier(0)
; template <int EPI>
; __device__ __forceinline__ void gemm_tile(const Params& p, const bf16* __restrict__ A, const bf16* __restrict__ Bt, const int K,
;                                           const int nt, const int brow, const int bcol, int pm, int pn) {
;     ...
;     LDB(B0, 0, 0); SCHED; LDA(At, 0, 0); STAGE(SA(1, 1), A, brow + HALF, t + 1);
;     WAIT_L(8); BAR; WAIT_L(0); MMA(0, 0, At, B0); BAR; SCHED;
;     LDB(B1, 0, 1); STAGE(SB(0, 0), Bt, bcol, t + 2);
;     BAR; WAIT_L(0); MMA(0, 1, At, B1); BAR;
;     LDA(At, 0, 1); STAGE(SA(0, 0), A, brow, t + 2);
;     BAR; WAIT_L(0); MMA(1, 0, At, B0); BAR; SCHED;
.LBB0_1690:
	ds_read_b128 v[156:159], v153
	ds_read_b128 v[160:163], v153 offset:1024
	ds_read_b128 v[164:167], v153 offset:2048
	ds_read_b128 v[168:171], v153 offset:3072
	v_readfirstlane_b32 s42, v154
	v_lshl_add_u64 v[192:193], v[130:131], 0, s[6:7]
	s_mov_b32 m0, s42
	v_readfirstlane_b32 s42, v155
	ds_read_b128 v[172:175], v135
	ds_read_b128 v[176:179], v135 offset:1024
	ds_read_b128 v[180:183], v134
	ds_read_b128 v[184:187], v134 offset:1024
	ds_read_b128 v[188:191], v133
	ds_read_b128 v[196:199], v133 offset:1024
	ds_read_b128 v[200:203], v132
	ds_read_b128 v[208:211], v132 offset:1024
	global_load_lds_dwordx4 v[192:193], off
	v_lshl_add_u64 v[192:193], v[130:131], 0, s[8:9]
	s_mov_b32 m0, s42
	s_nop 0
	global_load_lds_dwordx4 v[192:193], off
	s_waitcnt lgkmcnt(8)
	s_setprio 1
	s_barrier
	s_waitcnt lgkmcnt(0)
	s_waitcnt lgkmcnt(0)
	v_mfma_f32_16x16x32_bf16 v[124:127], v[172:175], v[156:159], v[124:127]
	v_mfma_f32_16x16x32_bf16 v[120:123], v[172:175], v[164:167], v[120:123]
	v_mfma_f32_16x16x32_bf16 v[116:119], v[180:183], v[156:159], v[116:119]
	v_mfma_f32_16x16x32_bf16 v[112:115], v[180:183], v[164:167], v[112:115]
	v_mfma_f32_16x16x32_bf16 v[108:111], v[188:191], v[156:159], v[108:111]
	v_mfma_f32_16x16x32_bf16 v[104:107], v[188:191], v[164:167], v[104:107]
	v_mfma_f32_16x16x32_bf16 v[100:103], v[200:203], v[156:159], v[100:103]
	v_mfma_f32_16x16x32_bf16 v[96:99], v[200:203], v[164:167], v[96:99]
	v_mfma_f32_16x16x32_bf16 v[124:127], v[176:179], v[160:163], v[124:127]
	v_mfma_f32_16x16x32_bf16 v[120:123], v[176:179], v[168:171], v[120:123]
	v_mfma_f32_16x16x32_bf16 v[116:119], v[184:187], v[160:163], v[116:119]
	v_mfma_f32_16x16x32_bf16 v[112:115], v[184:187], v[168:171], v[112:115]
	v_mfma_f32_16x16x32_bf16 v[108:111], v[196:199], v[160:163], v[108:111]
	v_mfma_f32_16x16x32_bf16 v[104:107], v[196:199], v[168:171], v[104:107]
	v_mfma_f32_16x16x32_bf16 v[100:103], v[208:211], v[160:163], v[100:103]
	v_mfma_f32_16x16x32_bf16 v[96:99], v[208:211], v[168:171], v[96:99]
	s_setprio 0
	s_barrier
	v_lshl_add_u64 v[192:193], v[130:131], 0, s[4:5]
	v_readfirstlane_b32 s42, v137
	v_lshl_add_u64 v[204:205], v[192:193], 0, s[10:11]
	s_mov_b32 m0, s42
	v_readfirstlane_b32 s42, v138
	ds_read_b128 v[212:215], v152
	ds_read_b128 v[216:219], v152 offset:1024
	ds_read_b128 v[220:223], v152 offset:2048
	ds_read_b128 v[224:227], v152 offset:3072
	global_load_lds_dwordx4 v[204:205], off
	v_lshl_add_u64 v[204:205], v[192:193], 0, s[12:13]
	s_mov_b32 m0, s42
	s_nop 0
	global_load_lds_dwordx4 v[204:205], off
	s_setprio 1
	s_barrier
	s_waitcnt lgkmcnt(0)
	s_waitcnt lgkmcnt(0)
	v_mfma_f32_16x16x32_bf16 v[92:95], v[172:175], v[212:215], v[92:95]
	v_mfma_f32_16x16x32_bf16 v[88:91], v[172:175], v[220:223], v[88:91]
	v_mfma_f32_16x16x32_bf16 v[84:87], v[180:183], v[212:215], v[84:87]
	v_mfma_f32_16x16x32_bf16 v[80:83], v[180:183], v[220:223], v[80:83]
	v_mfma_f32_16x16x32_bf16 v[76:79], v[188:191], v[212:215], v[76:79]
	v_mfma_f32_16x16x32_bf16 v[72:75], v[188:191], v[220:223], v[72:75]
	v_mfma_f32_16x16x32_bf16 v[68:71], v[200:203], v[212:215], v[68:71]
	v_mfma_f32_16x16x32_bf16 v[64:67], v[200:203], v[220:223], v[64:67]
	v_mfma_f32_16x16x32_bf16 v[92:95], v[176:179], v[216:219], v[92:95]
	v_mfma_f32_16x16x32_bf16 v[88:91], v[176:179], v[224:227], v[88:91]
	v_mfma_f32_16x16x32_bf16 v[84:87], v[184:187], v[216:219], v[84:87]
	v_mfma_f32_16x16x32_bf16 v[80:83], v[184:187], v[224:227], v[80:83]
	v_mfma_f32_16x16x32_bf16 v[76:79], v[196:199], v[216:219], v[76:79]
	v_mfma_f32_16x16x32_bf16 v[72:75], v[196:199], v[224:227], v[72:75]
	v_mfma_f32_16x16x32_bf16 v[68:71], v[208:211], v[216:219], v[68:71]
	v_mfma_f32_16x16x32_bf16 v[64:67], v[208:211], v[224:227], v[64:67]
	s_setprio 0
	v_readfirstlane_b32 s42, v136
	v_lshl_add_u64 v[204:205], v[130:131], 0, s[14:15]
	s_mov_b32 m0, s42
	v_readfirstlane_b32 s42, v139
	s_barrier
	ds_read_b128 v[172:175], v135 offset:16384
	ds_read_b128 v[176:179], v135 offset:17408
	ds_read_b128 v[180:183], v134 offset:16384
	ds_read_b128 v[184:187], v134 offset:17408
	ds_read_b128 v[188:191], v133 offset:16384
	ds_read_b128 v[196:199], v133 offset:17408
	ds_read_b128 v[200:203], v132 offset:16384
	ds_read_b128 v[208:211], v132 offset:17408
	global_load_lds_dwordx4 v[204:205], off
	v_lshl_add_u64 v[204:205], v[130:131], 0, s[16:17]
	s_mov_b32 m0, s42
	s_nop 0
	global_load_lds_dwordx4 v[204:205], off
	s_setprio 1
	s_barrier
	s_waitcnt lgkmcnt(0)
	s_waitcnt lgkmcnt(0)
	v_mfma_f32_16x16x32_bf16 v[60:63], v[172:175], v[156:159], v[60:63]
	v_mfma_f32_16x16x32_bf16 v[56:59], v[172:175], v[164:167], v[56:59]
	v_mfma_f32_16x16x32_bf16 v[52:55], v[180:183], v[156:159], v[52:55]
	v_mfma_f32_16x16x32_bf16 v[48:51], v[180:183], v[164:167], v[48:51]
	v_mfma_f32_16x16x32_bf16 v[44:47], v[188:191], v[156:159], v[44:47]
	v_mfma_f32_16x16x32_bf16 v[40:43], v[188:191], v[164:167], v[40:43]
	v_mfma_f32_16x16x32_bf16 v[36:39], v[200:203], v[156:159], v[36:39]
	v_mfma_f32_16x16x32_bf16 v[32:35], v[200:203], v[164:167], v[32:35]
	v_mfma_f32_16x16x32_bf16 v[60:63], v[176:179], v[160:163], v[60:63]
	v_mfma_f32_16x16x32_bf16 v[56:59], v[176:179], v[168:171], v[56:59]
	v_mfma_f32_16x16x32_bf16 v[52:55], v[184:187], v[160:163], v[52:55]
	v_mfma_f32_16x16x32_bf16 v[48:51], v[184:187], v[168:171], v[48:51]
	v_mfma_f32_16x16x32_bf16 v[44:47], v[196:199], v[160:163], v[44:47]
	v_mfma_f32_16x16x32_bf16 v[40:43], v[196:199], v[168:171], v[40:43]
	v_mfma_f32_16x16x32_bf16 v[36:39], v[208:211], v[160:163], v[36:39]
	v_mfma_f32_16x16x32_bf16 v[32:35], v[208:211], v[168:171], v[32:35]
	s_setprio 0
	s_barrier
; #define WAIT_V(n) asm volatile("s_waitcnt vmcnt(" #n ")" ::: "memory")
; #define WAIT_L(n) asm volatile("s_waitcnt lgkmcnt(" #n ")" ::: "memory")
; #define BAR __builtin_amdgcn_s_barrier()
; #define SCHED __builtin_amdgcn_sched_barrier(0)
; template <int EPI>
; __device__ __forceinline__ void gemm_tile(const Params& p, const bf16* __restrict__ A, const bf16* __restrict__ Bt, const int K,
;                                           const int nt, const int brow, const int bcol, int pm, int pn) {
;     ...
;   for (int t = 0; t < nt - 2; t += 2) {
;     LDB(B0, 0, 0); SCHED; LDA(At, 0, 0); STAGE(SA(1, 1), A, brow + HALF, t + 1);
;     WAIT_L(8); BAR; WAIT_L(0); MMA(0, 0, At, B0); BAR; SCHED;
;     LDB(B1, 0, 1); STAGE(SB(0, 0), Bt, bcol, t + 2);
;     BAR; WAIT_L(0); MMA(0, 1, At, B1); BAR;
;     LDA(At, 0, 1); STAGE(SA(0, 0), A, brow, t + 2);
;     BAR; WAIT_L(0); MMA(1, 0, At, B0); BAR; SCHED;
;     STAGE(SB(0, 1), Bt, bcol + HALF, t + 2);
;     WAIT_V(6); BAR; MMA(1, 1, At, B1); BAR;
;     LDB(B0, 1, 0); SCHED; LDA(At, 1, 0); STAGE(SA(0, 1), A, brow + HALF, t + 2);
;     WAIT_L(8); BAR; WAIT_L(0); MMA(0, 0, At, B0); BAR; SCHED;
;     LDB(B1, 1, 1); STAGE(SB(1, 0), Bt, bcol, t + 3);
;     BAR; WAIT_L(0); MMA(0, 1, At, B1); BAR;
;     LDA(At, 1, 1); STAGE(SA(1, 0), A, brow, t + 3);
;     BAR; WAIT_L(0); MMA(1, 0, At, B0); BAR; SCHED;
;     STAGE(SB(1, 1), Bt, bcol + HALF, t + 3);
;     WAIT_V(6); BAR; MMA(1, 1, At, B1); BAR;
;   }
	v_readfirstlane_b32 s42, v140
	v_lshl_add_u64 v[156:157], v[192:193], 0, s[18:19]
	s_mov_b32 m0, s42
	v_readfirstlane_b32 s42, v142
	global_load_lds_dwordx4 v[156:157], off
	v_lshl_add_u64 v[156:157], v[192:193], 0, s[20:21]
	s_mov_b32 m0, s42
	s_nop 0
	global_load_lds_dwordx4 v[156:157], off
	s_waitcnt vmcnt(6)
	s_setprio 1
	s_barrier
	v_mfma_f32_16x16x32_bf16 v[28:31], v[172:175], v[212:215], v[28:31]
	v_mfma_f32_16x16x32_bf16 v[24:27], v[172:175], v[220:223], v[24:27]
	v_mfma_f32_16x16x32_bf16 v[20:23], v[180:183], v[212:215], v[20:23]
	v_mfma_f32_16x16x32_bf16 v[16:19], v[180:183], v[220:223], v[16:19]
	v_mfma_f32_16x16x32_bf16 v[12:15], v[188:191], v[212:215], v[12:15]
	v_mfma_f32_16x16x32_bf16 v[8:11], v[188:191], v[220:223], v[8:11]
	v_mfma_f32_16x16x32_bf16 v[4:7], v[200:203], v[212:215], v[4:7]
	v_mfma_f32_16x16x32_bf16 v[0:3], v[200:203], v[220:223], v[0:3]
	v_mfma_f32_16x16x32_bf16 v[28:31], v[176:179], v[216:219], v[28:31]
	v_mfma_f32_16x16x32_bf16 v[24:27], v[176:179], v[224:227], v[24:27]
	v_mfma_f32_16x16x32_bf16 v[20:23], v[184:187], v[216:219], v[20:23]
	v_mfma_f32_16x16x32_bf16 v[16:19], v[184:187], v[224:227], v[16:19]
	v_mfma_f32_16x16x32_bf16 v[12:15], v[196:199], v[216:219], v[12:15]
	v_mfma_f32_16x16x32_bf16 v[8:11], v[196:199], v[224:227], v[8:11]
	v_mfma_f32_16x16x32_bf16 v[4:7], v[208:211], v[216:219], v[4:7]
	v_mfma_f32_16x16x32_bf16 v[0:3], v[208:211], v[224:227], v[0:3]
	s_setprio 0
	s_barrier
	ds_read_b128 v[156:159], v145
	ds_read_b128 v[160:163], v145 offset:1024
	ds_read_b128 v[164:167], v145 offset:2048
	ds_read_b128 v[168:171], v145 offset:3072
	v_readfirstlane_b32 s42, v143
	v_lshl_add_u64 v[204:205], v[130:131], 0, s[22:23]
	s_mov_b32 m0, s42
	v_readfirstlane_b32 s42, v144
	ds_read_b128 v[172:175], v135 offset:32768
	ds_read_b128 v[176:179], v135 offset:33792
	ds_read_b128 v[180:183], v134 offset:32768
	ds_read_b128 v[184:187], v134 offset:33792
	ds_read_b128 v[188:191], v133 offset:32768
	ds_read_b128 v[196:199], v133 offset:33792
	ds_read_b128 v[200:203], v132 offset:32768
	ds_read_b128 v[208:211], v132 offset:33792
	global_load_lds_dwordx4 v[204:205], off
	s_mov_b32 m0, s42
	s_nop 0
	global_load_lds_dwordx4 v[130:131], off
	s_waitcnt lgkmcnt(8)
	s_setprio 1
	s_barrier
	s_waitcnt lgkmcnt(0)
	s_waitcnt lgkmcnt(0)
	v_mfma_f32_16x16x32_bf16 v[124:127], v[172:175], v[156:159], v[124:127]
	v_mfma_f32_16x16x32_bf16 v[120:123], v[172:175], v[164:167], v[120:123]
	v_mfma_f32_16x16x32_bf16 v[116:119], v[180:183], v[156:159], v[116:119]
	v_mfma_f32_16x16x32_bf16 v[112:115], v[180:183], v[164:167], v[112:115]
	v_mfma_f32_16x16x32_bf16 v[108:111], v[188:191], v[156:159], v[108:111]
	v_mfma_f32_16x16x32_bf16 v[104:107], v[188:191], v[164:167], v[104:107]
	v_mfma_f32_16x16x32_bf16 v[100:103], v[200:203], v[156:159], v[100:103]
	v_mfma_f32_16x16x32_bf16 v[96:99], v[200:203], v[164:167], v[96:99]
	v_mfma_f32_16x16x32_bf16 v[124:127], v[176:179], v[160:163], v[124:127]
	v_mfma_f32_16x16x32_bf16 v[120:123], v[176:179], v[168:171], v[120:123]
	v_mfma_f32_16x16x32_bf16 v[116:119], v[184:187], v[160:163], v[116:119]
	v_mfma_f32_16x16x32_bf16 v[112:115], v[184:187], v[168:171], v[112:115]
	v_mfma_f32_16x16x32_bf16 v[108:111], v[196:199], v[160:163], v[108:111]
	v_mfma_f32_16x16x32_bf16 v[104:107], v[196:199], v[168:171], v[104:107]
	v_mfma_f32_16x16x32_bf16 v[100:103], v[208:211], v[160:163], v[100:103]
	v_mfma_f32_16x16x32_bf16 v[96:99], v[208:211], v[168:171], v[96:99]
	s_setprio 0
	s_barrier
	v_readfirstlane_b32 s42, v146
	v_lshl_add_u64 v[204:205], v[192:193], 0, s[24:25]
	s_mov_b32 m0, s42
	v_readfirstlane_b32 s42, v147
	ds_read_b128 v[212:215], v141
	ds_read_b128 v[216:219], v141 offset:1024
	ds_read_b128 v[220:223], v141 offset:2048
	ds_read_b128 v[224:227], v141 offset:3072
	global_load_lds_dwordx4 v[204:205], off
	v_lshl_add_u64 v[204:205], v[192:193], 0, s[26:27]
	s_mov_b32 m0, s42
	s_nop 0
	global_load_lds_dwordx4 v[204:205], off
	s_setprio 1
	s_barrier
	s_waitcnt lgkmcnt(0)
	s_waitcnt lgkmcnt(0)
	v_mfma_f32_16x16x32_bf16 v[92:95], v[172:175], v[212:215], v[92:95]
	v_mfma_f32_16x16x32_bf16 v[88:91], v[172:175], v[220:223], v[88:91]
	v_mfma_f32_16x16x32_bf16 v[84:87], v[180:183], v[212:215], v[84:87]
	v_mfma_f32_16x16x32_bf16 v[80:83], v[180:183], v[220:223], v[80:83]
	v_mfma_f32_16x16x32_bf16 v[76:79], v[188:191], v[212:215], v[76:79]
	v_mfma_f32_16x16x32_bf16 v[72:75], v[188:191], v[220:223], v[72:75]
	v_mfma_f32_16x16x32_bf16 v[68:71], v[200:203], v[212:215], v[68:71]
	v_mfma_f32_16x16x32_bf16 v[64:67], v[200:203], v[220:223], v[64:67]
	v_mfma_f32_16x16x32_bf16 v[92:95], v[176:179], v[216:219], v[92:95]
	v_mfma_f32_16x16x32_bf16 v[88:91], v[176:179], v[224:227], v[88:91]
	v_mfma_f32_16x16x32_bf16 v[84:87], v[184:187], v[216:219], v[84:87]
	v_mfma_f32_16x16x32_bf16 v[80:83], v[184:187], v[224:227], v[80:83]
	v_mfma_f32_16x16x32_bf16 v[76:79], v[196:199], v[216:219], v[76:79]
	v_mfma_f32_16x16x32_bf16 v[72:75], v[196:199], v[224:227], v[72:75]
	v_mfma_f32_16x16x32_bf16 v[68:71], v[208:211], v[216:219], v[68:71]
	v_mfma_f32_16x16x32_bf16 v[64:67], v[208:211], v[224:227], v[64:67]
	s_setprio 0
	v_readfirstlane_b32 s42, v148
	v_lshl_add_u64 v[204:205], v[130:131], 0, s[28:29]
	s_mov_b32 m0, s42
	v_readfirstlane_b32 s42, v149
	s_barrier
	ds_read_b128 v[172:175], v135 offset:49152
	ds_read_b128 v[176:179], v135 offset:50176
	ds_read_b128 v[180:183], v134 offset:49152
	ds_read_b128 v[184:187], v134 offset:50176
	ds_read_b128 v[188:191], v133 offset:49152
	ds_read_b128 v[196:199], v133 offset:50176
	ds_read_b128 v[200:203], v132 offset:49152
	ds_read_b128 v[208:211], v132 offset:50176
	global_load_lds_dwordx4 v[204:205], off
	v_lshl_add_u64 v[204:205], v[130:131], 0, s[30:31]
	s_mov_b32 m0, s42
	s_nop 0
	global_load_lds_dwordx4 v[204:205], off
	s_setprio 1
	s_barrier
; #define WAIT_V(n) asm volatile("s_waitcnt vmcnt(" #n ")" ::: "memory")
; #define WAIT_L(n) asm volatile("s_waitcnt lgkmcnt(" #n ")" ::: "memory")
; #define BAR __builtin_amdgcn_s_barrier()
; #define SCHED __builtin_amdgcn_sched_barrier(0)
; template <int EPI>
; __device__ __forceinline__ void gemm_tile(const Params& p, const bf16* __restrict__ A, const bf16* __restrict__ Bt, const int K,
;                                           const int nt, const int brow, const int bcol, int pm, int pn) {
;     ...
;     WAIT_V(6); BAR; MMA(1, 1, At, B1); BAR;
;     LDB(B0, 1, 0); SCHED; LDA(At, 1, 0); STAGE(SA(0, 1), A, brow + HALF, t + 2);
;     WAIT_L(8); BAR; WAIT_L(0); MMA(0, 0, At, B0); BAR; SCHED;
;     LDB(B1, 1, 1); STAGE(SB(1, 0), Bt, bcol, t + 3);
;     BAR; WAIT_L(0); MMA(0, 1, At, B1); BAR;
;     LDA(At, 1, 1); STAGE(SA(1, 0), A, brow, t + 3);
;     BAR; WAIT_L(0); MMA(1, 0, At, B0); BAR; SCHED;
;     STAGE(SB(1, 1), Bt, bcol + HALF, t + 3);
;     WAIT_V(6); BAR; MMA(1, 1, At, B1); BAR;
;   }
;   { LDB(B0, 0, 0); LDA(At, 0, 0); STAGE(SA(1, 1), A, brow + HALF, nt - 1);
;     BAR; WAIT_L(0); MMA(0, 0, At, B0); BAR;
;     LDB(B1, 0, 1); BAR; WAIT_L(0); MMA(0, 1, At, B1); BAR;
	s_waitcnt lgkmcnt(0)
	s_waitcnt lgkmcnt(0)
	v_mfma_f32_16x16x32_bf16 v[60:63], v[172:175], v[156:159], v[60:63]
	v_mfma_f32_16x16x32_bf16 v[56:59], v[172:175], v[164:167], v[56:59]
	v_mfma_f32_16x16x32_bf16 v[52:55], v[180:183], v[156:159], v[52:55]
	v_mfma_f32_16x16x32_bf16 v[48:51], v[180:183], v[164:167], v[48:51]
	v_mfma_f32_16x16x32_bf16 v[44:47], v[188:191], v[156:159], v[44:47]
	v_mfma_f32_16x16x32_bf16 v[40:43], v[188:191], v[164:167], v[40:43]
	v_mfma_f32_16x16x32_bf16 v[36:39], v[200:203], v[156:159], v[36:39]
	v_mfma_f32_16x16x32_bf16 v[32:35], v[200:203], v[164:167], v[32:35]
	v_mfma_f32_16x16x32_bf16 v[60:63], v[176:179], v[160:163], v[60:63]
	v_mfma_f32_16x16x32_bf16 v[56:59], v[176:179], v[168:171], v[56:59]
	v_mfma_f32_16x16x32_bf16 v[52:55], v[184:187], v[160:163], v[52:55]
	v_mfma_f32_16x16x32_bf16 v[48:51], v[184:187], v[168:171], v[48:51]
	v_mfma_f32_16x16x32_bf16 v[44:47], v[196:199], v[160:163], v[44:47]
	v_mfma_f32_16x16x32_bf16 v[40:43], v[196:199], v[168:171], v[40:43]
	v_mfma_f32_16x16x32_bf16 v[36:39], v[208:211], v[160:163], v[36:39]
	v_mfma_f32_16x16x32_bf16 v[32:35], v[208:211], v[168:171], v[32:35]
	s_setprio 0
	s_barrier
	v_readfirstlane_b32 s42, v150
	v_lshl_add_u64 v[156:157], v[192:193], 0, s[34:35]
	s_mov_b32 m0, s42
	v_readfirstlane_b32 s42, v151
	global_load_lds_dwordx4 v[156:157], off
	v_lshl_add_u64 v[156:157], v[192:193], 0, s[36:37]
	s_mov_b32 m0, s42
	s_nop 0
	global_load_lds_dwordx4 v[156:157], off
	s_waitcnt vmcnt(6)
	s_setprio 1
	s_barrier
	v_mfma_f32_16x16x32_bf16 v[28:31], v[172:175], v[212:215], v[28:31]
	v_mfma_f32_16x16x32_bf16 v[24:27], v[172:175], v[220:223], v[24:27]
	v_mfma_f32_16x16x32_bf16 v[20:23], v[180:183], v[212:215], v[20:23]
	v_mfma_f32_16x16x32_bf16 v[16:19], v[180:183], v[220:223], v[16:19]
	v_mfma_f32_16x16x32_bf16 v[12:15], v[188:191], v[212:215], v[12:15]
	v_mfma_f32_16x16x32_bf16 v[8:11], v[188:191], v[220:223], v[8:11]
	v_mfma_f32_16x16x32_bf16 v[4:7], v[200:203], v[212:215], v[4:7]
	v_mfma_f32_16x16x32_bf16 v[0:3], v[200:203], v[220:223], v[0:3]
	v_mfma_f32_16x16x32_bf16 v[28:31], v[176:179], v[216:219], v[28:31]
	v_mfma_f32_16x16x32_bf16 v[24:27], v[176:179], v[224:227], v[24:27]
	v_mfma_f32_16x16x32_bf16 v[20:23], v[184:187], v[216:219], v[20:23]
	v_mfma_f32_16x16x32_bf16 v[16:19], v[184:187], v[224:227], v[16:19]
	v_mfma_f32_16x16x32_bf16 v[12:15], v[196:199], v[216:219], v[12:15]
	v_mfma_f32_16x16x32_bf16 v[8:11], v[196:199], v[224:227], v[8:11]
	v_mfma_f32_16x16x32_bf16 v[4:7], v[208:211], v[216:219], v[4:7]
	v_mfma_f32_16x16x32_bf16 v[0:3], v[208:211], v[224:227], v[0:3]
	s_setprio 0
	s_add_i32 s41, s41, 2
	s_cmp_lt_u32 s41, 4
	v_lshl_add_u64 v[130:131], v[130:131], 0, s[38:39]
	s_barrier
	s_cbranch_scc1 .LBB0_1690
	s_mov_b64 s[4:5], 0xb160380
	v_add_u32_e32 v137, 0xc000, v136
	v_lshl_add_u64 v[130:131], v[128:129], 0, s[4:5]
	v_readfirstlane_b32 s4, v137
	s_mov_b32 m0, s4
	ds_read_b128 v[146:149], v153
	ds_read_b128 v[154:157], v153 offset:1024
	ds_read_b128 v[158:161], v153 offset:2048
	ds_read_b128 v[162:165], v153 offset:3072
	ds_read_b128 v[166:169], v135
	ds_read_b128 v[170:173], v135 offset:1024
	ds_read_b128 v[174:177], v134
	ds_read_b128 v[178:181], v134 offset:1024
	ds_read_b128 v[182:185], v133
	ds_read_b128 v[186:189], v133 offset:1024
	ds_read_b128 v[190:193], v132
	ds_read_b128 v[196:199], v132 offset:1024
	global_load_lds_dwordx4 v[130:131], off
	s_mov_b64 s[4:5], 0xb210380
	v_add_u32_e32 v130, 0xe000, v136
	v_lshl_add_u64 v[128:129], v[128:129], 0, s[4:5]
	v_readfirstlane_b32 s4, v130
	s_mov_b32 m0, s4
	s_nop 0
	global_load_lds_dwordx4 v[128:129], off
	s_setprio 1
	s_barrier
	s_waitcnt lgkmcnt(0)
	s_waitcnt lgkmcnt(0)
	v_mfma_f32_16x16x32_bf16 v[124:127], v[166:169], v[146:149], v[124:127]
	v_mfma_f32_16x16x32_bf16 v[120:123], v[166:169], v[158:161], v[120:123]
	v_mfma_f32_16x16x32_bf16 v[108:111], v[182:185], v[146:149], v[108:111]
	v_mfma_f32_16x16x32_bf16 v[100:103], v[190:193], v[146:149], v[100:103]
	v_mfma_f32_16x16x32_bf16 v[124:127], v[170:173], v[154:157], v[124:127]
	v_mfma_f32_16x16x32_bf16 v[120:123], v[170:173], v[162:165], v[120:123]
	v_mfma_f32_16x16x32_bf16 v[116:119], v[174:177], v[146:149], v[116:119]
	v_mfma_f32_16x16x32_bf16 v[112:115], v[174:177], v[158:161], v[112:115]
	v_mfma_f32_16x16x32_bf16 v[108:111], v[186:189], v[154:157], v[108:111]
	v_mfma_f32_16x16x32_bf16 v[104:107], v[182:185], v[158:161], v[104:107]
	v_mfma_f32_16x16x32_bf16 v[100:103], v[196:199], v[154:157], v[100:103]
	v_mfma_f32_16x16x32_bf16 v[96:99], v[190:193], v[158:161], v[96:99]
	v_mfma_f32_16x16x32_bf16 v[128:131], v[178:181], v[154:157], v[116:119]
	v_mfma_f32_16x16x32_bf16 v[136:139], v[178:181], v[162:165], v[112:115]
	v_mfma_f32_16x16x32_bf16 v[200:203], v[186:189], v[162:165], v[104:107]
	v_mfma_f32_16x16x32_bf16 v[208:211], v[196:199], v[162:165], v[96:99]
	s_setprio 0
	s_barrier
	s_nop 1
	ds_read_b128 v[96:99], v152
	ds_read_b128 v[104:107], v152 offset:1024
	ds_read_b128 v[112:115], v152 offset:2048
	ds_read_b128 v[116:119], v152 offset:3072
	s_setprio 1
	s_barrier
; #define WAIT_V(n) asm volatile("s_waitcnt vmcnt(" #n ")" ::: "memory")
; #define WAIT_L(n) asm volatile("s_waitcnt lgkmcnt(" #n ")" ::: "memory")
; #define BAR __builtin_amdgcn_s_barrier()
; template <int EPI>
; __device__ __forceinline__ void gemm_tile(const Params& p, const bf16* __restrict__ A, const bf16* __restrict__ Bt, const int K,
;                                           const int nt, const int brow, const int bcol, int pm, int pn) {
;     ...
;   { LDB(B0, 0, 0); LDA(At, 0, 0); STAGE(SA(1, 1), A, brow + HALF, nt - 1);
;     BAR; WAIT_L(0); MMA(0, 0, At, B0); BAR;
;     LDB(B1, 0, 1); BAR; WAIT_L(0); MMA(0, 1, At, B1); BAR;
;     LDA(At, 0, 1); WAIT_V(4); BAR; WAIT_L(0); MMA(1, 0, At, B0); MMA(1, 1, At, B1); BAR; }
;   { LDB(B0, 1, 0); LDA(At, 1, 0); WAIT_V(2); BAR; WAIT_L(0); MMA(0, 0, At, B0); BAR;
;     LDB(B1, 1, 1); WAIT_V(0); BAR; WAIT_L(0); MMA(0, 1, At, B1); BAR;
	s_waitcnt lgkmcnt(0)
	s_waitcnt lgkmcnt(0)
	v_mfma_f32_16x16x32_bf16 v[92:95], v[166:169], v[96:99], v[92:95]
	v_mfma_f32_16x16x32_bf16 v[88:91], v[166:169], v[112:115], v[88:91]
	v_mfma_f32_16x16x32_bf16 v[84:87], v[174:177], v[96:99], v[84:87]
	v_mfma_f32_16x16x32_bf16 v[76:79], v[182:185], v[96:99], v[76:79]
	v_mfma_f32_16x16x32_bf16 v[92:95], v[170:173], v[104:107], v[92:95]
	v_mfma_f32_16x16x32_bf16 v[88:91], v[170:173], v[116:119], v[88:91]
	v_mfma_f32_16x16x32_bf16 v[84:87], v[178:181], v[104:107], v[84:87]
	v_mfma_f32_16x16x32_bf16 v[80:83], v[174:177], v[112:115], v[80:83]
	v_mfma_f32_16x16x32_bf16 v[76:79], v[186:189], v[104:107], v[76:79]
	v_mfma_f32_16x16x32_bf16 v[72:75], v[182:185], v[112:115], v[72:75]
	v_mfma_f32_16x16x32_bf16 v[68:71], v[190:193], v[96:99], v[68:71]
	v_mfma_f32_16x16x32_bf16 v[64:67], v[190:193], v[112:115], v[64:67]
	v_mfma_f32_16x16x32_bf16 v[150:153], v[178:181], v[116:119], v[80:83]
	v_mfma_f32_16x16x32_bf16 v[166:169], v[186:189], v[116:119], v[72:75]
	v_mfma_f32_16x16x32_bf16 v[170:173], v[196:199], v[104:107], v[68:71]
	v_mfma_f32_16x16x32_bf16 v[174:177], v[196:199], v[116:119], v[64:67]
	s_setprio 0
	s_barrier
	s_nop 1
	ds_read_b128 v[64:67], v135 offset:16384
	ds_read_b128 v[68:71], v135 offset:17408
	ds_read_b128 v[72:75], v134 offset:16384
	ds_read_b128 v[80:83], v134 offset:17408
	ds_read_b128 v[178:181], v133 offset:16384
	ds_read_b128 v[182:185], v133 offset:17408
	ds_read_b128 v[186:189], v132 offset:16384
	ds_read_b128 v[190:193], v132 offset:17408
	s_waitcnt vmcnt(4)
	s_setprio 1
	s_barrier
	s_waitcnt lgkmcnt(0)
	s_waitcnt lgkmcnt(0)
	v_mfma_f32_16x16x32_bf16 v[60:63], v[64:67], v[146:149], v[60:63]
	v_mfma_f32_16x16x32_bf16 v[56:59], v[64:67], v[158:161], v[56:59]
	v_mfma_f32_16x16x32_bf16 v[52:55], v[72:75], v[146:149], v[52:55]
	v_mfma_f32_16x16x32_bf16 v[44:47], v[178:181], v[146:149], v[44:47]
	v_mfma_f32_16x16x32_bf16 v[60:63], v[68:71], v[154:157], v[60:63]
	v_mfma_f32_16x16x32_bf16 v[56:59], v[68:71], v[162:165], v[56:59]
	v_mfma_f32_16x16x32_bf16 v[52:55], v[80:83], v[154:157], v[52:55]
	v_mfma_f32_16x16x32_bf16 v[48:51], v[72:75], v[158:161], v[48:51]
	v_mfma_f32_16x16x32_bf16 v[44:47], v[182:185], v[154:157], v[44:47]
	v_mfma_f32_16x16x32_bf16 v[40:43], v[178:181], v[158:161], v[40:43]
	v_mfma_f32_16x16x32_bf16 v[36:39], v[186:189], v[146:149], v[36:39]
	v_mfma_f32_16x16x32_bf16 v[32:35], v[186:189], v[158:161], v[32:35]
	v_mfma_f32_16x16x32_bf16 v[196:199], v[80:83], v[162:165], v[48:51]
	v_mfma_f32_16x16x32_bf16 v[212:215], v[182:185], v[162:165], v[40:43]
	v_mfma_f32_16x16x32_bf16 v[146:149], v[190:193], v[154:157], v[36:39]
	v_mfma_f32_16x16x32_bf16 v[154:157], v[190:193], v[162:165], v[32:35]
	s_setprio 0
	s_setprio 1
	v_mfma_f32_16x16x32_bf16 v[28:31], v[64:67], v[96:99], v[28:31]
	v_mfma_f32_16x16x32_bf16 v[24:27], v[64:67], v[112:115], v[24:27]
	v_mfma_f32_16x16x32_bf16 v[20:23], v[72:75], v[96:99], v[20:23]
	v_mfma_f32_16x16x32_bf16 v[12:15], v[178:181], v[96:99], v[12:15]
	v_mfma_f32_16x16x32_bf16 v[28:31], v[68:71], v[104:107], v[28:31]
	v_mfma_f32_16x16x32_bf16 v[24:27], v[68:71], v[116:119], v[24:27]
	v_mfma_f32_16x16x32_bf16 v[20:23], v[80:83], v[104:107], v[20:23]
	v_mfma_f32_16x16x32_bf16 v[16:19], v[72:75], v[112:115], v[16:19]
	v_mfma_f32_16x16x32_bf16 v[12:15], v[182:185], v[104:107], v[12:15]
	v_mfma_f32_16x16x32_bf16 v[8:11], v[178:181], v[112:115], v[8:11]
	v_mfma_f32_16x16x32_bf16 v[4:7], v[186:189], v[96:99], v[4:7]
	v_mfma_f32_16x16x32_bf16 v[0:3], v[186:189], v[112:115], v[0:3]
	v_mfma_f32_16x16x32_bf16 v[158:161], v[80:83], v[116:119], v[16:19]
	v_mfma_f32_16x16x32_bf16 v[162:165], v[182:185], v[116:119], v[8:11]
	v_mfma_f32_16x16x32_bf16 v[178:181], v[190:193], v[104:107], v[4:7]
	v_mfma_f32_16x16x32_bf16 v[182:185], v[190:193], v[116:119], v[0:3]
	s_setprio 0
	s_barrier
	s_nop 1
	ds_read_b128 v[0:3], v145
	ds_read_b128 v[4:7], v145 offset:1024
	ds_read_b128 v[8:11], v145 offset:2048
	ds_read_b128 v[16:19], v145 offset:3072
	ds_read_b128 v[32:35], v135 offset:32768
	ds_read_b128 v[36:39], v135 offset:33792
	ds_read_b128 v[40:43], v134 offset:32768
	ds_read_b128 v[48:51], v134 offset:33792
	ds_read_b128 v[142:145], v133 offset:32768
	ds_read_b128 v[186:189], v133 offset:33792
	ds_read_b128 v[190:193], v132 offset:32768
	ds_read_b128 v[216:219], v132 offset:33792
	s_waitcnt vmcnt(2)
	s_setprio 1
	s_barrier
; #define WAIT_V(n) asm volatile("s_waitcnt vmcnt(" #n ")" ::: "memory")
; #define WAIT_L(n) asm volatile("s_waitcnt lgkmcnt(" #n ")" ::: "memory")
; #define BAR __builtin_amdgcn_s_barrier()
; template <int EPI>
; __device__ __forceinline__ void gemm_tile(const Params& p, const bf16* __restrict__ A, const bf16* __restrict__ Bt, const int K,
;                                           const int nt, const int brow, const int bcol, int pm, int pn) {
;     ...
;     LDA(At, 0, 1); WAIT_V(4); BAR; WAIT_L(0); MMA(1, 0, At, B0); MMA(1, 1, At, B1); BAR; }
;   { LDB(B0, 1, 0); LDA(At, 1, 0); WAIT_V(2); BAR; WAIT_L(0); MMA(0, 0, At, B0); BAR;
;     LDB(B1, 1, 1); WAIT_V(0); BAR; WAIT_L(0); MMA(0, 1, At, B1); BAR;
;     LDA(At, 1, 1); BAR; WAIT_L(0); MMA(1, 0, At, B0); MMA(1, 1, At, B1); BAR; }
;   if (wr == 0) BAR;
	s_waitcnt lgkmcnt(0)
	s_waitcnt lgkmcnt(0)
	v_mfma_f32_16x16x32_bf16 v[64:67], v[32:35], v[0:3], v[124:127]
	v_mfma_f32_16x16x32_bf16 v[116:119], v[36:39], v[4:7], v[64:67]
	v_mfma_f32_16x16x32_bf16 v[64:67], v[32:35], v[8:11], v[120:123]
	v_mfma_f32_16x16x32_bf16 v[124:127], v[36:39], v[16:19], v[64:67]
	v_mfma_f32_16x16x32_bf16 v[64:67], v[40:43], v[0:3], v[128:131]
	v_mfma_f32_16x16x32_bf16 v[112:115], v[48:51], v[4:7], v[64:67]
	v_mfma_f32_16x16x32_bf16 v[64:67], v[40:43], v[8:11], v[136:139]
	v_mfma_f32_16x16x32_bf16 v[120:123], v[48:51], v[16:19], v[64:67]
	v_mfma_f32_16x16x32_bf16 v[64:67], v[142:145], v[0:3], v[108:111]
	v_mfma_f32_16x16x32_bf16 v[104:107], v[186:189], v[4:7], v[64:67]
	v_mfma_f32_16x16x32_bf16 v[64:67], v[142:145], v[8:11], v[200:203]
	v_mfma_f32_16x16x32_bf16 v[108:111], v[186:189], v[16:19], v[64:67]
	v_mfma_f32_16x16x32_bf16 v[64:67], v[190:193], v[0:3], v[100:103]
	v_mfma_f32_16x16x32_bf16 v[96:99], v[216:219], v[4:7], v[64:67]
	v_mfma_f32_16x16x32_bf16 v[64:67], v[190:193], v[8:11], v[208:211]
	v_mfma_f32_16x16x32_bf16 v[100:103], v[216:219], v[16:19], v[64:67]
	s_setprio 0
	s_barrier
	ds_read_b128 v[128:131], v141
	ds_read_b128 v[136:139], v141 offset:1024
	ds_read_b128 v[200:203], v141 offset:2048
	ds_read_b128 v[208:211], v141 offset:3072
	s_waitcnt vmcnt(0)
	s_setprio 1
	s_barrier
	s_waitcnt lgkmcnt(0)
	s_waitcnt lgkmcnt(0)
	v_mfma_f32_16x16x32_bf16 v[64:67], v[32:35], v[128:131], v[92:95]
	v_mfma_f32_16x16x32_bf16 v[32:35], v[32:35], v[200:203], v[88:91]
	v_mfma_f32_16x16x32_bf16 v[80:83], v[36:39], v[208:211], v[32:35]
	v_mfma_f32_16x16x32_bf16 v[32:35], v[40:43], v[128:131], v[84:87]
	v_mfma_f32_16x16x32_bf16 v[68:71], v[48:51], v[136:139], v[32:35]
	v_mfma_f32_16x16x32_bf16 v[32:35], v[40:43], v[200:203], v[150:153]
	v_mfma_f32_16x16x32_bf16 v[84:87], v[48:51], v[208:211], v[32:35]
	v_mfma_f32_16x16x32_bf16 v[32:35], v[142:145], v[128:131], v[76:79]
	v_mfma_f32_16x16x32_bf16 v[72:75], v[186:189], v[136:139], v[32:35]
	v_mfma_f32_16x16x32_bf16 v[32:35], v[142:145], v[200:203], v[166:169]
	v_mfma_f32_16x16x32_bf16 v[88:91], v[186:189], v[208:211], v[32:35]
	v_mfma_f32_16x16x32_bf16 v[32:35], v[190:193], v[128:131], v[170:173]
	v_mfma_f32_16x16x32_bf16 v[76:79], v[216:219], v[136:139], v[32:35]
	v_mfma_f32_16x16x32_bf16 v[32:35], v[190:193], v[200:203], v[174:177]
	v_mfma_f32_16x16x32_bf16 v[64:67], v[36:39], v[136:139], v[64:67]
	v_mfma_f32_16x16x32_bf16 v[92:95], v[216:219], v[208:211], v[32:35]
	s_setprio 0
	s_barrier
	ds_read_b128 v[140:143], v135 offset:49152
	ds_read_b128 v[150:153], v135 offset:50176
	ds_read_b128 v[166:169], v134 offset:49152
	ds_read_b128 v[170:173], v134 offset:50176
	ds_read_b128 v[174:177], v133 offset:49152
	ds_read_b128 v[186:189], v133 offset:50176
	ds_read_b128 v[190:193], v132 offset:49152
	ds_read_b128 v[132:135], v132 offset:50176
	s_setprio 1
	s_barrier
	s_waitcnt lgkmcnt(0)
	s_waitcnt lgkmcnt(0)
	v_mfma_f32_16x16x32_bf16 v[36:39], v[140:143], v[8:11], v[56:59]
	v_mfma_f32_16x16x32_bf16 v[40:43], v[166:169], v[8:11], v[196:199]
	v_mfma_f32_16x16x32_bf16 v[32:35], v[140:143], v[0:3], v[60:63]
	v_mfma_f32_16x16x32_bf16 v[48:51], v[150:153], v[16:19], v[36:39]
	v_mfma_f32_16x16x32_bf16 v[36:39], v[166:169], v[0:3], v[52:55]
	v_mfma_f32_16x16x32_bf16 v[52:55], v[170:173], v[16:19], v[40:43]
	v_mfma_f32_16x16x32_bf16 v[40:43], v[174:177], v[0:3], v[44:47]
	v_mfma_f32_16x16x32_bf16 v[44:47], v[174:177], v[8:11], v[212:215]
	v_mfma_f32_16x16x32_bf16 v[0:3], v[190:193], v[0:3], v[146:149]
	v_mfma_f32_16x16x32_bf16 v[56:59], v[186:189], v[16:19], v[44:47]
	v_mfma_f32_16x16x32_bf16 v[44:47], v[132:135], v[4:7], v[0:3]
	v_mfma_f32_16x16x32_bf16 v[0:3], v[190:193], v[8:11], v[154:157]
	v_mfma_f32_16x16x32_bf16 v[32:35], v[150:153], v[4:7], v[32:35]
	v_mfma_f32_16x16x32_bf16 v[36:39], v[170:173], v[4:7], v[36:39]
	v_mfma_f32_16x16x32_bf16 v[40:43], v[186:189], v[4:7], v[40:43]
	v_mfma_f32_16x16x32_bf16 v[60:63], v[132:135], v[16:19], v[0:3]
	s_setprio 0
	s_setprio 1
	v_mfma_f32_16x16x32_bf16 v[4:7], v[140:143], v[200:203], v[24:27]
	v_mfma_f32_16x16x32_bf16 v[8:11], v[166:169], v[200:203], v[158:161]
	v_mfma_f32_16x16x32_bf16 v[16:19], v[150:153], v[208:211], v[4:7]
	v_mfma_f32_16x16x32_bf16 v[4:7], v[166:169], v[128:131], v[20:23]
	v_mfma_f32_16x16x32_bf16 v[20:23], v[170:173], v[208:211], v[8:11]
	v_mfma_f32_16x16x32_bf16 v[8:11], v[174:177], v[128:131], v[12:15]
	v_mfma_f32_16x16x32_bf16 v[12:15], v[174:177], v[200:203], v[162:165]
	v_mfma_f32_16x16x32_bf16 v[0:3], v[140:143], v[128:131], v[28:31]
	v_mfma_f32_16x16x32_bf16 v[24:27], v[186:189], v[208:211], v[12:15]
	v_mfma_f32_16x16x32_bf16 v[12:15], v[190:193], v[128:131], v[178:181]
	v_mfma_f32_16x16x32_bf16 v[28:31], v[190:193], v[200:203], v[182:185]
	v_mfma_f32_16x16x32_bf16 v[0:3], v[150:153], v[136:139], v[0:3]
	v_mfma_f32_16x16x32_bf16 v[4:7], v[170:173], v[136:139], v[4:7]
	v_mfma_f32_16x16x32_bf16 v[8:11], v[186:189], v[136:139], v[8:11]
	v_mfma_f32_16x16x32_bf16 v[12:15], v[132:135], v[136:139], v[12:15]
	v_mfma_f32_16x16x32_bf16 v[28:31], v[132:135], v[208:211], v[28:31]
	s_setprio 0
	s_cmpk_gt_u32 s40, 0xff
	s_barrier
	s_cbranch_scc1 .LBB0_1693
	s_barrier

; #define WAIT_V(n) asm volatile("s_waitcnt vmcnt(" #n ")" ::: "memory")
; #define WAIT_L(n) asm volatile("s_waitcnt lgkmcnt(" #n ")" ::: "memory")
; #define BAR __builtin_amdgcn_s_barrier()
; #define SCHED __builtin_amdgcn_sched_barrier(0)
; template <int EPI>
; __device__ __forceinline__ void gemm_tile(const Params& p, const bf16* __restrict__ A, const bf16* __restrict__ Bt, const int K,
;                                           const int nt, const int brow, const int bcol, int pm, int pn) {
;     ...
;   for (int t = 0; t < nt - 2; t += 2) {
;     LDB(B0, 0, 0); SCHED; LDA(At, 0, 0); STAGE(SA(1, 1), A, brow + HALF, t + 1);
;     WAIT_L(8); BAR; WAIT_L(0); MMA(0, 0, At, B0); BAR; SCHED;
;     LDB(B1, 0, 1); STAGE(SB(0, 0), Bt, bcol, t + 2);
;     BAR; WAIT_L(0); MMA(0, 1, At, B1); BAR;
;     LDA(At, 0, 1); STAGE(SA(0, 0), A, brow, t + 2);
;     BAR; WAIT_L(0); MMA(1, 0, At, B0); BAR; SCHED;
;     STAGE(SB(0, 1), Bt, bcol + HALF, t + 2);
;     WAIT_V(6); BAR; MMA(1, 1, At, B1); BAR;
;     LDB(B0, 1, 0); SCHED; LDA(At, 1, 0); STAGE(SA(0, 1), A, brow + HALF, t + 2);
;     WAIT_L(8); BAR; WAIT_L(0); MMA(0, 0, At, B0); BAR; SCHED;
;     LDB(B1, 1, 1); STAGE(SB(1, 0), Bt, bcol, t + 3);
;     BAR; WAIT_L(0); MMA(0, 1, At, B1); BAR;
;     LDA(At, 1, 1); STAGE(SA(1, 0), A, brow, t + 3);
;     BAR; WAIT_L(0); MMA(1, 0, At, B0); BAR; SCHED;
;     STAGE(SB(1, 1), Bt, bcol + HALF, t + 3);
;     WAIT_V(6); BAR; MMA(1, 1, At, B1); BAR;
;   }
.LBB0_1704:
	ds_read_b128 v[158:161], v155
	ds_read_b128 v[162:165], v155 offset:1024
	ds_read_b128 v[166:169], v155 offset:2048
	ds_read_b128 v[170:173], v155 offset:3072
	v_lshl_add_u64 v[204:205], s[70:71], 0, v[130:131]
	s_mov_b64 s[84:85], 0x12662080
	v_lshl_add_u64 v[212:213], v[204:205], 0, s[84:85]
	v_readfirstlane_b32 s84, v154
	s_mov_b32 m0, s84
	s_mov_b64 s[84:85], 0x12712080
	ds_read_b128 v[174:177], v137
	ds_read_b128 v[178:181], v137 offset:1024
	ds_read_b128 v[182:185], v136
	ds_read_b128 v[186:189], v136 offset:1024
	ds_read_b128 v[190:193], v135
	ds_read_b128 v[196:199], v135 offset:1024
	ds_read_b128 v[200:203], v133
	ds_read_b128 v[208:211], v133 offset:1024
	global_load_lds_dwordx4 v[212:213], off
	v_lshl_add_u64 v[212:213], v[204:205], 0, s[84:85]
	v_readfirstlane_b32 s84, v153
	s_mov_b32 m0, s84
	s_nop 0
	global_load_lds_dwordx4 v[212:213], off
	s_waitcnt lgkmcnt(8)
	s_setprio 1
	s_barrier
	s_waitcnt lgkmcnt(0)
	s_waitcnt lgkmcnt(0)
	v_mfma_f32_16x16x32_bf16 v[124:127], v[174:177], v[158:161], v[124:127]
	v_mfma_f32_16x16x32_bf16 v[120:123], v[174:177], v[166:169], v[120:123]
	v_mfma_f32_16x16x32_bf16 v[116:119], v[182:185], v[158:161], v[116:119]
	v_mfma_f32_16x16x32_bf16 v[112:115], v[182:185], v[166:169], v[112:115]
	v_mfma_f32_16x16x32_bf16 v[108:111], v[190:193], v[158:161], v[108:111]
	v_mfma_f32_16x16x32_bf16 v[104:107], v[190:193], v[166:169], v[104:107]
	v_mfma_f32_16x16x32_bf16 v[100:103], v[200:203], v[158:161], v[100:103]
	v_mfma_f32_16x16x32_bf16 v[96:99], v[200:203], v[166:169], v[96:99]
	v_mfma_f32_16x16x32_bf16 v[124:127], v[178:181], v[162:165], v[124:127]
	v_mfma_f32_16x16x32_bf16 v[120:123], v[178:181], v[170:173], v[120:123]
	v_mfma_f32_16x16x32_bf16 v[116:119], v[186:189], v[162:165], v[116:119]
	v_mfma_f32_16x16x32_bf16 v[112:115], v[186:189], v[170:173], v[112:115]
	v_mfma_f32_16x16x32_bf16 v[108:111], v[196:199], v[162:165], v[108:111]
	v_mfma_f32_16x16x32_bf16 v[104:107], v[196:199], v[170:173], v[104:107]
	v_mfma_f32_16x16x32_bf16 v[100:103], v[208:211], v[162:165], v[100:103]
	v_mfma_f32_16x16x32_bf16 v[96:99], v[208:211], v[170:173], v[96:99]
	s_setprio 0
	s_barrier
	v_lshl_add_u64 v[228:229], s[68:69], 0, v[130:131]
	s_mov_b64 s[84:85], 0x4c00100
	v_lshl_add_u64 v[230:231], v[228:229], 0, s[84:85]
	v_readfirstlane_b32 s84, v132
	s_mov_b32 m0, s84
	s_mov_b64 s[84:85], 0x4cb0100
	ds_read_b128 v[212:215], v151
	ds_read_b128 v[216:219], v151 offset:1024
	ds_read_b128 v[220:223], v151 offset:2048
	ds_read_b128 v[224:227], v151 offset:3072
	global_load_lds_dwordx4 v[230:231], off
	v_lshl_add_u64 v[230:231], v[228:229], 0, s[84:85]
	v_readfirstlane_b32 s84, v134
	s_mov_b32 m0, s84
	s_nop 0
	global_load_lds_dwordx4 v[230:231], off
	s_setprio 1
	s_barrier
	s_waitcnt lgkmcnt(0)
	s_waitcnt lgkmcnt(0)
	v_mfma_f32_16x16x32_bf16 v[92:95], v[174:177], v[212:215], v[92:95]
	v_mfma_f32_16x16x32_bf16 v[88:91], v[174:177], v[220:223], v[88:91]
	v_mfma_f32_16x16x32_bf16 v[84:87], v[182:185], v[212:215], v[84:87]
	v_mfma_f32_16x16x32_bf16 v[80:83], v[182:185], v[220:223], v[80:83]
	v_mfma_f32_16x16x32_bf16 v[76:79], v[190:193], v[212:215], v[76:79]
	v_mfma_f32_16x16x32_bf16 v[72:75], v[190:193], v[220:223], v[72:75]
	v_mfma_f32_16x16x32_bf16 v[68:71], v[200:203], v[212:215], v[68:71]
	v_mfma_f32_16x16x32_bf16 v[64:67], v[200:203], v[220:223], v[64:67]
	v_mfma_f32_16x16x32_bf16 v[92:95], v[178:181], v[216:219], v[92:95]
	v_mfma_f32_16x16x32_bf16 v[88:91], v[178:181], v[224:227], v[88:91]
	v_mfma_f32_16x16x32_bf16 v[84:87], v[186:189], v[216:219], v[84:87]
	v_mfma_f32_16x16x32_bf16 v[80:83], v[186:189], v[224:227], v[80:83]
	v_mfma_f32_16x16x32_bf16 v[76:79], v[196:199], v[216:219], v[76:79]
	v_mfma_f32_16x16x32_bf16 v[72:75], v[196:199], v[224:227], v[72:75]
	v_mfma_f32_16x16x32_bf16 v[68:71], v[208:211], v[216:219], v[68:71]
	v_mfma_f32_16x16x32_bf16 v[64:67], v[208:211], v[224:227], v[64:67]
	s_setprio 0
	s_mov_b64 s[84:85], 0x12502100
	v_lshl_add_u64 v[230:231], v[204:205], 0, s[84:85]
	v_readfirstlane_b32 s84, v138
	s_mov_b32 m0, s84
	s_mov_b64 s[84:85], 0x125b2100
	s_barrier
	ds_read_b128 v[174:177], v137 offset:16384
	ds_read_b128 v[178:181], v137 offset:17408
	ds_read_b128 v[182:185], v136 offset:16384
	ds_read_b128 v[186:189], v136 offset:17408
	ds_read_b128 v[190:193], v135 offset:16384
	ds_read_b128 v[196:199], v135 offset:17408
	ds_read_b128 v[200:203], v133 offset:16384
	ds_read_b128 v[208:211], v133 offset:17408
	global_load_lds_dwordx4 v[230:231], off
	v_lshl_add_u64 v[230:231], v[204:205], 0, s[84:85]
	v_readfirstlane_b32 s84, v139
	s_mov_b32 m0, s84
	s_nop 0
	global_load_lds_dwordx4 v[230:231], off
	s_setprio 1
	s_barrier
	s_waitcnt lgkmcnt(0)
	s_waitcnt lgkmcnt(0)
	v_mfma_f32_16x16x32_bf16 v[60:63], v[174:177], v[158:161], v[60:63]
	v_mfma_f32_16x16x32_bf16 v[56:59], v[174:177], v[166:169], v[56:59]
	v_mfma_f32_16x16x32_bf16 v[52:55], v[182:185], v[158:161], v[52:55]
	v_mfma_f32_16x16x32_bf16 v[48:51], v[182:185], v[166:169], v[48:51]
	v_mfma_f32_16x16x32_bf16 v[44:47], v[190:193], v[158:161], v[44:47]
	v_mfma_f32_16x16x32_bf16 v[40:43], v[190:193], v[166:169], v[40:43]
	v_mfma_f32_16x16x32_bf16 v[36:39], v[200:203], v[158:161], v[36:39]
	v_mfma_f32_16x16x32_bf16 v[32:35], v[200:203], v[166:169], v[32:35]
	v_mfma_f32_16x16x32_bf16 v[60:63], v[178:181], v[162:165], v[60:63]
	v_mfma_f32_16x16x32_bf16 v[56:59], v[178:181], v[170:173], v[56:59]
	v_mfma_f32_16x16x32_bf16 v[52:55], v[186:189], v[162:165], v[52:55]
	v_mfma_f32_16x16x32_bf16 v[48:51], v[186:189], v[170:173], v[48:51]
	v_mfma_f32_16x16x32_bf16 v[44:47], v[196:199], v[162:165], v[44:47]
	v_mfma_f32_16x16x32_bf16 v[40:43], v[196:199], v[170:173], v[40:43]
	v_mfma_f32_16x16x32_bf16 v[36:39], v[208:211], v[162:165], v[36:39]
	v_mfma_f32_16x16x32_bf16 v[32:35], v[208:211], v[170:173], v[32:35]
	s_setprio 0
	s_barrier
; #define WAIT_V(n) asm volatile("s_waitcnt vmcnt(" #n ")" ::: "memory")
; #define WAIT_L(n) asm volatile("s_waitcnt lgkmcnt(" #n ")" ::: "memory")
; #define BAR __builtin_amdgcn_s_barrier()
; #define SCHED __builtin_amdgcn_sched_barrier(0)
; template <int EPI>
; __device__ __forceinline__ void gemm_tile(const Params& p, const bf16* __restrict__ A, const bf16* __restrict__ Bt, const int K,
;                                           const int nt, const int brow, const int bcol, int pm, int pn) {
;     ...
;   for (int t = 0; t < nt - 2; t += 2) {
;     LDB(B0, 0, 0); SCHED; LDA(At, 0, 0); STAGE(SA(1, 1), A, brow + HALF, t + 1);
;     WAIT_L(8); BAR; WAIT_L(0); MMA(0, 0, At, B0); BAR; SCHED;
;     LDB(B1, 0, 1); STAGE(SB(0, 0), Bt, bcol, t + 2);
;     BAR; WAIT_L(0); MMA(0, 1, At, B1); BAR;
;     LDA(At, 0, 1); STAGE(SA(0, 0), A, brow, t + 2);
;     BAR; WAIT_L(0); MMA(1, 0, At, B0); BAR; SCHED;
;     STAGE(SB(0, 1), Bt, bcol + HALF, t + 2);
;     WAIT_V(6); BAR; MMA(1, 1, At, B1); BAR;
;     LDB(B0, 1, 0); SCHED; LDA(At, 1, 0); STAGE(SA(0, 1), A, brow + HALF, t + 2);
;     WAIT_L(8); BAR; WAIT_L(0); MMA(0, 0, At, B0); BAR; SCHED;
;     LDB(B1, 1, 1); STAGE(SB(1, 0), Bt, bcol, t + 3);
;     BAR; WAIT_L(0); MMA(0, 1, At, B1); BAR;
;     LDA(At, 1, 1); STAGE(SA(1, 0), A, brow, t + 3);
;     BAR; WAIT_L(0); MMA(1, 0, At, B0); BAR; SCHED;
;     STAGE(SB(1, 1), Bt, bcol + HALF, t + 3);
;     WAIT_V(6); BAR; MMA(1, 1, At, B1); BAR;
;   }
	s_mov_b64 s[84:85], 0x4d60100
	v_lshl_add_u64 v[158:159], v[228:229], 0, s[84:85]
	v_readfirstlane_b32 s84, v140
	s_mov_b32 m0, s84
	s_mov_b64 s[84:85], 0x4e10100
	global_load_lds_dwordx4 v[158:159], off
	v_lshl_add_u64 v[158:159], v[228:229], 0, s[84:85]
	v_readfirstlane_b32 s84, v141
	s_mov_b32 m0, s84
	s_nop 0
	global_load_lds_dwordx4 v[158:159], off
	s_waitcnt vmcnt(6)
	s_setprio 1
	s_barrier
	v_mfma_f32_16x16x32_bf16 v[28:31], v[174:177], v[212:215], v[28:31]
	v_mfma_f32_16x16x32_bf16 v[24:27], v[174:177], v[220:223], v[24:27]
	v_mfma_f32_16x16x32_bf16 v[20:23], v[182:185], v[212:215], v[20:23]
	v_mfma_f32_16x16x32_bf16 v[16:19], v[182:185], v[220:223], v[16:19]
	v_mfma_f32_16x16x32_bf16 v[12:15], v[190:193], v[212:215], v[12:15]
	v_mfma_f32_16x16x32_bf16 v[8:11], v[190:193], v[220:223], v[8:11]
	v_mfma_f32_16x16x32_bf16 v[4:7], v[200:203], v[212:215], v[4:7]
	v_mfma_f32_16x16x32_bf16 v[0:3], v[200:203], v[220:223], v[0:3]
	v_mfma_f32_16x16x32_bf16 v[28:31], v[178:181], v[216:219], v[28:31]
	v_mfma_f32_16x16x32_bf16 v[24:27], v[178:181], v[224:227], v[24:27]
	v_mfma_f32_16x16x32_bf16 v[20:23], v[186:189], v[216:219], v[20:23]
	v_mfma_f32_16x16x32_bf16 v[16:19], v[186:189], v[224:227], v[16:19]
	v_mfma_f32_16x16x32_bf16 v[12:15], v[196:199], v[216:219], v[12:15]
	v_mfma_f32_16x16x32_bf16 v[8:11], v[196:199], v[224:227], v[8:11]
	v_mfma_f32_16x16x32_bf16 v[4:7], v[208:211], v[216:219], v[4:7]
	v_mfma_f32_16x16x32_bf16 v[0:3], v[208:211], v[224:227], v[0:3]
	s_setprio 0
	s_barrier
	ds_read_b128 v[158:161], v145
	ds_read_b128 v[162:165], v145 offset:1024
	ds_read_b128 v[166:169], v145 offset:2048
	ds_read_b128 v[170:173], v145 offset:3072
	s_mov_b64 s[84:85], 0x12662100
	v_lshl_add_u64 v[212:213], v[204:205], 0, s[84:85]
	v_readfirstlane_b32 s84, v143
	s_mov_b32 m0, s84
	s_mov_b64 s[84:85], 0x12712100
	ds_read_b128 v[174:177], v137 offset:32768
	ds_read_b128 v[178:181], v137 offset:33792
	ds_read_b128 v[182:185], v136 offset:32768
	ds_read_b128 v[186:189], v136 offset:33792
	ds_read_b128 v[190:193], v135 offset:32768
	ds_read_b128 v[196:199], v135 offset:33792
	ds_read_b128 v[200:203], v133 offset:32768
	ds_read_b128 v[208:211], v133 offset:33792
	global_load_lds_dwordx4 v[212:213], off
	v_lshl_add_u64 v[212:213], v[204:205], 0, s[84:85]
	v_readfirstlane_b32 s84, v144
	s_mov_b32 m0, s84
	s_nop 0
	global_load_lds_dwordx4 v[212:213], off
	s_waitcnt lgkmcnt(8)
	s_setprio 1
	s_barrier
	s_waitcnt lgkmcnt(0)
	s_waitcnt lgkmcnt(0)
	v_mfma_f32_16x16x32_bf16 v[124:127], v[174:177], v[158:161], v[124:127]
	v_mfma_f32_16x16x32_bf16 v[120:123], v[174:177], v[166:169], v[120:123]
	v_mfma_f32_16x16x32_bf16 v[116:119], v[182:185], v[158:161], v[116:119]
	v_mfma_f32_16x16x32_bf16 v[112:115], v[182:185], v[166:169], v[112:115]
	v_mfma_f32_16x16x32_bf16 v[108:111], v[190:193], v[158:161], v[108:111]
	v_mfma_f32_16x16x32_bf16 v[104:107], v[190:193], v[166:169], v[104:107]
	v_mfma_f32_16x16x32_bf16 v[100:103], v[200:203], v[158:161], v[100:103]
	v_mfma_f32_16x16x32_bf16 v[96:99], v[200:203], v[166:169], v[96:99]
	v_mfma_f32_16x16x32_bf16 v[124:127], v[178:181], v[162:165], v[124:127]
	v_mfma_f32_16x16x32_bf16 v[120:123], v[178:181], v[170:173], v[120:123]
	v_mfma_f32_16x16x32_bf16 v[116:119], v[186:189], v[162:165], v[116:119]
	v_mfma_f32_16x16x32_bf16 v[112:115], v[186:189], v[170:173], v[112:115]
	v_mfma_f32_16x16x32_bf16 v[108:111], v[196:199], v[162:165], v[108:111]
	v_mfma_f32_16x16x32_bf16 v[104:107], v[196:199], v[170:173], v[104:107]
	v_mfma_f32_16x16x32_bf16 v[100:103], v[208:211], v[162:165], v[100:103]
	v_mfma_f32_16x16x32_bf16 v[96:99], v[208:211], v[170:173], v[96:99]
	s_setprio 0
	s_barrier
	s_mov_b64 s[84:85], 0x4c00180
	v_lshl_add_u64 v[230:231], v[228:229], 0, s[84:85]
	v_readfirstlane_b32 s84, v146
	s_mov_b32 m0, s84
	v_readfirstlane_b32 s84, v147
	ds_read_b128 v[212:215], v142
	ds_read_b128 v[216:219], v142 offset:1024
	ds_read_b128 v[220:223], v142 offset:2048
	ds_read_b128 v[224:227], v142 offset:3072
	global_load_lds_dwordx4 v[230:231], off
	v_lshl_add_u64 v[230:231], v[228:229], 0, s[10:11]
	s_mov_b32 m0, s84
	s_nop 0
	global_load_lds_dwordx4 v[230:231], off
	s_setprio 1
	s_barrier
	s_waitcnt lgkmcnt(0)
	s_waitcnt lgkmcnt(0)
	v_mfma_f32_16x16x32_bf16 v[92:95], v[174:177], v[212:215], v[92:95]
	v_mfma_f32_16x16x32_bf16 v[88:91], v[174:177], v[220:223], v[88:91]
	v_mfma_f32_16x16x32_bf16 v[84:87], v[182:185], v[212:215], v[84:87]
	v_mfma_f32_16x16x32_bf16 v[80:83], v[182:185], v[220:223], v[80:83]
	v_mfma_f32_16x16x32_bf16 v[76:79], v[190:193], v[212:215], v[76:79]
	v_mfma_f32_16x16x32_bf16 v[72:75], v[190:193], v[220:223], v[72:75]
	v_mfma_f32_16x16x32_bf16 v[68:71], v[200:203], v[212:215], v[68:71]
	v_mfma_f32_16x16x32_bf16 v[64:67], v[200:203], v[220:223], v[64:67]
	v_mfma_f32_16x16x32_bf16 v[92:95], v[178:181], v[216:219], v[92:95]
	v_mfma_f32_16x16x32_bf16 v[88:91], v[178:181], v[224:227], v[88:91]
	v_mfma_f32_16x16x32_bf16 v[84:87], v[186:189], v[216:219], v[84:87]
	v_mfma_f32_16x16x32_bf16 v[80:83], v[186:189], v[224:227], v[80:83]
	v_mfma_f32_16x16x32_bf16 v[76:79], v[196:199], v[216:219], v[76:79]
	v_mfma_f32_16x16x32_bf16 v[72:75], v[196:199], v[224:227], v[72:75]
	v_mfma_f32_16x16x32_bf16 v[68:71], v[208:211], v[216:219], v[68:71]
	v_mfma_f32_16x16x32_bf16 v[64:67], v[208:211], v[224:227], v[64:67]
	s_setprio 0
	v_readfirstlane_b32 s84, v148
	v_lshl_add_u64 v[230:231], v[204:205], 0, s[12:13]
	s_mov_b32 m0, s84
	v_readfirstlane_b32 s84, v149
	s_barrier
; #define WAIT_V(n) asm volatile("s_waitcnt vmcnt(" #n ")" ::: "memory")
; #define WAIT_L(n) asm volatile("s_waitcnt lgkmcnt(" #n ")" ::: "memory")
; #define BAR __builtin_amdgcn_s_barrier()
; #define SCHED __builtin_amdgcn_sched_barrier(0)
; template <int EPI>
; __device__ __forceinline__ void gemm_tile(const Params& p, const bf16* __restrict__ A, const bf16* __restrict__ Bt, const int K,
;                                           const int nt, const int brow, const int bcol, int pm, int pn) {
;     ...
;   for (int t = 0; t < nt - 2; t += 2) {
;     LDB(B0, 0, 0); SCHED; LDA(At, 0, 0); STAGE(SA(1, 1), A, brow + HALF, t + 1);
;     WAIT_L(8); BAR; WAIT_L(0); MMA(0, 0, At, B0); BAR; SCHED;
;     LDB(B1, 0, 1); STAGE(SB(0, 0), Bt, bcol, t + 2);
;     BAR; WAIT_L(0); MMA(0, 1, At, B1); BAR;
;     LDA(At, 0, 1); STAGE(SA(0, 0), A, brow, t + 2);
;     BAR; WAIT_L(0); MMA(1, 0, At, B0); BAR; SCHED;
;     STAGE(SB(0, 1), Bt, bcol + HALF, t + 2);
;     WAIT_V(6); BAR; MMA(1, 1, At, B1); BAR;
;     LDB(B0, 1, 0); SCHED; LDA(At, 1, 0); STAGE(SA(0, 1), A, brow + HALF, t + 2);
;     WAIT_L(8); BAR; WAIT_L(0); MMA(0, 0, At, B0); BAR; SCHED;
;     LDB(B1, 1, 1); STAGE(SB(1, 0), Bt, bcol, t + 3);
;     BAR; WAIT_L(0); MMA(0, 1, At, B1); BAR;
;     LDA(At, 1, 1); STAGE(SA(1, 0), A, brow, t + 3);
;     BAR; WAIT_L(0); MMA(1, 0, At, B0); BAR; SCHED;
;     STAGE(SB(1, 1), Bt, bcol + HALF, t + 3);
;     WAIT_V(6); BAR; MMA(1, 1, At, B1); BAR;
;   }
;   { LDB(B0, 0, 0); LDA(At, 0, 0); STAGE(SA(1, 1), A, brow + HALF, nt - 1);
;     BAR; WAIT_L(0); MMA(0, 0, At, B0); BAR;
	ds_read_b128 v[174:177], v137 offset:49152
	ds_read_b128 v[178:181], v137 offset:50176
	ds_read_b128 v[182:185], v136 offset:49152
	ds_read_b128 v[186:189], v136 offset:50176
	ds_read_b128 v[190:193], v135 offset:49152
	ds_read_b128 v[196:199], v135 offset:50176
	ds_read_b128 v[200:203], v133 offset:49152
	ds_read_b128 v[208:211], v133 offset:50176
	global_load_lds_dwordx4 v[230:231], off
	v_lshl_add_u64 v[204:205], v[204:205], 0, s[14:15]
	s_mov_b32 m0, s84
	s_nop 0
	global_load_lds_dwordx4 v[204:205], off
	s_setprio 1
	s_barrier
	s_waitcnt lgkmcnt(0)
	s_waitcnt lgkmcnt(0)
	v_mfma_f32_16x16x32_bf16 v[60:63], v[174:177], v[158:161], v[60:63]
	v_mfma_f32_16x16x32_bf16 v[56:59], v[174:177], v[166:169], v[56:59]
	v_mfma_f32_16x16x32_bf16 v[52:55], v[182:185], v[158:161], v[52:55]
	v_mfma_f32_16x16x32_bf16 v[48:51], v[182:185], v[166:169], v[48:51]
	v_mfma_f32_16x16x32_bf16 v[44:47], v[190:193], v[158:161], v[44:47]
	v_mfma_f32_16x16x32_bf16 v[40:43], v[190:193], v[166:169], v[40:43]
	v_mfma_f32_16x16x32_bf16 v[36:39], v[200:203], v[158:161], v[36:39]
	v_mfma_f32_16x16x32_bf16 v[32:35], v[200:203], v[166:169], v[32:35]
	v_mfma_f32_16x16x32_bf16 v[60:63], v[178:181], v[162:165], v[60:63]
	v_mfma_f32_16x16x32_bf16 v[56:59], v[178:181], v[170:173], v[56:59]
	v_mfma_f32_16x16x32_bf16 v[52:55], v[186:189], v[162:165], v[52:55]
	v_mfma_f32_16x16x32_bf16 v[48:51], v[186:189], v[170:173], v[48:51]
	v_mfma_f32_16x16x32_bf16 v[44:47], v[196:199], v[162:165], v[44:47]
	v_mfma_f32_16x16x32_bf16 v[40:43], v[196:199], v[170:173], v[40:43]
	v_mfma_f32_16x16x32_bf16 v[36:39], v[208:211], v[162:165], v[36:39]
	v_mfma_f32_16x16x32_bf16 v[32:35], v[208:211], v[170:173], v[32:35]
	s_setprio 0
	s_barrier
	v_readfirstlane_b32 s84, v150
	v_lshl_add_u64 v[158:159], v[228:229], 0, s[16:17]
	s_mov_b32 m0, s84
	v_readfirstlane_b32 s84, v152
	global_load_lds_dwordx4 v[158:159], off
	v_lshl_add_u64 v[158:159], v[228:229], 0, s[18:19]
	s_mov_b32 m0, s84
	s_nop 0
	global_load_lds_dwordx4 v[158:159], off
	s_waitcnt vmcnt(6)
	s_setprio 1
	s_barrier
	v_mfma_f32_16x16x32_bf16 v[28:31], v[174:177], v[212:215], v[28:31]
	v_mfma_f32_16x16x32_bf16 v[24:27], v[174:177], v[220:223], v[24:27]
	v_mfma_f32_16x16x32_bf16 v[20:23], v[182:185], v[212:215], v[20:23]
	v_mfma_f32_16x16x32_bf16 v[16:19], v[182:185], v[220:223], v[16:19]
	v_mfma_f32_16x16x32_bf16 v[12:15], v[190:193], v[212:215], v[12:15]
	v_mfma_f32_16x16x32_bf16 v[8:11], v[190:193], v[220:223], v[8:11]
	v_mfma_f32_16x16x32_bf16 v[4:7], v[200:203], v[212:215], v[4:7]
	v_mfma_f32_16x16x32_bf16 v[0:3], v[200:203], v[220:223], v[0:3]
	v_mfma_f32_16x16x32_bf16 v[28:31], v[178:181], v[216:219], v[28:31]
	v_mfma_f32_16x16x32_bf16 v[24:27], v[178:181], v[224:227], v[24:27]
	v_mfma_f32_16x16x32_bf16 v[20:23], v[186:189], v[216:219], v[20:23]
	v_mfma_f32_16x16x32_bf16 v[16:19], v[186:189], v[224:227], v[16:19]
	v_mfma_f32_16x16x32_bf16 v[12:15], v[196:199], v[216:219], v[12:15]
	v_mfma_f32_16x16x32_bf16 v[8:11], v[196:199], v[224:227], v[8:11]
	v_mfma_f32_16x16x32_bf16 v[4:7], v[208:211], v[216:219], v[4:7]
	v_mfma_f32_16x16x32_bf16 v[0:3], v[208:211], v[224:227], v[0:3]
	s_setprio 0
	s_add_i32 s88, s88, 2
	s_add_u32 s68, s68, 0x100
	s_addc_u32 s69, s69, 0
	s_add_u32 s70, s70, 0x100
	s_addc_u32 s71, s71, 0
	s_cmpk_lt_u32 s88, 0x54
	s_barrier
	s_cbranch_scc1 .LBB0_1704
	s_add_u32 s68, s62, s87
	s_addc_u32 s69, s63, s86
	v_lshl_add_u64 v[130:131], s[68:69], 0, v[128:129]
	v_readfirstlane_b32 s68, v154
	s_mov_b32 m0, s68
	s_add_u32 s68, s62, s79
	v_lshl_add_u64 v[130:131], v[130:131], 0, s[20:21]
	s_addc_u32 s69, s63, s78
	ds_read_b128 v[138:141], v155
	ds_read_b128 v[146:149], v155 offset:1024
	ds_read_b128 v[158:161], v155 offset:2048
	ds_read_b128 v[162:165], v155 offset:3072
	ds_read_b128 v[166:169], v137
	ds_read_b128 v[170:173], v137 offset:1024
	ds_read_b128 v[174:177], v136
	ds_read_b128 v[178:181], v136 offset:1024
	ds_read_b128 v[182:185], v135
	ds_read_b128 v[186:189], v135 offset:1024
	ds_read_b128 v[190:193], v133
	ds_read_b128 v[196:199], v133 offset:1024
	global_load_lds_dwordx4 v[130:131], off
	v_lshl_add_u64 v[130:131], s[68:69], 0, v[128:129]
	v_readfirstlane_b32 s68, v153
	v_lshl_add_u64 v[130:131], v[130:131], 0, s[20:21]
	s_mov_b32 m0, s68
	s_nop 0
	global_load_lds_dwordx4 v[130:131], off
	s_setprio 1
	s_barrier
	s_waitcnt lgkmcnt(0)
	s_waitcnt lgkmcnt(0)
	v_mfma_f32_16x16x32_bf16 v[124:127], v[166:169], v[138:141], v[124:127]
	v_mfma_f32_16x16x32_bf16 v[120:123], v[166:169], v[158:161], v[120:123]
	v_mfma_f32_16x16x32_bf16 v[116:119], v[174:177], v[138:141], v[116:119]
	v_mfma_f32_16x16x32_bf16 v[108:111], v[182:185], v[138:141], v[108:111]
	v_mfma_f32_16x16x32_bf16 v[124:127], v[170:173], v[146:149], v[124:127]
	v_mfma_f32_16x16x32_bf16 v[120:123], v[170:173], v[162:165], v[120:123]
	v_mfma_f32_16x16x32_bf16 v[116:119], v[178:181], v[146:149], v[116:119]
	v_mfma_f32_16x16x32_bf16 v[112:115], v[174:177], v[158:161], v[112:115]
	v_mfma_f32_16x16x32_bf16 v[108:111], v[186:189], v[146:149], v[108:111]
	v_mfma_f32_16x16x32_bf16 v[104:107], v[182:185], v[158:161], v[104:107]
	v_mfma_f32_16x16x32_bf16 v[100:103], v[190:193], v[138:141], v[100:103]
	v_mfma_f32_16x16x32_bf16 v[96:99], v[190:193], v[158:161], v[96:99]
	v_mfma_f32_16x16x32_bf16 v[152:155], v[178:181], v[162:165], v[112:115]
	v_mfma_f32_16x16x32_bf16 v[200:203], v[186:189], v[162:165], v[104:107]
	v_mfma_f32_16x16x32_bf16 v[208:211], v[196:199], v[146:149], v[100:103]
	v_mfma_f32_16x16x32_bf16 v[212:215], v[196:199], v[162:165], v[96:99]
	s_setprio 0
	s_barrier
; #define WAIT_V(n) asm volatile("s_waitcnt vmcnt(" #n ")" ::: "memory")
; #define WAIT_L(n) asm volatile("s_waitcnt lgkmcnt(" #n ")" ::: "memory")
; #define BAR __builtin_amdgcn_s_barrier()
; template <int EPI>
; __device__ __forceinline__ void gemm_tile(const Params& p, const bf16* __restrict__ A, const bf16* __restrict__ Bt, const int K,
;                                           const int nt, const int brow, const int bcol, int pm, int pn) {
;     ...
;   { LDB(B0, 0, 0); LDA(At, 0, 0); STAGE(SA(1, 1), A, brow + HALF, nt - 1);
;     BAR; WAIT_L(0); MMA(0, 0, At, B0); BAR;
;     LDB(B1, 0, 1); BAR; WAIT_L(0); MMA(0, 1, At, B1); BAR;
;     LDA(At, 0, 1); WAIT_V(4); BAR; WAIT_L(0); MMA(1, 0, At, B0); MMA(1, 1, At, B1); BAR; }
;   { LDB(B0, 1, 0); LDA(At, 1, 0); WAIT_V(2); BAR; WAIT_L(0); MMA(0, 0, At, B0); BAR;
;     LDB(B1, 1, 1); WAIT_V(0); BAR; WAIT_L(0); MMA(0, 1, At, B1); BAR;
	s_nop 1
	ds_read_b128 v[96:99], v151
	ds_read_b128 v[100:103], v151 offset:1024
	ds_read_b128 v[104:107], v151 offset:2048
	ds_read_b128 v[112:115], v151 offset:3072
	s_setprio 1
	s_barrier
	s_waitcnt lgkmcnt(0)
	s_waitcnt lgkmcnt(0)
	v_mfma_f32_16x16x32_bf16 v[92:95], v[166:169], v[96:99], v[92:95]
	v_mfma_f32_16x16x32_bf16 v[88:91], v[166:169], v[104:107], v[88:91]
	v_mfma_f32_16x16x32_bf16 v[84:87], v[174:177], v[96:99], v[84:87]
	v_mfma_f32_16x16x32_bf16 v[76:79], v[182:185], v[96:99], v[76:79]
	v_mfma_f32_16x16x32_bf16 v[92:95], v[170:173], v[100:103], v[92:95]
	v_mfma_f32_16x16x32_bf16 v[88:91], v[170:173], v[112:115], v[88:91]
	v_mfma_f32_16x16x32_bf16 v[84:87], v[178:181], v[100:103], v[84:87]
	v_mfma_f32_16x16x32_bf16 v[80:83], v[174:177], v[104:107], v[80:83]
	v_mfma_f32_16x16x32_bf16 v[76:79], v[186:189], v[100:103], v[76:79]
	v_mfma_f32_16x16x32_bf16 v[72:75], v[182:185], v[104:107], v[72:75]
	v_mfma_f32_16x16x32_bf16 v[68:71], v[190:193], v[96:99], v[68:71]
	v_mfma_f32_16x16x32_bf16 v[64:67], v[190:193], v[104:107], v[64:67]
	v_mfma_f32_16x16x32_bf16 v[166:169], v[178:181], v[112:115], v[80:83]
	v_mfma_f32_16x16x32_bf16 v[170:173], v[186:189], v[112:115], v[72:75]
	v_mfma_f32_16x16x32_bf16 v[174:177], v[196:199], v[100:103], v[68:71]
	v_mfma_f32_16x16x32_bf16 v[178:181], v[196:199], v[112:115], v[64:67]
	s_setprio 0
	s_barrier
	s_nop 1
	ds_read_b128 v[64:67], v137 offset:16384
	ds_read_b128 v[68:71], v137 offset:17408
	ds_read_b128 v[72:75], v136 offset:16384
	ds_read_b128 v[80:83], v136 offset:17408
	ds_read_b128 v[182:185], v135 offset:16384
	ds_read_b128 v[186:189], v135 offset:17408
	ds_read_b128 v[190:193], v133 offset:16384
	ds_read_b128 v[196:199], v133 offset:17408
	s_waitcnt vmcnt(4)
	s_setprio 1
	s_barrier
	s_waitcnt lgkmcnt(0)
	s_waitcnt lgkmcnt(0)
	v_mfma_f32_16x16x32_bf16 v[60:63], v[64:67], v[138:141], v[60:63]
	v_mfma_f32_16x16x32_bf16 v[56:59], v[64:67], v[158:161], v[56:59]
	v_mfma_f32_16x16x32_bf16 v[52:55], v[72:75], v[138:141], v[52:55]
	v_mfma_f32_16x16x32_bf16 v[44:47], v[182:185], v[138:141], v[44:47]
	v_mfma_f32_16x16x32_bf16 v[60:63], v[68:71], v[146:149], v[60:63]
	v_mfma_f32_16x16x32_bf16 v[56:59], v[68:71], v[162:165], v[56:59]
	v_mfma_f32_16x16x32_bf16 v[52:55], v[80:83], v[146:149], v[52:55]
	v_mfma_f32_16x16x32_bf16 v[48:51], v[72:75], v[158:161], v[48:51]
	v_mfma_f32_16x16x32_bf16 v[44:47], v[186:189], v[146:149], v[44:47]
	v_mfma_f32_16x16x32_bf16 v[40:43], v[182:185], v[158:161], v[40:43]
	v_mfma_f32_16x16x32_bf16 v[36:39], v[190:193], v[138:141], v[36:39]
	v_mfma_f32_16x16x32_bf16 v[32:35], v[190:193], v[158:161], v[32:35]
	v_mfma_f32_16x16x32_bf16 v[216:219], v[80:83], v[162:165], v[48:51]
	v_mfma_f32_16x16x32_bf16 v[220:223], v[186:189], v[162:165], v[40:43]
	v_mfma_f32_16x16x32_bf16 v[138:141], v[196:199], v[146:149], v[36:39]
	v_mfma_f32_16x16x32_bf16 v[146:149], v[196:199], v[162:165], v[32:35]
	s_setprio 0
	s_setprio 1
	v_mfma_f32_16x16x32_bf16 v[28:31], v[64:67], v[96:99], v[28:31]
	v_mfma_f32_16x16x32_bf16 v[24:27], v[64:67], v[104:107], v[24:27]
	v_mfma_f32_16x16x32_bf16 v[20:23], v[72:75], v[96:99], v[20:23]
	v_mfma_f32_16x16x32_bf16 v[12:15], v[182:185], v[96:99], v[12:15]
	v_mfma_f32_16x16x32_bf16 v[28:31], v[68:71], v[100:103], v[28:31]
	v_mfma_f32_16x16x32_bf16 v[24:27], v[68:71], v[112:115], v[24:27]
	v_mfma_f32_16x16x32_bf16 v[20:23], v[80:83], v[100:103], v[20:23]
	v_mfma_f32_16x16x32_bf16 v[16:19], v[72:75], v[104:107], v[16:19]
	v_mfma_f32_16x16x32_bf16 v[12:15], v[186:189], v[100:103], v[12:15]
	v_mfma_f32_16x16x32_bf16 v[8:11], v[182:185], v[104:107], v[8:11]
	v_mfma_f32_16x16x32_bf16 v[4:7], v[190:193], v[96:99], v[4:7]
	v_mfma_f32_16x16x32_bf16 v[0:3], v[190:193], v[104:107], v[0:3]
	v_mfma_f32_16x16x32_bf16 v[158:161], v[80:83], v[112:115], v[16:19]
	v_mfma_f32_16x16x32_bf16 v[162:165], v[186:189], v[112:115], v[8:11]
	v_mfma_f32_16x16x32_bf16 v[182:185], v[196:199], v[100:103], v[4:7]
	v_mfma_f32_16x16x32_bf16 v[186:189], v[196:199], v[112:115], v[0:3]
	s_setprio 0
	s_barrier
	s_nop 1
	ds_read_b128 v[0:3], v145
	ds_read_b128 v[4:7], v145 offset:1024
	ds_read_b128 v[8:11], v145 offset:2048
	ds_read_b128 v[16:19], v145 offset:3072
	ds_read_b128 v[32:35], v137 offset:32768
	ds_read_b128 v[36:39], v137 offset:33792
	ds_read_b128 v[40:43], v136 offset:32768
	ds_read_b128 v[48:51], v136 offset:33792
	ds_read_b128 v[190:193], v135 offset:32768
	ds_read_b128 v[196:199], v135 offset:33792
	ds_read_b128 v[224:227], v133 offset:32768
	ds_read_b128 v[228:231], v133 offset:33792
	s_waitcnt vmcnt(2)
	s_setprio 1
	s_barrier
; #define WAIT_V(n) asm volatile("s_waitcnt vmcnt(" #n ")" ::: "memory")
; #define WAIT_L(n) asm volatile("s_waitcnt lgkmcnt(" #n ")" ::: "memory")
; #define BAR __builtin_amdgcn_s_barrier()
; template <int EPI>
; __device__ __forceinline__ void gemm_tile(const Params& p, const bf16* __restrict__ A, const bf16* __restrict__ Bt, const int K,
;                                           const int nt, const int brow, const int bcol, int pm, int pn) {
;     ...
;     LDA(At, 0, 1); WAIT_V(4); BAR; WAIT_L(0); MMA(1, 0, At, B0); MMA(1, 1, At, B1); BAR; }
;   { LDB(B0, 1, 0); LDA(At, 1, 0); WAIT_V(2); BAR; WAIT_L(0); MMA(0, 0, At, B0); BAR;
;     LDB(B1, 1, 1); WAIT_V(0); BAR; WAIT_L(0); MMA(0, 1, At, B1); BAR;
;     LDA(At, 1, 1); BAR; WAIT_L(0); MMA(1, 0, At, B0); MMA(1, 1, At, B1); BAR; }
;   if (wr == 0) BAR;
	s_waitcnt lgkmcnt(0)
	s_waitcnt lgkmcnt(0)
	v_mfma_f32_16x16x32_bf16 v[64:67], v[32:35], v[0:3], v[124:127]
	v_mfma_f32_16x16x32_bf16 v[96:99], v[36:39], v[4:7], v[64:67]
	v_mfma_f32_16x16x32_bf16 v[64:67], v[32:35], v[8:11], v[120:123]
	v_mfma_f32_16x16x32_bf16 v[112:115], v[36:39], v[16:19], v[64:67]
	v_mfma_f32_16x16x32_bf16 v[64:67], v[40:43], v[0:3], v[116:119]
	v_mfma_f32_16x16x32_bf16 v[100:103], v[48:51], v[4:7], v[64:67]
	v_mfma_f32_16x16x32_bf16 v[64:67], v[40:43], v[8:11], v[152:155]
	v_mfma_f32_16x16x32_bf16 v[116:119], v[48:51], v[16:19], v[64:67]
	v_mfma_f32_16x16x32_bf16 v[64:67], v[190:193], v[0:3], v[108:111]
	v_mfma_f32_16x16x32_bf16 v[104:107], v[196:199], v[4:7], v[64:67]
	v_mfma_f32_16x16x32_bf16 v[64:67], v[190:193], v[8:11], v[200:203]
	v_mfma_f32_16x16x32_bf16 v[120:123], v[196:199], v[16:19], v[64:67]
	v_mfma_f32_16x16x32_bf16 v[64:67], v[224:227], v[0:3], v[208:211]
	v_mfma_f32_16x16x32_bf16 v[108:111], v[228:231], v[4:7], v[64:67]
	v_mfma_f32_16x16x32_bf16 v[64:67], v[224:227], v[8:11], v[212:215]
	v_mfma_f32_16x16x32_bf16 v[124:127], v[228:231], v[16:19], v[64:67]
	s_setprio 0
	s_barrier
	ds_read_b128 v[150:153], v142
	ds_read_b128 v[200:203], v142 offset:1024
	ds_read_b128 v[208:211], v142 offset:2048
	ds_read_b128 v[142:145], v142 offset:3072
	s_waitcnt vmcnt(0)
	s_setprio 1
	s_barrier
	s_waitcnt lgkmcnt(0)
	s_waitcnt lgkmcnt(0)
	v_mfma_f32_16x16x32_bf16 v[64:67], v[32:35], v[150:153], v[92:95]
	v_mfma_f32_16x16x32_bf16 v[32:35], v[32:35], v[208:211], v[88:91]
	v_mfma_f32_16x16x32_bf16 v[80:83], v[36:39], v[142:145], v[32:35]
	v_mfma_f32_16x16x32_bf16 v[32:35], v[40:43], v[150:153], v[84:87]
	v_mfma_f32_16x16x32_bf16 v[68:71], v[48:51], v[200:203], v[32:35]
	v_mfma_f32_16x16x32_bf16 v[32:35], v[40:43], v[208:211], v[166:169]
	v_mfma_f32_16x16x32_bf16 v[84:87], v[48:51], v[142:145], v[32:35]
	v_mfma_f32_16x16x32_bf16 v[32:35], v[190:193], v[150:153], v[76:79]
	v_mfma_f32_16x16x32_bf16 v[72:75], v[196:199], v[200:203], v[32:35]
	v_mfma_f32_16x16x32_bf16 v[32:35], v[190:193], v[208:211], v[170:173]
	v_mfma_f32_16x16x32_bf16 v[88:91], v[196:199], v[142:145], v[32:35]
	v_mfma_f32_16x16x32_bf16 v[32:35], v[224:227], v[150:153], v[174:177]
	v_mfma_f32_16x16x32_bf16 v[76:79], v[228:231], v[200:203], v[32:35]
	v_mfma_f32_16x16x32_bf16 v[32:35], v[224:227], v[208:211], v[178:181]
	v_mfma_f32_16x16x32_bf16 v[64:67], v[36:39], v[200:203], v[64:67]
	v_mfma_f32_16x16x32_bf16 v[92:95], v[228:231], v[142:145], v[32:35]
	s_setprio 0
	s_barrier
	ds_read_b128 v[166:169], v137 offset:49152
	ds_read_b128 v[170:173], v137 offset:50176
	ds_read_b128 v[174:177], v136 offset:49152
	ds_read_b128 v[178:181], v136 offset:50176
	ds_read_b128 v[190:193], v135 offset:49152
	ds_read_b128 v[134:137], v135 offset:50176
	ds_read_b128 v[196:199], v133 offset:49152
	ds_read_b128 v[130:133], v133 offset:50176
	s_setprio 1
	s_barrier
	s_waitcnt lgkmcnt(0)
	s_waitcnt lgkmcnt(0)
	v_mfma_f32_16x16x32_bf16 v[36:39], v[166:169], v[8:11], v[56:59]
	v_mfma_f32_16x16x32_bf16 v[40:43], v[174:177], v[8:11], v[216:219]
	v_mfma_f32_16x16x32_bf16 v[32:35], v[166:169], v[0:3], v[60:63]
	v_mfma_f32_16x16x32_bf16 v[48:51], v[170:173], v[16:19], v[36:39]
	v_mfma_f32_16x16x32_bf16 v[36:39], v[174:177], v[0:3], v[52:55]
	v_mfma_f32_16x16x32_bf16 v[52:55], v[178:181], v[16:19], v[40:43]
	v_mfma_f32_16x16x32_bf16 v[40:43], v[190:193], v[0:3], v[44:47]
	v_mfma_f32_16x16x32_bf16 v[44:47], v[190:193], v[8:11], v[220:223]
	v_mfma_f32_16x16x32_bf16 v[0:3], v[196:199], v[0:3], v[138:141]
	v_mfma_f32_16x16x32_bf16 v[56:59], v[134:137], v[16:19], v[44:47]
	v_mfma_f32_16x16x32_bf16 v[44:47], v[130:133], v[4:7], v[0:3]
	v_mfma_f32_16x16x32_bf16 v[0:3], v[196:199], v[8:11], v[146:149]
	v_mfma_f32_16x16x32_bf16 v[32:35], v[170:173], v[4:7], v[32:35]
	v_mfma_f32_16x16x32_bf16 v[36:39], v[178:181], v[4:7], v[36:39]
	v_mfma_f32_16x16x32_bf16 v[40:43], v[134:137], v[4:7], v[40:43]
	v_mfma_f32_16x16x32_bf16 v[60:63], v[130:133], v[16:19], v[0:3]
	s_setprio 0
	s_setprio 1
	v_mfma_f32_16x16x32_bf16 v[4:7], v[166:169], v[208:211], v[24:27]
	v_mfma_f32_16x16x32_bf16 v[8:11], v[174:177], v[208:211], v[158:161]
	v_mfma_f32_16x16x32_bf16 v[16:19], v[170:173], v[142:145], v[4:7]
	v_mfma_f32_16x16x32_bf16 v[4:7], v[174:177], v[150:153], v[20:23]
	v_mfma_f32_16x16x32_bf16 v[20:23], v[178:181], v[142:145], v[8:11]
	v_mfma_f32_16x16x32_bf16 v[8:11], v[190:193], v[150:153], v[12:15]
	v_mfma_f32_16x16x32_bf16 v[12:15], v[190:193], v[208:211], v[162:165]
	v_mfma_f32_16x16x32_bf16 v[0:3], v[166:169], v[150:153], v[28:31]
	v_mfma_f32_16x16x32_bf16 v[24:27], v[134:137], v[142:145], v[12:15]
	v_mfma_f32_16x16x32_bf16 v[12:15], v[196:199], v[150:153], v[182:185]
	v_mfma_f32_16x16x32_bf16 v[28:31], v[196:199], v[208:211], v[186:189]
	v_mfma_f32_16x16x32_bf16 v[0:3], v[170:173], v[200:203], v[0:3]
	v_mfma_f32_16x16x32_bf16 v[4:7], v[178:181], v[200:203], v[4:7]
	v_mfma_f32_16x16x32_bf16 v[8:11], v[134:137], v[200:203], v[8:11]
	v_mfma_f32_16x16x32_bf16 v[12:15], v[130:133], v[200:203], v[12:15]
	v_mfma_f32_16x16x32_bf16 v[28:31], v[130:133], v[142:145], v[28:31]
	s_setprio 0
	s_cmpk_gt_u32 s77, 0xff
	s_barrier
	s_cbranch_scc1 .LBB0_1696
	s_barrier
	s_branch .LBB0_1696

; __device__ __forceinline__ void phase_final(const Params& p) {
;     ...
;   for (int row = blockIdx.x * 8 + wid; row < NTOK; row += gridDim.x * 8) {
;     float* y = p.out + O_Y + (long)row * DM;
;     if (row < SEQ) {
;       const bf16* xb = P_HBUF(p) + (long)row * DM;
;       u32x4 u[4];
;       float ss = 0.f;
; #pragma unroll
;       for (int i = 0; i < 4; ++i) {
;         u[i] = *reinterpret_cast<const u32x4*>(xb + i * 512 + lane * 8);
.LBB0_1744:
	s_or_b64 exec, exec, s[2:3]
	s_barrier
	v_mov_b32 v0, v206
	v_readlane_b32 s2, v243, 5
	v_ashrrev_i32_e32 v1, 6, v0
	s_nop 0
	v_add_u32_e32 v32, s2, v1
	s_movk_i32 s2, 0x4100
	v_cmp_gt_i32_e32 vcc, s2, v32
	s_and_saveexec_b64 s[2:3], vcc
	s_cbranch_execz .LBB0_1753
	s_load_dword s0, s[0:1], 0xa0
	v_and_b32_e32 v1, 63, v0
	v_mov_b32_e32 v35, 0
	v_lshlrev_b32_e32 v34, 4, v1
	v_lshlrev_b32_e32 v0, 2, v1
	s_waitcnt lgkmcnt(0)
	s_lshl_b32 s14, s0, 3
	s_add_u32 s8, s80, 0x1000
	s_addc_u32 s9, s81, 0
	s_add_u32 s10, s80, 0x1800
	v_lshlrev_b32_e32 v2, 3, v1
	v_lshl_add_u64 v[38:39], s[80:81], 0, v[34:35]
	s_mov_b64 s[2:3], 0x1400
	s_addc_u32 s11, s81, 0
	s_mov_b64 s[6:7], 0x1c00
	v_lshlrev_b32_e32 v4, 5, v1
	v_mov_b32_e32 v5, v35
	v_lshl_add_u64 v[36:37], s[60:61], 0, v[34:35]
	s_mov_b64 s[0:1], 0x1000
	v_lshl_add_u64 v[40:41], s[8:9], 0, v[34:35]
	v_lshl_add_u64 v[42:43], v[38:39], 0, s[2:3]
	s_mov_b64 s[4:5], 0x1800
	v_lshl_add_u64 v[44:45], s[10:11], 0, v[34:35]
	v_lshl_add_u64 v[46:47], v[38:39], 0, s[6:7]
	v_lshl_add_u64 v[48:49], s[80:81], 0, v[4:5]
	v_lshl_add_u64 v[50:51], s[8:9], 0, v[4:5]
	v_lshl_add_u64 v[52:53], s[10:11], 0, v[4:5]
	v_lshl_add_u64 v[54:55], s[46:47], 0, v[34:35]
	v_add_u32_e32 v56, 0xffffc000, v32
	s_mov_b64 s[8:9], 0
	s_movk_i32 s15, 0x3fff
	v_lshlrev_b32_e32 v58, 2, v0
	s_movk_i32 s16, 0x1000
	s_mov_b32 s17, 0x1d7d6000
	s_mov_b32 s18, 0x1d7d7000
	s_mov_b32 s19, 0x1d7d8000
	v_mov_b32_e32 v72, 0x358637bd
	s_mov_b32 s20, 0x800000
	v_lshlrev_b32_e32 v34, 2, v2
	s_movk_i32 s21, 0x40ff
	s_branch .LBB0_1747

; __device__ __forceinline__ void phase_final(const Params& p) {
;     ...
;     } else {
;       float4 v[8];
;       float ss = 0.f;
; #pragma unroll
;       for (int i = 0; i < 8; ++i) v[i] = *reinterpret_cast<const float4*>(y + i * 256 + lane * 4);
; #pragma unroll 1
;       for (int s = 0; s < DSK; ++s) {
;         const float* pp = P_PART(p) + (long)s * DECB * DECT * DM + (long)(row - SEQ) * DM + lane * 4;
; #pragma unroll
;         for (int i = 0; i < 8; ++i) {
;           const float4 q4 = *reinterpret_cast<const float4*>(pp + i * 256);
;           v[i].x += q4.x; v[i].y += q4.y; v[i].z += q4.z; v[i].w += q4.w;
;         }
;       }
; #pragma unroll
;       for (int i = 0; i < 8; ++i) ss += v[i].x * v[i].x + v[i].y * v[i].y + v[i].z * v[i].z + v[i].w * v[i].w;
;       ss = wave_sum(ss);
;       float r = rsqrtf(ss * (1.f / DM) + EPS);
.LBB0_1747:
	v_ashrrev_i32_e32 v33, 31, v32
	v_lshlrev_b64 v[0:1], 13, v[32:33]
	v_lshl_add_u64 v[0:1], s[82:83], 0, v[0:1]
	v_cmp_lt_i32_e32 vcc, s15, v32
	s_and_saveexec_b64 s[10:11], vcc
	s_xor_b64 s[10:11], exec, s[10:11]
	s_cbranch_execz .LBB0_1751
	v_mov_b32_e32 v59, v35
	v_lshl_add_u64 v[60:61], v[0:1], 0, v[58:59]
	v_add_co_u32_e32 v62, vcc, s16, v60
	global_load_dwordx4 v[28:31], v[60:61], off
	global_load_dwordx4 v[24:27], v[60:61], off offset:1024
	global_load_dwordx4 v[20:23], v[60:61], off offset:2048
	global_load_dwordx4 v[16:19], v[60:61], off offset:3072
	v_addc_co_u32_e32 v63, vcc, 0, v61, vcc
	global_load_dwordx4 v[12:15], v[62:63], off
	global_load_dwordx4 v[8:11], v[62:63], off offset:1024
	global_load_dwordx4 v[4:7], v[62:63], off offset:2048
	global_load_dwordx4 v[0:3], v[62:63], off offset:3072
	v_mov_b32_e32 v57, v35
	v_lshlrev_b64 v[62:63], 13, v[56:57]
	v_lshl_add_u64 v[70:71], v[54:55], 0, v[62:63]
	v_lshl_add_u64 v[68:69], v[60:61], 0, s[0:1]
	v_lshl_add_u64 v[66:67], v[60:61], 0, s[2:3]
	v_lshl_add_u64 v[64:65], v[60:61], 0, s[4:5]
	v_lshl_add_u64 v[62:63], v[60:61], 0, s[6:7]
	s_mov_b64 s[12:13], 0
.LBB0_1749:
	v_lshl_add_u64 v[74:75], v[70:71], 0, s[12:13]
	v_add_co_u32_e32 v106, vcc, s17, v74
	s_add_u32 s12, s12, 0x200000
	s_nop 0
	v_addc_co_u32_e32 v107, vcc, 0, v75, vcc
	v_add_co_u32_e32 v108, vcc, s18, v74
	s_addc_u32 s13, s13, 0
	s_nop 0
	v_addc_co_u32_e32 v109, vcc, 0, v75, vcc
	v_add_co_u32_e32 v110, vcc, s19, v74
	s_cmp_lg_u32 s12, 0x1600000
	s_nop 0
	v_addc_co_u32_e32 v111, vcc, 0, v75, vcc
	global_load_dwordx4 v[74:77], v[106:107], off offset:1024
	global_load_dwordx4 v[78:81], v[106:107], off offset:2048
	global_load_dwordx4 v[82:85], v[106:107], off offset:3072
	global_load_dwordx4 v[86:89], v[110:111], off offset:-4096
	global_load_dwordx4 v[90:93], v[108:109], off offset:1024
	global_load_dwordx4 v[94:97], v[108:109], off offset:2048
	global_load_dwordx4 v[98:101], v[108:109], off offset:3072
	global_load_dwordx4 v[102:105], v[110:111], off
	s_waitcnt vmcnt(7)
	v_pk_add_f32 v[28:29], v[28:29], v[74:75]
	v_pk_add_f32 v[30:31], v[30:31], v[76:77]
	s_waitcnt vmcnt(6)
	v_pk_add_f32 v[24:25], v[24:25], v[78:79]
	v_pk_add_f32 v[26:27], v[26:27], v[80:81]
	s_waitcnt vmcnt(5)
	v_pk_add_f32 v[20:21], v[20:21], v[82:83]
	v_pk_add_f32 v[22:23], v[22:23], v[84:85]
	s_waitcnt vmcnt(4)
	v_pk_add_f32 v[16:17], v[16:17], v[86:87]
	v_pk_add_f32 v[18:19], v[18:19], v[88:89]
	s_waitcnt vmcnt(3)
	v_pk_add_f32 v[12:13], v[12:13], v[90:91]
	v_pk_add_f32 v[14:15], v[14:15], v[92:93]
	s_waitcnt vmcnt(2)
	v_pk_add_f32 v[8:9], v[8:9], v[94:95]
	v_pk_add_f32 v[10:11], v[10:11], v[96:97]
	s_waitcnt vmcnt(1)
	v_pk_add_f32 v[4:5], v[4:5], v[98:99]
	v_pk_add_f32 v[6:7], v[6:7], v[100:101]
	s_waitcnt vmcnt(0)
	v_pk_add_f32 v[0:1], v[0:1], v[102:103]
	v_pk_add_f32 v[2:3], v[2:3], v[104:105]
	s_cbranch_scc1 .LBB0_1749
	v_pk_mul_f32 v[70:71], v[28:29], v[28:29]
	v_pk_mul_f32 v[74:75], v[30:31], v[30:31]
	v_add_f32_e32 v57, v70, v71
	v_pk_mul_f32 v[76:77], v[24:25], v[24:25]
	v_add_f32_e32 v57, v57, v74
	v_add_f32_e32 v33, v76, v77
	v_add_f32_e32 v57, v57, v75
	global_load_dwordx4 v[74:77], v[38:39], off
	v_pk_mul_f32 v[78:79], v[26:27], v[26:27]
	v_pk_mul_f32 v[80:81], v[20:21], v[20:21]
	v_add_f32_e32 v33, v33, v78
	v_add_f32_e32 v33, v33, v79
	v_pk_mul_f32 v[82:83], v[22:23], v[22:23]
	v_add_f32_e32 v33, v57, v33
	v_add_f32_e32 v57, v80, v81
	v_mov_b32_e32 v90, v13
	v_mov_b32_e32 v91, v9
	v_add_f32_e32 v57, v57, v82
	v_pk_mul_f32 v[84:85], v[16:17], v[16:17]
	v_mov_b32_e32 v88, v12
	v_mov_b32_e32 v89, v8
	v_pk_mul_f32 v[90:91], v[90:91], v[90:91]
	v_add_f32_e32 v57, v57, v83
	v_pk_mul_f32 v[86:87], v[18:19], v[18:19]
	v_pk_fma_f32 v[88:89], v[88:89], v[88:89], v[90:91]
	v_mov_b32_e32 v90, v14
	v_mov_b32_e32 v91, v10
	v_add_f32_e32 v33, v33, v57
	v_add_f32_e32 v57, v84, v85
	v_pk_fma_f32 v[88:89], v[90:91], v[90:91], v[88:89]
	v_mov_b32_e32 v90, v15
	v_mov_b32_e32 v91, v11
	v_mov_b32_e32 v92, v5
	v_mov_b32_e32 v93, v1
	v_add_f32_e32 v57, v57, v86
	v_pk_fma_f32 v[88:89], v[90:91], v[90:91], v[88:89]
	v_mov_b32_e32 v90, v4
	v_mov_b32_e32 v91, v0
	v_pk_mul_f32 v[92:93], v[92:93], v[92:93]
	v_add_f32_e32 v57, v57, v87
	v_pk_fma_f32 v[90:91], v[90:91], v[90:91], v[92:93]
	v_mov_b32_e32 v92, v6
	v_mov_b32_e32 v93, v2
	v_add_f32_e32 v33, v33, v57
	v_and_b32_e32 v57, 64, v194
	v_pk_fma_f32 v[90:91], v[92:93], v[92:93], v[90:91]
	v_mov_b32_e32 v92, v7
	v_mov_b32_e32 v93, v3
	v_add_f32_e32 v33, v33, v88
	v_add_u32_e32 v57, 64, v57
	v_xor_b32_e32 v59, 32, v194
	v_pk_fma_f32 v[90:91], v[92:93], v[92:93], v[90:91]
	v_add_f32_e32 v33, v33, v89
	v_cmp_lt_i32_e32 vcc, v59, v57
	v_add_f32_e32 v33, v33, v90
	v_add_f32_e32 v33, v33, v91
	v_cndmask_b32_e32 v59, v194, v59, vcc
	v_lshlrev_b32_e32 v59, 2, v59
	ds_bpermute_b32 v59, v59, v33
	s_waitcnt lgkmcnt(0)
	v_add_f32_e32 v33, v33, v59
	v_xor_b32_e32 v59, 16, v194
	v_cmp_lt_i32_e32 vcc, v59, v57
	s_nop 1
	v_cndmask_b32_e32 v59, v194, v59, vcc
	v_lshlrev_b32_e32 v59, 2, v59
	ds_bpermute_b32 v59, v59, v33
	s_waitcnt lgkmcnt(0)
	v_add_f32_e32 v33, v33, v59
	v_xor_b32_e32 v59, 8, v194
	v_cmp_lt_i32_e32 vcc, v59, v57
	s_nop 1
	v_cndmask_b32_e32 v59, v194, v59, vcc
	v_lshlrev_b32_e32 v59, 2, v59
	ds_bpermute_b32 v59, v59, v33
	s_waitcnt lgkmcnt(0)
	v_add_f32_e32 v33, v33, v59
	v_xor_b32_e32 v59, 4, v194
	v_cmp_lt_i32_e32 vcc, v59, v57
	s_nop 1
	v_cndmask_b32_e32 v59, v194, v59, vcc
	v_lshlrev_b32_e32 v59, 2, v59
	ds_bpermute_b32 v59, v59, v33
	s_waitcnt lgkmcnt(0)
	v_add_f32_e32 v33, v33, v59
	v_xor_b32_e32 v59, 2, v194
	v_cmp_lt_i32_e32 vcc, v59, v57
	s_nop 1
	v_cndmask_b32_e32 v59, v194, v59, vcc
	v_lshlrev_b32_e32 v59, 2, v59
	ds_bpermute_b32 v59, v59, v33
	s_waitcnt lgkmcnt(0)
; __device__ __forceinline__ void phase_final(const Params& p) {
;     ...
;     if (row < SEQ) {
;       const bf16* xb = P_HBUF(p) + (long)row * DM;
;       u32x4 u[4];
;       float ss = 0.f;
; #pragma unroll
;       for (int i = 0; i < 4; ++i) {
;         u[i] = *reinterpret_cast<const u32x4*>(xb + i * 512 + lane * 8);
; #pragma unroll
;         for (int j = 0; j < 4; ++j) { float a = __uint_as_float(u[i][j] << 16), b = __uint_as_float(u[i][j] & 0xffff0000u); ss += a * a + b * b; }
;       }
;       ss = wave_sum(ss);
;     ...
;       ss = wave_sum(ss);
;       float r = rsqrtf(ss * (1.f / DM) + EPS);
; #pragma unroll
;       for (int i = 0; i < 8; ++i) {
;         float4 gg = *reinterpret_cast<const float4*>(p.g_final + i * 256 + lane * 4);
;         float4 ov = {v[i].x * r * gg.x, v[i].y * r * gg.y, v[i].z * r * gg.z, v[i].w * r * gg.w};
;         *reinterpret_cast<float4*>(y + i * 256 + lane * 4) = ov;
;       }
	v_add_f32_e32 v33, v33, v59
	v_xor_b32_e32 v59, 1, v194
	v_cmp_lt_i32_e32 vcc, v59, v57
	s_nop 1
	v_cndmask_b32_e32 v57, v194, v59, vcc
	v_lshlrev_b32_e32 v57, 2, v57
	ds_bpermute_b32 v57, v57, v33
	s_waitcnt lgkmcnt(0)
	v_add_f32_e32 v33, v33, v57
	v_fmamk_f32 v33, v33, 0x3a000000, v72
	v_mul_f32_e32 v57, 0x4b800000, v33
	v_cmp_gt_f32_e32 vcc, s20, v33
	s_nop 1
	v_cndmask_b32_e32 v33, v33, v57, vcc
	v_rsq_f32_e32 v33, v33
	s_nop 0
	v_mul_f32_e32 v57, 0x45800000, v33
	v_cndmask_b32_e32 v70, v33, v57, vcc
	v_pk_mul_f32 v[28:29], v[28:29], v[70:71] op_sel_hi:[1,0]
	v_pk_mul_f32 v[30:31], v[30:31], v[70:71] op_sel_hi:[1,0]
	s_waitcnt vmcnt(0)
	v_pk_mul_f32 v[28:29], v[74:75], v[28:29]
	v_pk_mul_f32 v[30:31], v[76:77], v[30:31]
	global_store_dwordx4 v[60:61], v[28:31], off
	global_load_dwordx4 v[28:31], v[38:39], off offset:1024
	v_pk_mul_f32 v[24:25], v[24:25], v[70:71] op_sel_hi:[1,0]
	v_pk_mul_f32 v[26:27], v[26:27], v[70:71] op_sel_hi:[1,0]
	v_pk_mul_f32 v[20:21], v[20:21], v[70:71] op_sel_hi:[1,0]
	v_pk_mul_f32 v[22:23], v[22:23], v[70:71] op_sel_hi:[1,0]
	v_pk_mul_f32 v[16:17], v[16:17], v[70:71] op_sel_hi:[1,0]
	v_pk_mul_f32 v[18:19], v[18:19], v[70:71] op_sel_hi:[1,0]
	v_pk_mul_f32 v[12:13], v[12:13], v[70:71] op_sel_hi:[1,0]
	v_pk_mul_f32 v[14:15], v[14:15], v[70:71] op_sel_hi:[1,0]
	v_pk_mul_f32 v[8:9], v[8:9], v[70:71] op_sel_hi:[1,0]
	v_pk_mul_f32 v[10:11], v[10:11], v[70:71] op_sel_hi:[1,0]
	v_pk_mul_f32 v[4:5], v[4:5], v[70:71] op_sel_hi:[1,0]
	v_pk_mul_f32 v[6:7], v[6:7], v[70:71] op_sel_hi:[1,0]
	v_pk_mul_f32 v[0:1], v[0:1], v[70:71] op_sel_hi:[1,0]
	v_pk_mul_f32 v[2:3], v[2:3], v[70:71] op_sel_hi:[1,0]
	s_waitcnt vmcnt(0)
	v_pk_mul_f32 v[24:25], v[28:29], v[24:25]
	v_pk_mul_f32 v[26:27], v[26:27], v[30:31]
	global_store_dwordx4 v[60:61], v[24:27], off offset:1024
	global_load_dwordx4 v[24:27], v[38:39], off offset:2048
	s_waitcnt vmcnt(0)
	v_pk_mul_f32 v[20:21], v[20:21], v[24:25]
	v_pk_mul_f32 v[22:23], v[22:23], v[26:27]
	global_store_dwordx4 v[60:61], v[20:23], off offset:2048
	global_load_dwordx4 v[20:23], v[38:39], off offset:3072
	s_waitcnt vmcnt(0)
	v_pk_mul_f32 v[16:17], v[16:17], v[20:21]
	v_pk_mul_f32 v[18:19], v[18:19], v[22:23]
	global_store_dwordx4 v[60:61], v[16:19], off offset:3072
	global_load_dwordx4 v[16:19], v[40:41], off
	s_waitcnt vmcnt(0)
	v_pk_mul_f32 v[12:13], v[12:13], v[16:17]
	v_pk_mul_f32 v[14:15], v[14:15], v[18:19]
	global_store_dwordx4 v[68:69], v[12:15], off
	global_load_dwordx4 v[12:15], v[42:43], off
	s_waitcnt vmcnt(0)
	v_pk_mul_f32 v[8:9], v[8:9], v[12:13]
	v_pk_mul_f32 v[10:11], v[10:11], v[14:15]
	global_store_dwordx4 v[66:67], v[8:11], off
	global_load_dwordx4 v[8:11], v[44:45], off
	s_waitcnt vmcnt(0)
	v_pk_mul_f32 v[4:5], v[4:5], v[8:9]
	v_pk_mul_f32 v[6:7], v[6:7], v[10:11]
	global_store_dwordx4 v[64:65], v[4:7], off
	global_load_dwordx4 v[4:7], v[46:47], off
	s_waitcnt vmcnt(0)
	v_pk_mul_f32 v[0:1], v[0:1], v[4:5]
	v_pk_mul_f32 v[2:3], v[2:3], v[6:7]
	global_store_dwordx4 v[62:63], v[0:3], off
.LBB0_1751:
	s_andn2_saveexec_b64 s[10:11], s[10:11]
	s_cbranch_execz .LBB0_1746
	v_lshlrev_b64 v[2:3], 11, v[32:33]
	v_lshl_add_u64 v[18:19], v[2:3], 1, v[36:37]
	global_load_dwordx4 v[2:5], v[18:19], off
	global_load_dwordx4 v[6:9], v[18:19], off offset:1024
	global_load_dwordx4 v[10:13], v[18:19], off offset:2048
	global_load_dwordx4 v[14:17], v[18:19], off offset:3072
	s_nop 0
	global_load_dwordx4 v[18:21], v[48:49], off offset:16
	global_load_dwordx4 v[22:25], v[48:49], off
	v_and_b32_e32 v26, 64, v194
	v_xor_b32_e32 v27, 32, v194
	v_add_u32_e32 v33, 64, v26
	v_cmp_lt_i32_e32 vcc, v27, v33
	s_waitcnt vmcnt(5)
	v_lshlrev_b32_e32 v28, 16, v2
	v_cndmask_b32_e32 v26, v194, v27, vcc
	v_and_b32_e32 v29, 0xffff0000, v2
	v_lshlrev_b32_e32 v2, 16, v3
	v_and_b32_e32 v3, 0xffff0000, v3
	v_lshlrev_b32_e32 v57, 2, v26
	v_lshlrev_b32_e32 v26, 16, v4
	v_and_b32_e32 v27, 0xffff0000, v4
	v_pk_mul_f32 v[76:77], v[28:29], v[28:29]
	v_pk_mul_f32 v[78:79], v[2:3], v[2:3]
	v_lshlrev_b32_e32 v4, 16, v5
	v_and_b32_e32 v5, 0xffff0000, v5
	s_waitcnt vmcnt(4)
	v_lshlrev_b32_e32 v60, 16, v6
	v_and_b32_e32 v61, 0xffff0000, v6
	v_lshlrev_b32_e32 v62, 16, v7
	v_and_b32_e32 v63, 0xffff0000, v7
	v_pk_mul_f32 v[6:7], v[26:27], v[26:27]
	v_add_f32_e32 v73, v78, v79
	v_add_f32_e32 v76, v76, v77
	v_pk_mul_f32 v[74:75], v[4:5], v[4:5]
	v_add_f32_e32 v77, v6, v7
	v_add_f32_e32 v73, v76, v73
	v_pk_mul_f32 v[84:85], v[60:61], v[60:61]
	v_add_f32_e32 v59, v74, v75
	v_add_f32_e32 v73, v77, v73
	v_lshlrev_b32_e32 v30, 16, v8
	v_and_b32_e32 v31, 0xffff0000, v8
	v_pk_mul_f32 v[86:87], v[62:63], v[62:63]
	v_add_f32_e32 v78, v84, v85
	v_add_f32_e32 v59, v59, v73
	v_lshlrev_b32_e32 v8, 16, v9
	v_and_b32_e32 v9, 0xffff0000, v9
	v_pk_mul_f32 v[80:81], v[30:31], v[30:31]
	v_add_f32_e32 v79, v86, v87
	v_add_f32_e32 v59, v78, v59
	s_waitcnt vmcnt(3)
	v_lshlrev_b32_e32 v66, 16, v10
	v_and_b32_e32 v67, 0xffff0000, v10
	v_pk_mul_f32 v[82:83], v[8:9], v[8:9]
	v_add_f32_e32 v80, v80, v81
	v_add_f32_e32 v59, v79, v59
	v_lshlrev_b32_e32 v10, 16, v11
	v_and_b32_e32 v11, 0xffff0000, v11
	v_pk_mul_f32 v[92:93], v[66:67], v[66:67]
	v_add_f32_e32 v81, v82, v83
	v_add_f32_e32 v59, v80, v59
	v_lshlrev_b32_e32 v64, 16, v12
	v_and_b32_e32 v65, 0xffff0000, v12
	v_pk_mul_f32 v[94:95], v[10:11], v[10:11]
	v_add_f32_e32 v82, v92, v93
	v_add_f32_e32 v59, v81, v59
	v_lshlrev_b32_e32 v12, 16, v13
	v_and_b32_e32 v13, 0xffff0000, v13
	s_waitcnt vmcnt(2)
; __device__ __forceinline__ void phase_final(const Params& p) {
;     ...
; #pragma unroll
;       for (int i = 0; i < 4; ++i) {
;         u[i] = *reinterpret_cast<const u32x4*>(xb + i * 512 + lane * 8);
; #pragma unroll
;         for (int j = 0; j < 4; ++j) { float a = __uint_as_float(u[i][j] << 16), b = __uint_as_float(u[i][j] & 0xffff0000u); ss += a * a + b * b; }
;       }
;       ss = wave_sum(ss);
;       float r = rsqrtf(ss * (1.f / DM) + EPS);
; #pragma unroll
;       for (int i = 0; i < 4; ++i) {
;         float4 g0 = *reinterpret_cast<const float4*>(p.g_final + i * 512 + lane * 8), g1 = *reinterpret_cast<const float4*>(p.g_final + i * 512 + lane * 8 + 4);
;         float4 o0 = {__uint_as_float(u[i][0] << 16) * r * g0.x, __uint_as_float(u[i][0] & 0xffff0000u) * r * g0.y,
;                      __uint_as_float(u[i][1] << 16) * r * g0.z, __uint_as_float(u[i][1] & 0xffff0000u) * r * g0.w};
;         float4 o1 = {__uint_as_float(u[i][2] << 16) * r * g1.x, __uint_as_float(u[i][2] & 0xffff0000u) * r * g1.y,
;                      __uint_as_float(u[i][3] << 16) * r * g1.z, __uint_as_float(u[i][3] & 0xffff0000u) * r * g1.w};
;         nt_store4(y + i * 512 + lane * 8, o0);
;         nt_store4(y + i * 512 + lane * 8 + 4, o1);
;       }
	v_lshlrev_b32_e32 v70, 16, v14
	v_and_b32_e32 v71, 0xffff0000, v14
	v_lshlrev_b32_e32 v14, 16, v15
	v_and_b32_e32 v15, 0xffff0000, v15
	v_pk_mul_f32 v[88:89], v[64:65], v[64:65]
	v_add_f32_e32 v83, v94, v95
	v_add_f32_e32 v59, v82, v59
	v_pk_mul_f32 v[90:91], v[12:13], v[12:13]
	v_mov_b32_e32 v102, v15
	v_mov_b32_e32 v103, v71
	v_add_f32_e32 v84, v88, v89
	v_add_f32_e32 v59, v83, v59
	v_lshlrev_b32_e32 v68, 16, v16
	v_and_b32_e32 v69, 0xffff0000, v16
	v_lshlrev_b32_e32 v16, 16, v17
	v_and_b32_e32 v17, 0xffff0000, v17
	v_mov_b32_e32 v100, v14
	v_mov_b32_e32 v101, v70
	v_pk_mul_f32 v[102:103], v[102:103], v[102:103]
	v_add_f32_e32 v85, v90, v91
	v_add_f32_e32 v59, v84, v59
	v_mov_b32_e32 v98, v17
	v_mov_b32_e32 v99, v69
	v_pk_fma_f32 v[74:75], v[100:101], v[100:101], v[102:103]
	v_add_f32_e32 v59, v85, v59
	v_mov_b32_e32 v96, v16
	v_mov_b32_e32 v97, v68
	v_pk_mul_f32 v[98:99], v[98:99], v[98:99]
	v_add_f32_e32 v59, v75, v59
	v_pk_fma_f32 v[6:7], v[96:97], v[96:97], v[98:99]
	v_add_f32_e32 v59, v74, v59
	v_add_f32_e32 v7, v7, v59
	v_add_f32_e32 v6, v6, v7
	ds_bpermute_b32 v7, v57, v6
	v_xor_b32_e32 v57, 16, v194
	v_cmp_lt_i32_e32 vcc, v57, v33
	v_lshl_add_u64 v[74:75], v[0:1], 0, v[34:35]
	s_waitcnt lgkmcnt(0)
	v_add_f32_e32 v6, v6, v7
	v_cndmask_b32_e32 v57, v194, v57, vcc
	v_lshlrev_b32_e32 v57, 2, v57
	ds_bpermute_b32 v7, v57, v6
	v_xor_b32_e32 v57, 8, v194
	v_cmp_lt_i32_e32 vcc, v57, v33
	s_waitcnt lgkmcnt(0)
	v_add_f32_e32 v6, v6, v7
	v_cndmask_b32_e32 v57, v194, v57, vcc
	v_lshlrev_b32_e32 v57, 2, v57
	ds_bpermute_b32 v7, v57, v6
	v_xor_b32_e32 v57, 4, v194
	v_cmp_lt_i32_e32 vcc, v57, v33
	s_waitcnt lgkmcnt(0)
	v_add_f32_e32 v6, v6, v7
	v_cndmask_b32_e32 v57, v194, v57, vcc
	v_lshlrev_b32_e32 v57, 2, v57
	ds_bpermute_b32 v7, v57, v6
	v_xor_b32_e32 v57, 2, v194
	v_cmp_lt_i32_e32 vcc, v57, v33
	s_waitcnt lgkmcnt(0)
	v_add_f32_e32 v6, v6, v7
	v_cndmask_b32_e32 v57, v194, v57, vcc
	v_lshlrev_b32_e32 v57, 2, v57
	ds_bpermute_b32 v7, v57, v6
	v_xor_b32_e32 v57, 1, v194
	v_cmp_lt_i32_e32 vcc, v57, v33
	s_waitcnt lgkmcnt(0)
	v_add_f32_e32 v6, v6, v7
	v_cndmask_b32_e32 v33, v194, v57, vcc
	v_lshlrev_b32_e32 v33, 2, v33
	ds_bpermute_b32 v7, v33, v6
	s_waitcnt lgkmcnt(0)
	v_add_f32_e32 v6, v6, v7
	v_fmamk_f32 v6, v6, 0x3a000000, v72
	v_mul_f32_e32 v7, 0x4b800000, v6
	v_cmp_gt_f32_e32 vcc, s20, v6
	s_nop 1
	v_cndmask_b32_e32 v6, v6, v7, vcc
	v_rsq_f32_e32 v6, v6
	s_nop 0
	v_mul_f32_e32 v0, 0x45800000, v6
	v_cndmask_b32_e32 v76, v6, v0, vcc
	v_pk_mul_f32 v[0:1], v[76:77], v[28:29] op_sel_hi:[0,1]
	v_pk_mul_f32 v[2:3], v[76:77], v[2:3] op_sel_hi:[0,1]
	v_pk_mul_f32 v[26:27], v[76:77], v[26:27] op_sel_hi:[0,1]
	v_pk_mul_f32 v[4:5], v[76:77], v[4:5] op_sel_hi:[0,1]
	s_waitcnt vmcnt(0)
	v_pk_mul_f32 v[2:3], v[24:25], v[2:3]
	v_pk_mul_f32 v[0:1], v[22:23], v[0:1]
	v_pk_mul_f32 v[6:7], v[20:21], v[4:5]
	v_pk_mul_f32 v[4:5], v[18:19], v[26:27]
	global_store_dwordx4 v[74:75], v[0:3], off nt
	global_store_dwordx4 v[74:75], v[4:7], off offset:16 nt
	global_load_dwordx4 v[0:3], v[48:49], off offset:2048
	s_nop 0
	global_load_dwordx4 v[4:7], v[48:49], off offset:2064
	v_pk_mul_f32 v[18:19], v[76:77], v[62:63] op_sel_hi:[0,1]
	v_pk_mul_f32 v[20:21], v[76:77], v[60:61] op_sel_hi:[0,1]
	v_pk_mul_f32 v[8:9], v[76:77], v[8:9] op_sel_hi:[0,1]
	v_pk_mul_f32 v[22:23], v[76:77], v[30:31] op_sel_hi:[0,1]
	v_pk_mul_f32 v[10:11], v[76:77], v[10:11] op_sel_hi:[0,1]
	v_pk_mul_f32 v[12:13], v[76:77], v[12:13] op_sel_hi:[0,1]
	v_pk_mul_f32 v[16:17], v[76:77], v[16:17] op_sel_hi:[0,1]
	s_waitcnt vmcnt(1)
	v_pk_mul_f32 v[0:1], v[0:1], v[20:21]
	v_pk_mul_f32 v[2:3], v[2:3], v[18:19]
	s_waitcnt vmcnt(0)
	v_pk_mul_f32 v[4:5], v[4:5], v[22:23]
	v_pk_mul_f32 v[6:7], v[6:7], v[8:9]
	global_store_dwordx4 v[74:75], v[0:3], off offset:2048 nt
	global_store_dwordx4 v[74:75], v[4:7], off offset:2064 nt
	global_load_dwordx4 v[0:3], v[50:51], off
	s_nop 0
	global_load_dwordx4 v[4:7], v[50:51], off offset:16
	v_add_co_u32_e32 v8, vcc, s16, v74
	v_pk_mul_f32 v[18:19], v[76:77], v[66:67] op_sel_hi:[0,1]
	s_nop 0
	v_addc_co_u32_e32 v9, vcc, 0, v75, vcc
	v_pk_mul_f32 v[20:21], v[76:77], v[64:65] op_sel_hi:[0,1]
	s_waitcnt vmcnt(1)
	v_pk_mul_f32 v[0:1], v[0:1], v[18:19]
	v_pk_mul_f32 v[2:3], v[10:11], v[2:3]
	s_waitcnt vmcnt(0)
	v_pk_mul_f32 v[4:5], v[20:21], v[4:5]
	v_pk_mul_f32 v[6:7], v[12:13], v[6:7]
	global_store_dwordx4 v[8:9], v[0:3], off nt
	global_store_dwordx4 v[8:9], v[4:7], off offset:16 nt
	global_load_dwordx4 v[0:3], v[52:53], off
	s_nop 0
	global_load_dwordx4 v[4:7], v[52:53], off offset:16
	v_pk_mul_f32 v[10:11], v[76:77], v[70:71] op_sel_hi:[0,1]
	v_pk_mul_f32 v[12:13], v[76:77], v[14:15] op_sel_hi:[0,1]
	v_pk_mul_f32 v[14:15], v[76:77], v[68:69] op_sel_hi:[0,1]
	s_waitcnt vmcnt(1)
	v_pk_mul_f32 v[0:1], v[10:11], v[0:1]
	v_pk_mul_f32 v[2:3], v[12:13], v[2:3]
	s_waitcnt vmcnt(0)
	v_pk_mul_f32 v[4:5], v[14:15], v[4:5]
	v_pk_mul_f32 v[6:7], v[16:17], v[6:7]
	global_store_dwordx4 v[8:9], v[0:3], off offset:2048 nt
	global_store_dwordx4 v[8:9], v[4:7], off offset:2064 nt
	s_branch .LBB0_1746
